# k43 + write-through (sc1) attention and conv output stores so the L2 writeback inside the barrier after the attention/conv/decode phase has less dirty data
# speedup vs baseline: 1.0197x; 1.0197x over previous
.LBB0_496:
	s_or_b64 exec, exec, s[4:5]
	s_movk_i32 s4, 0x100
	v_cmp_gt_u32_e32 vcc, s4, v148
	s_waitcnt lgkmcnt(0)
	s_barrier
	s_and_saveexec_b64 s[64:65], vcc
	s_cbranch_execz .LBB0_459
	ds_read2st64_b32 v[8:9], v57 offset1:1
	ds_read2st64_b32 v[10:11], v57 offset0:2 offset1:3
	ds_read2st64_b32 v[12:13], v57 offset0:4 offset1:5
	ds_read2st64_b32 v[26:27], v57 offset0:6 offset1:7
	s_lshl_b32 s4, s91, 11
	s_add_u32 s4, s84, s4
	s_waitcnt lgkmcnt(2)
	v_fma_f32 v15, -v140, v10, v33
	v_fma_f32 v16, -v140, v9, v16
	s_waitcnt lgkmcnt(0)
	v_fma_f32 v9, -v140, v26, v5
	v_fma_f32 v7, -v140, v27, v6
	ds_read2st64_b32 v[26:27], v57 offset0:8 offset1:9
	ds_read2st64_b32 v[28:29], v57 offset0:10 offset1:11
	ds_read2st64_b32 v[30:31], v57 offset0:12 offset1:13
	ds_read2st64_b32 v[44:45], v57 offset0:14 offset1:15
	v_fma_f32 v17, -v140, v8, v68
	v_fma_f32 v14, -v140, v11, v69
	v_fma_f32 v10, -v140, v13, v71
	s_waitcnt lgkmcnt(3)
	v_fma_f32 v13, -v140, v26, v0
	v_fma_f32 v11, -v140, v27, v1
	s_waitcnt lgkmcnt(2)
	v_fma_f32 v8, -v140, v28, v2
	v_fma_f32 v6, -v140, v29, v3
	s_waitcnt lgkmcnt(1)
	v_fma_f32 v5, -v140, v30, v4
	v_fma_f32 v4, -v140, v31, v24
	s_waitcnt lgkmcnt(0)
	v_fma_f32 v3, -v140, v44, v23
	v_fma_f32 v2, -v140, v45, v25
	ds_read2st64_b32 v[24:25], v57 offset0:16 offset1:17
	ds_read2st64_b32 v[26:27], v57 offset0:18 offset1:19
	ds_read2st64_b32 v[28:29], v57 offset0:20 offset1:21
	ds_read2st64_b32 v[44:45], v57 offset0:22 offset1:23
	v_fma_f32 v90, v17, v17, 0
	s_addc_u32 s5, s85, 0
	s_waitcnt lgkmcnt(2)
	v_fma_f32 v30, -v140, v27, v96
	v_fma_f32 v33, -v140, v24, v32
	s_waitcnt lgkmcnt(0)
	v_fma_f32 v24, -v140, v44, v97
	v_fma_f32 v22, -v140, v45, v22
	ds_read2st64_b32 v[44:45], v57 offset0:24 offset1:25
	ds_read2st64_b32 v[46:47], v57 offset0:26 offset1:27
	ds_read2st64_b32 v[62:63], v57 offset0:28 offset1:29
	ds_read2st64_b32 v[96:97], v57 offset0:30 offset1:31
	v_fma_f32 v32, -v140, v25, v49
	v_fma_f32 v31, -v140, v26, v95
	v_fma_f32 v26, -v140, v29, v99
	s_waitcnt lgkmcnt(3)
	v_fma_f32 v29, -v140, v44, v18
	v_fma_f32 v27, -v140, v45, v19
	s_waitcnt lgkmcnt(2)
	v_fma_f32 v25, -v140, v46, v20
	v_fma_f32 v23, -v140, v47, v21
	s_waitcnt lgkmcnt(1)
	v_fma_f32 v21, -v140, v62, v40
	v_fma_f32 v20, -v140, v63, v43
	s_waitcnt lgkmcnt(0)
	v_fma_f32 v19, -v140, v96, v41
	v_fma_f32 v18, -v140, v97, v42
	ds_read2st64_b32 v[40:41], v57 offset0:32 offset1:33
	ds_read2st64_b32 v[42:43], v57 offset0:34 offset1:35
	ds_read2st64_b32 v[44:45], v57 offset0:36 offset1:37
	ds_read2st64_b32 v[62:63], v57 offset0:38 offset1:39
	v_fmac_f32_e32 v90, v33, v33
	s_lshl_b32 s6, s15, 1
	s_waitcnt lgkmcnt(2)
	v_fma_f32 v47, -v140, v42, v91
	v_fma_f32 v49, -v140, v40, v48
	v_fma_f32 v46, -v140, v43, v92
	s_waitcnt lgkmcnt(1)
	v_fma_f32 v44, -v140, v44, v93
	v_fma_f32 v42, -v140, v45, v94
	s_waitcnt lgkmcnt(0)
	v_fma_f32 v40, -v140, v62, v38
	v_fma_f32 v38, -v140, v63, v39
	ds_read2st64_b32 v[62:63], v57 offset0:40 offset1:41
	ds_read2st64_b32 v[92:93], v57 offset0:42 offset1:43
	ds_read2st64_b32 v[94:95], v57 offset0:44 offset1:45
	ds_read2st64_b32 v[96:97], v57 offset0:46 offset1:47
	v_fma_f32 v48, -v140, v41, v67
	v_fmac_f32_e32 v90, v49, v49
	s_waitcnt lgkmcnt(2)
	v_fma_f32 v41, -v140, v92, v36
	v_fma_f32 v45, -v140, v62, v34
	v_fma_f32 v43, -v140, v63, v35
	v_fma_f32 v39, -v140, v93, v37
	s_waitcnt lgkmcnt(1)
	v_fma_f32 v37, -v140, v94, v56
	v_fma_f32 v36, -v140, v95, v60
	s_waitcnt lgkmcnt(0)
	v_fma_f32 v35, -v140, v96, v58
	v_fma_f32 v34, -v140, v97, v59
	ds_read2st64_b32 v[58:59], v57 offset0:48 offset1:49
	ds_read2st64_b32 v[60:61], v57 offset0:50 offset1:51
	ds_read2st64_b32 v[92:93], v57 offset0:52 offset1:53
	ds_read2st64_b32 v[94:95], v57 offset0:54 offset1:55
	s_add_u32 s66, s4, s6
	v_fma_f32 v85, v16, v16, 0
	s_waitcnt lgkmcnt(2)
	v_fma_f32 v63, -v140, v60, v84
	v_fma_f32 v67, -v140, v58, v66
	v_fma_f32 v62, -v140, v61, v86
	s_waitcnt lgkmcnt(1)
	v_fma_f32 v60, -v140, v92, v87
	v_fma_f32 v58, -v140, v93, v88
	s_waitcnt lgkmcnt(0)
	v_fma_f32 v56, -v140, v94, v53
	v_fma_f32 v53, -v140, v95, v89
	ds_read2st64_b32 v[86:87], v57 offset0:56 offset1:57
	ds_read2st64_b32 v[88:89], v57 offset0:58 offset1:59
	ds_read2st64_b32 v[92:93], v57 offset0:60 offset1:61
	ds_read2st64_b32 v[94:95], v57 offset0:62 offset1:63
	v_fmac_f32_e32 v90, v67, v67
	v_fma_f32 v66, -v140, v59, v83
	s_waitcnt lgkmcnt(2)
	v_fma_f32 v57, -v140, v88, v55
	v_add_f32_dpp v55, v90, v90 quad_perm:[1,0,3,2] row_mask:0xf bank_mask:0xf bound_ctrl:1
	v_fma_f32 v59, -v140, v87, v54
	v_fma_f32 v54, -v140, v89, v81
	v_add_f32_dpp v55, v55, v55 quad_perm:[2,3,0,1] row_mask:0xf bank_mask:0xf bound_ctrl:1
	v_fma_f32 v61, -v140, v86, v50
	s_waitcnt lgkmcnt(1)
	v_fma_f32 v50, -v140, v92, v82
	v_add_f32_dpp v55, v55, v55 row_half_mirror row_mask:0xf bank_mask:0xf bound_ctrl:1
	s_addc_u32 s67, s5, 0
	v_fmac_f32_e32 v85, v32, v32
	v_add_f32_dpp v55, v55, v55 row_ror:8 row_mask:0xf bank_mask:0xf bound_ctrl:1
	v_mov_b32_e32 v81, v55
	s_nop 1
	v_permlane16_swap_b32_e32 v55, v81
	v_add_f32_e32 v55, v55, v81
	v_fmamk_f32 v55, v55, 0x3c000000, v141
	v_mul_f32_e32 v81, 0x4f800000, v55
	v_cmp_gt_f32_e32 vcc, s86, v55
	v_fmac_f32_e32 v85, v48, v48
	v_fmac_f32_e32 v85, v66, v66
	v_cndmask_b32_e32 v81, v55, v81, vcc
	v_sqrt_f32_e32 v82, v81
	v_fma_f32 v55, -v140, v93, v51
	s_waitcnt lgkmcnt(0)
	v_fma_f32 v51, -v140, v94, v72
	v_add_f32_dpp v85, v85, v85 quad_perm:[1,0,3,2] row_mask:0xf bank_mask:0xf bound_ctrl:1
	v_add_u32_e32 v72, -1, v82
	v_fma_f32 v83, -v72, v82, v81
	v_cmp_ge_f32_e64 s[4:5], 0, v83
	v_add_u32_e32 v83, 1, v82
	v_add_f32_dpp v85, v85, v85 quad_perm:[2,3,0,1] row_mask:0xf bank_mask:0xf bound_ctrl:1
	v_cndmask_b32_e64 v72, v82, v72, s[4:5]
	v_fma_f32 v82, -v83, v82, v81
	v_cmp_lt_f32_e64 s[4:5], 0, v82
	v_add_f32_dpp v85, v85, v85 row_half_mirror row_mask:0xf bank_mask:0xf bound_ctrl:1
	v_fma_f32 v73, v15, v15, 0
	v_cndmask_b32_e64 v72, v72, v83, s[4:5]
	v_mul_f32_e32 v82, 0x37800000, v72
	v_cndmask_b32_e32 v72, v72, v82, vcc
	v_cmp_class_f32_e32 vcc, v81, v142
	v_add_f32_dpp v85, v85, v85 row_ror:8 row_mask:0xf bank_mask:0xf bound_ctrl:1
	v_mov_b32_e32 v86, v85
	v_cndmask_b32_e32 v72, v72, v81, vcc
	v_div_scale_f32 v81, s[4:5], v72, v72, s87
	v_rcp_f32_e32 v82, v81
	v_permlane16_swap_b32_e32 v85, v86
	v_add_f32_e32 v85, v85, v86
	v_fmamk_f32 v85, v85, 0x3c000000, v141
	v_mul_f32_e32 v86, 0x4f800000, v85
	v_cmp_gt_f32_e64 s[4:5], s86, v85
	v_fma_f32 v83, -v81, v82, 1.0
	v_fmac_f32_e32 v82, v83, v82
	v_cndmask_b32_e64 v85, v85, v86, s[4:5]
	v_div_scale_f32 v83, vcc, s87, v72, s87
	v_sqrt_f32_e32 v86, v85
	v_mul_f32_e32 v84, v83, v82
	v_fma_f32 v87, -v81, v84, v83
	v_fmac_f32_e32 v84, v87, v82
	v_fma_f32 v81, -v81, v84, v83
	v_add_u32_e32 v83, -1, v86
	v_fma_f32 v87, -v83, v86, v85
	v_fmac_f32_e32 v73, v31, v31
	v_cmp_ge_f32_e64 s[6:7], 0, v87
	v_add_u32_e32 v87, 1, v86
	v_fmac_f32_e32 v73, v47, v47
	v_cndmask_b32_e64 v83, v86, v83, s[6:7]
	v_fma_f32 v86, -v87, v86, v85
	v_fmac_f32_e32 v73, v63, v63
	v_cmp_lt_f32_e64 s[6:7], 0, v86
	v_div_fmas_f32 v81, v81, v82, v84
	v_add_f32_dpp v73, v73, v73 quad_perm:[1,0,3,2] row_mask:0xf bank_mask:0xf bound_ctrl:1
	v_cndmask_b32_e64 v83, v83, v87, s[6:7]
	v_mul_f32_e32 v86, 0x37800000, v83
	v_add_f32_dpp v73, v73, v73 quad_perm:[2,3,0,1] row_mask:0xf bank_mask:0xf bound_ctrl:1
	v_cndmask_b32_e64 v83, v83, v86, s[4:5]
	v_cmp_class_f32_e64 s[4:5], v85, v142
	v_add_f32_dpp v73, v73, v73 row_half_mirror row_mask:0xf bank_mask:0xf bound_ctrl:1
	v_div_fixup_f32 v72, v81, v72, s87
	v_cndmask_b32_e64 v83, v83, v85, s[4:5]
	v_add_f32_dpp v73, v73, v73 row_ror:8 row_mask:0xf bank_mask:0xf bound_ctrl:1
	v_div_scale_f32 v85, s[4:5], v83, v83, s87
	v_mov_b32_e32 v84, v73
	v_rcp_f32_e32 v86, v85
	s_nop 0
	v_permlane16_swap_b32_e32 v73, v84
	v_add_f32_e32 v73, v73, v84
	v_fmamk_f32 v73, v73, 0x3c000000, v141
	v_mul_f32_e32 v84, 0x4f800000, v73
	v_cmp_gt_f32_e64 s[4:5], s86, v73
	v_fma_f32 v81, -v85, v86, 1.0
	v_fmac_f32_e32 v86, v81, v86
	v_cndmask_b32_e64 v73, v73, v84, s[4:5]
	v_div_scale_f32 v81, vcc, s87, v83, s87
	v_sqrt_f32_e32 v84, v73
	v_mul_f32_e32 v82, v81, v86
	v_fma_f32 v87, -v85, v82, v81
	v_fmac_f32_e32 v82, v87, v86
	v_fma_f32 v81, -v85, v82, v81
	v_add_u32_e32 v85, -1, v84
	v_fma_f32 v75, v14, v14, 0
	v_fma_f32 v87, -v85, v84, v73
	v_fmac_f32_e32 v75, v30, v30
	v_cmp_ge_f32_e64 s[6:7], 0, v87
	v_add_u32_e32 v87, 1, v84
	v_fmac_f32_e32 v75, v46, v46
	v_cndmask_b32_e64 v85, v84, v85, s[6:7]
	v_fma_f32 v84, -v87, v84, v73
	v_fmac_f32_e32 v75, v62, v62
	v_cmp_lt_f32_e64 s[6:7], 0, v84
	v_fma_f32 v12, -v140, v12, v70
	v_add_f32_dpp v75, v75, v75 quad_perm:[1,0,3,2] row_mask:0xf bank_mask:0xf bound_ctrl:1
	v_cndmask_b32_e64 v84, v85, v87, s[6:7]
	v_mul_f32_e32 v85, 0x37800000, v84
	v_add_f32_dpp v75, v75, v75 quad_perm:[2,3,0,1] row_mask:0xf bank_mask:0xf bound_ctrl:1
	v_cndmask_b32_e64 v84, v84, v85, s[4:5]
	v_cmp_class_f32_e64 s[4:5], v73, v142
	v_add_f32_dpp v75, v75, v75 row_half_mirror row_mask:0xf bank_mask:0xf bound_ctrl:1
	v_fma_f32 v77, v12, v12, 0
	v_cndmask_b32_e64 v84, v84, v73, s[4:5]
	v_div_fmas_f32 v73, v81, v86, v82
	v_add_f32_dpp v75, v75, v75 row_ror:8 row_mask:0xf bank_mask:0xf bound_ctrl:1
	v_div_scale_f32 v85, s[4:5], v84, v84, s87
	v_div_fixup_f32 v73, v73, v83, s87
	v_mov_b32_e32 v83, v75
	v_rcp_f32_e32 v87, v85
	s_nop 0
	v_permlane16_swap_b32_e32 v75, v83
	v_add_f32_e32 v75, v75, v83
	v_fmamk_f32 v75, v75, 0x3c000000, v141
	v_mul_f32_e32 v83, 0x4f800000, v75
	v_cmp_gt_f32_e64 s[4:5], s86, v75
	v_fma_f32 v81, -v85, v87, 1.0
	v_fmac_f32_e32 v87, v81, v87
	v_cndmask_b32_e64 v75, v75, v83, s[4:5]
	v_div_scale_f32 v81, vcc, s87, v84, s87
	v_sqrt_f32_e32 v83, v75
	v_mul_f32_e32 v82, v81, v87
	v_fma_f32 v86, -v85, v82, v81
	v_fmac_f32_e32 v82, v86, v87
	v_fma_f32 v81, -v85, v82, v81
	v_add_u32_e32 v85, -1, v83
	v_fma_f32 v28, -v140, v28, v98
	v_fma_f32 v86, -v85, v83, v75
	v_fmac_f32_e32 v77, v28, v28
	v_cmp_ge_f32_e64 s[6:7], 0, v86
	v_add_u32_e32 v86, 1, v83
	v_fmac_f32_e32 v77, v44, v44
	v_cndmask_b32_e64 v85, v83, v85, s[6:7]
	v_fma_f32 v83, -v86, v83, v75
	v_fmac_f32_e32 v77, v60, v60
	v_cmp_lt_f32_e64 s[6:7], 0, v83
	v_fma_f32 v79, v10, v10, 0
	v_add_f32_dpp v77, v77, v77 quad_perm:[1,0,3,2] row_mask:0xf bank_mask:0xf bound_ctrl:1
	v_cndmask_b32_e64 v83, v85, v86, s[6:7]
	v_mul_f32_e32 v85, 0x37800000, v83
	v_add_f32_dpp v77, v77, v77 quad_perm:[2,3,0,1] row_mask:0xf bank_mask:0xf bound_ctrl:1
	v_cndmask_b32_e64 v83, v83, v85, s[4:5]
	v_cmp_class_f32_e64 s[4:5], v75, v142
	v_add_f32_dpp v77, v77, v77 row_half_mirror row_mask:0xf bank_mask:0xf bound_ctrl:1
	v_fmac_f32_e32 v79, v26, v26
	v_cndmask_b32_e64 v83, v83, v75, s[4:5]
	v_div_fmas_f32 v75, v81, v87, v82
	v_add_f32_dpp v77, v77, v77 row_ror:8 row_mask:0xf bank_mask:0xf bound_ctrl:1
	v_div_scale_f32 v85, s[4:5], v83, v83, s87
	v_div_fixup_f32 v75, v75, v84, s87
	v_mov_b32_e32 v84, v77
	v_rcp_f32_e32 v86, v85
	s_nop 0
	v_permlane16_swap_b32_e32 v77, v84
	v_add_f32_e32 v77, v77, v84
	v_fmamk_f32 v77, v77, 0x3c000000, v141
	v_mul_f32_e32 v84, 0x4f800000, v77
	v_cmp_gt_f32_e64 s[4:5], s86, v77
	v_fma_f32 v81, -v85, v86, 1.0
	v_fmac_f32_e32 v86, v81, v86
	v_cndmask_b32_e64 v77, v77, v84, s[4:5]
	v_div_scale_f32 v81, vcc, s87, v83, s87
	v_sqrt_f32_e32 v84, v77
	v_mul_f32_e32 v82, v81, v86
	v_fma_f32 v87, -v85, v82, v81
	v_fmac_f32_e32 v82, v87, v86
	v_fma_f32 v81, -v85, v82, v81
	v_add_u32_e32 v85, -1, v84
	v_fma_f32 v87, -v85, v84, v77
	v_cmp_ge_f32_e64 s[6:7], 0, v87
	v_add_u32_e32 v87, 1, v84
	v_fmac_f32_e32 v79, v42, v42
	v_cndmask_b32_e64 v85, v84, v85, s[6:7]
	v_fma_f32 v84, -v87, v84, v77
	v_fmac_f32_e32 v79, v58, v58
	v_cmp_lt_f32_e64 s[6:7], 0, v84
	v_fma_f32 v80, v9, v9, 0
	v_add_f32_dpp v79, v79, v79 quad_perm:[1,0,3,2] row_mask:0xf bank_mask:0xf bound_ctrl:1
	v_cndmask_b32_e64 v84, v85, v87, s[6:7]
	v_mul_f32_e32 v85, 0x37800000, v84
	v_add_f32_dpp v79, v79, v79 quad_perm:[2,3,0,1] row_mask:0xf bank_mask:0xf bound_ctrl:1
	v_cndmask_b32_e64 v84, v84, v85, s[4:5]
	v_cmp_class_f32_e64 s[4:5], v77, v142
	v_add_f32_dpp v79, v79, v79 row_half_mirror row_mask:0xf bank_mask:0xf bound_ctrl:1
	v_fmac_f32_e32 v80, v24, v24
	v_cndmask_b32_e64 v84, v84, v77, s[4:5]
	v_div_fmas_f32 v77, v81, v86, v82
	v_add_f32_dpp v79, v79, v79 row_ror:8 row_mask:0xf bank_mask:0xf bound_ctrl:1
	v_div_scale_f32 v85, s[4:5], v84, v84, s87
	v_div_fixup_f32 v77, v77, v83, s87
	v_mov_b32_e32 v83, v79
	v_rcp_f32_e32 v87, v85
	s_nop 0
	v_permlane16_swap_b32_e32 v79, v83
	v_add_f32_e32 v79, v79, v83
	v_fmamk_f32 v79, v79, 0x3c000000, v141
	v_mul_f32_e32 v83, 0x4f800000, v79
	v_cmp_gt_f32_e64 s[4:5], s86, v79
	v_fma_f32 v81, -v85, v87, 1.0
	v_fmac_f32_e32 v87, v81, v87
	v_cndmask_b32_e64 v79, v79, v83, s[4:5]
	v_div_scale_f32 v81, vcc, s87, v84, s87
	v_sqrt_f32_e32 v83, v79
	v_mul_f32_e32 v82, v81, v87
	v_fma_f32 v86, -v85, v82, v81
	v_fmac_f32_e32 v82, v86, v87
	v_fma_f32 v81, -v85, v82, v81
	v_add_u32_e32 v85, -1, v83
	v_fma_f32 v86, -v85, v83, v79
	v_cmp_ge_f32_e64 s[6:7], 0, v86
	v_add_u32_e32 v86, 1, v83
	v_fmac_f32_e32 v80, v40, v40
	v_cndmask_b32_e64 v85, v83, v85, s[6:7]
	v_fma_f32 v83, -v86, v83, v79
	v_fmac_f32_e32 v80, v56, v56
	v_cmp_lt_f32_e64 s[6:7], 0, v83
	v_fma_f32 v78, v7, v7, 0
	v_add_f32_dpp v80, v80, v80 quad_perm:[1,0,3,2] row_mask:0xf bank_mask:0xf bound_ctrl:1
	v_cndmask_b32_e64 v83, v85, v86, s[6:7]
	v_mul_f32_e32 v85, 0x37800000, v83
	v_add_f32_dpp v80, v80, v80 quad_perm:[2,3,0,1] row_mask:0xf bank_mask:0xf bound_ctrl:1
	v_cndmask_b32_e64 v83, v83, v85, s[4:5]
	v_cmp_class_f32_e64 s[4:5], v79, v142
	v_add_f32_dpp v80, v80, v80 row_half_mirror row_mask:0xf bank_mask:0xf bound_ctrl:1
	v_fmac_f32_e32 v78, v22, v22
	v_cndmask_b32_e64 v83, v83, v79, s[4:5]
	v_div_fmas_f32 v79, v81, v87, v82
	v_add_f32_dpp v80, v80, v80 row_ror:8 row_mask:0xf bank_mask:0xf bound_ctrl:1
	v_div_scale_f32 v85, s[4:5], v83, v83, s87
	v_div_fixup_f32 v79, v79, v84, s87
	v_mov_b32_e32 v84, v80
	v_rcp_f32_e32 v86, v85
	s_nop 0
	v_permlane16_swap_b32_e32 v80, v84
	v_add_f32_e32 v80, v80, v84
	v_fmamk_f32 v80, v80, 0x3c000000, v141
	v_mul_f32_e32 v84, 0x4f800000, v80
	v_cmp_gt_f32_e64 s[4:5], s86, v80
	v_fma_f32 v81, -v85, v86, 1.0
	v_fmac_f32_e32 v86, v81, v86
	v_cndmask_b32_e64 v80, v80, v84, s[4:5]
	v_div_scale_f32 v81, vcc, s87, v83, s87
	v_sqrt_f32_e32 v84, v80
	v_mul_f32_e32 v82, v81, v86
	v_fma_f32 v87, -v85, v82, v81
	v_fmac_f32_e32 v82, v87, v86
	v_fma_f32 v81, -v85, v82, v81
	v_add_u32_e32 v85, -1, v84
	v_fma_f32 v87, -v85, v84, v80
	v_cmp_ge_f32_e64 s[6:7], 0, v87
	v_add_u32_e32 v87, 1, v84
	v_fmac_f32_e32 v78, v38, v38
	v_cndmask_b32_e64 v85, v84, v85, s[6:7]
	v_fma_f32 v84, -v87, v84, v80
	v_fmac_f32_e32 v78, v53, v53
	v_cmp_lt_f32_e64 s[6:7], 0, v84
	v_fma_f32 v76, v13, v13, 0
	v_add_f32_dpp v78, v78, v78 quad_perm:[1,0,3,2] row_mask:0xf bank_mask:0xf bound_ctrl:1
	v_cndmask_b32_e64 v84, v85, v87, s[6:7]
	v_mul_f32_e32 v85, 0x37800000, v84
	v_add_f32_dpp v78, v78, v78 quad_perm:[2,3,0,1] row_mask:0xf bank_mask:0xf bound_ctrl:1
	v_cndmask_b32_e64 v84, v84, v85, s[4:5]
	v_cmp_class_f32_e64 s[4:5], v80, v142
	v_add_f32_dpp v78, v78, v78 row_half_mirror row_mask:0xf bank_mask:0xf bound_ctrl:1
	v_fmac_f32_e32 v76, v29, v29
	v_cndmask_b32_e64 v84, v84, v80, s[4:5]
	v_div_fmas_f32 v80, v81, v86, v82
	v_add_f32_dpp v78, v78, v78 row_ror:8 row_mask:0xf bank_mask:0xf bound_ctrl:1
	v_div_scale_f32 v85, s[4:5], v84, v84, s87
	v_div_fixup_f32 v80, v80, v83, s87
	v_mov_b32_e32 v83, v78
	v_rcp_f32_e32 v87, v85
	s_nop 0
	v_permlane16_swap_b32_e32 v78, v83
	v_add_f32_e32 v78, v78, v83
	v_fmamk_f32 v78, v78, 0x3c000000, v141
	v_mul_f32_e32 v83, 0x4f800000, v78
	v_cmp_gt_f32_e64 s[4:5], s86, v78
	v_fma_f32 v81, -v85, v87, 1.0
	v_fmac_f32_e32 v87, v81, v87
	v_cndmask_b32_e64 v78, v78, v83, s[4:5]
	v_div_scale_f32 v81, vcc, s87, v84, s87
	v_sqrt_f32_e32 v83, v78
	v_mul_f32_e32 v82, v81, v87
	v_fma_f32 v86, -v85, v82, v81
	v_fmac_f32_e32 v82, v86, v87
	v_fma_f32 v81, -v85, v82, v81
	v_add_u32_e32 v85, -1, v83
	v_fma_f32 v86, -v85, v83, v78
	v_cmp_ge_f32_e64 s[6:7], 0, v86
	v_add_u32_e32 v86, 1, v83
	v_fmac_f32_e32 v76, v45, v45
	v_cndmask_b32_e64 v85, v83, v85, s[6:7]
	v_fma_f32 v83, -v86, v83, v78
	v_fmac_f32_e32 v76, v61, v61
	v_cmp_lt_f32_e64 s[6:7], 0, v83
	v_fma_f32 v74, v11, v11, 0
	v_add_f32_dpp v76, v76, v76 quad_perm:[1,0,3,2] row_mask:0xf bank_mask:0xf bound_ctrl:1
	v_cndmask_b32_e64 v83, v85, v86, s[6:7]
	v_mul_f32_e32 v85, 0x37800000, v83
	v_add_f32_dpp v76, v76, v76 quad_perm:[2,3,0,1] row_mask:0xf bank_mask:0xf bound_ctrl:1
	v_cndmask_b32_e64 v83, v83, v85, s[4:5]
	v_cmp_class_f32_e64 s[4:5], v78, v142
	v_add_f32_dpp v76, v76, v76 row_half_mirror row_mask:0xf bank_mask:0xf bound_ctrl:1
	v_fmac_f32_e32 v74, v27, v27
	v_cndmask_b32_e64 v83, v83, v78, s[4:5]
	v_div_fmas_f32 v78, v81, v87, v82
	v_add_f32_dpp v76, v76, v76 row_ror:8 row_mask:0xf bank_mask:0xf bound_ctrl:1
	v_div_scale_f32 v85, s[4:5], v83, v83, s87
	v_div_fixup_f32 v78, v78, v84, s87
	v_mov_b32_e32 v84, v76
	v_rcp_f32_e32 v86, v85
	s_nop 0
	v_permlane16_swap_b32_e32 v76, v84
	v_add_f32_e32 v76, v76, v84
	v_fmamk_f32 v76, v76, 0x3c000000, v141
	v_mul_f32_e32 v84, 0x4f800000, v76
	v_cmp_gt_f32_e64 s[4:5], s86, v76
	v_fma_f32 v81, -v85, v86, 1.0
	v_fmac_f32_e32 v86, v81, v86
	v_cndmask_b32_e64 v76, v76, v84, s[4:5]
	v_div_scale_f32 v81, vcc, s87, v83, s87
	v_sqrt_f32_e32 v84, v76
	v_mul_f32_e32 v82, v81, v86
	v_fma_f32 v87, -v85, v82, v81
	v_fmac_f32_e32 v82, v87, v86
	v_fma_f32 v81, -v85, v82, v81
	v_add_u32_e32 v85, -1, v84
	v_fma_f32 v87, -v85, v84, v76
	v_cmp_ge_f32_e64 s[6:7], 0, v87
	v_add_u32_e32 v87, 1, v84
	v_fmac_f32_e32 v74, v43, v43
	v_cndmask_b32_e64 v85, v84, v85, s[6:7]
	v_fma_f32 v84, -v87, v84, v76
	v_fmac_f32_e32 v74, v59, v59
	v_cmp_lt_f32_e64 s[6:7], 0, v84
	v_fma_f32 v71, v8, v8, 0
	v_add_f32_dpp v74, v74, v74 quad_perm:[1,0,3,2] row_mask:0xf bank_mask:0xf bound_ctrl:1
	v_cndmask_b32_e64 v84, v85, v87, s[6:7]
	v_mul_f32_e32 v85, 0x37800000, v84
	v_add_f32_dpp v74, v74, v74 quad_perm:[2,3,0,1] row_mask:0xf bank_mask:0xf bound_ctrl:1
	v_cndmask_b32_e64 v84, v84, v85, s[4:5]
	v_cmp_class_f32_e64 s[4:5], v76, v142
	v_add_f32_dpp v74, v74, v74 row_half_mirror row_mask:0xf bank_mask:0xf bound_ctrl:1
	v_fmac_f32_e32 v71, v25, v25
	v_cndmask_b32_e64 v84, v84, v76, s[4:5]
	v_div_fmas_f32 v76, v81, v86, v82
	v_add_f32_dpp v74, v74, v74 row_ror:8 row_mask:0xf bank_mask:0xf bound_ctrl:1
	v_div_scale_f32 v85, s[4:5], v84, v84, s87
	v_div_fixup_f32 v76, v76, v83, s87
	v_mov_b32_e32 v83, v74
	v_rcp_f32_e32 v87, v85
	s_nop 0
	v_permlane16_swap_b32_e32 v74, v83
	v_add_f32_e32 v74, v74, v83
	v_fmamk_f32 v74, v74, 0x3c000000, v141
	v_mul_f32_e32 v83, 0x4f800000, v74
	v_cmp_gt_f32_e64 s[4:5], s86, v74
	v_fma_f32 v81, -v85, v87, 1.0
	v_fmac_f32_e32 v87, v81, v87
	v_cndmask_b32_e64 v74, v74, v83, s[4:5]
	v_div_scale_f32 v81, vcc, s87, v84, s87
	v_sqrt_f32_e32 v83, v74
	v_mul_f32_e32 v82, v81, v87
	v_fma_f32 v86, -v85, v82, v81
	v_fmac_f32_e32 v82, v86, v87
	v_fma_f32 v81, -v85, v82, v81
	v_add_u32_e32 v85, -1, v83
	v_fma_f32 v86, -v85, v83, v74
	v_cmp_ge_f32_e64 s[6:7], 0, v86
	v_add_u32_e32 v86, 1, v83
	v_fmac_f32_e32 v71, v41, v41
	v_cndmask_b32_e64 v85, v83, v85, s[6:7]
	v_fma_f32 v83, -v86, v83, v74
	v_fmac_f32_e32 v71, v57, v57
	v_cmp_lt_f32_e64 s[6:7], 0, v83
	v_fma_f32 v70, v6, v6, 0
	v_add_f32_dpp v71, v71, v71 quad_perm:[1,0,3,2] row_mask:0xf bank_mask:0xf bound_ctrl:1
	v_cndmask_b32_e64 v83, v85, v86, s[6:7]
	v_mul_f32_e32 v85, 0x37800000, v83
	v_add_f32_dpp v71, v71, v71 quad_perm:[2,3,0,1] row_mask:0xf bank_mask:0xf bound_ctrl:1
	v_cndmask_b32_e64 v83, v83, v85, s[4:5]
	v_cmp_class_f32_e64 s[4:5], v74, v142
	v_add_f32_dpp v71, v71, v71 row_half_mirror row_mask:0xf bank_mask:0xf bound_ctrl:1
	v_fmac_f32_e32 v70, v23, v23
	v_cndmask_b32_e64 v83, v83, v74, s[4:5]
	v_div_fmas_f32 v74, v81, v87, v82
	v_add_f32_dpp v71, v71, v71 row_ror:8 row_mask:0xf bank_mask:0xf bound_ctrl:1
	v_div_scale_f32 v85, s[4:5], v83, v83, s87
	v_div_fixup_f32 v74, v74, v84, s87
	v_mov_b32_e32 v84, v71
	v_rcp_f32_e32 v86, v85
	s_nop 0
	v_permlane16_swap_b32_e32 v71, v84
	v_add_f32_e32 v71, v71, v84
	v_fmamk_f32 v71, v71, 0x3c000000, v141
	v_mul_f32_e32 v84, 0x4f800000, v71
	v_cmp_gt_f32_e64 s[4:5], s86, v71
	v_fma_f32 v81, -v85, v86, 1.0
	v_fmac_f32_e32 v86, v81, v86
	v_cndmask_b32_e64 v71, v71, v84, s[4:5]
	v_div_scale_f32 v81, vcc, s87, v83, s87
	v_sqrt_f32_e32 v84, v71
	v_mul_f32_e32 v82, v81, v86
	v_fma_f32 v87, -v85, v82, v81
	v_fmac_f32_e32 v82, v87, v86
	v_fma_f32 v81, -v85, v82, v81
	v_add_u32_e32 v85, -1, v84
	v_fma_f32 v87, -v85, v84, v71
	v_cmp_ge_f32_e64 s[6:7], 0, v87
	v_add_u32_e32 v87, 1, v84
	v_fmac_f32_e32 v70, v39, v39
	v_cndmask_b32_e64 v85, v84, v85, s[6:7]
	v_fma_f32 v84, -v87, v84, v71
	v_fmac_f32_e32 v70, v54, v54
	v_cmp_lt_f32_e64 s[6:7], 0, v84
	v_fma_f32 v69, v5, v5, 0
	v_add_f32_dpp v70, v70, v70 quad_perm:[1,0,3,2] row_mask:0xf bank_mask:0xf bound_ctrl:1
	v_cndmask_b32_e64 v84, v85, v87, s[6:7]
	v_mul_f32_e32 v85, 0x37800000, v84
	v_add_f32_dpp v70, v70, v70 quad_perm:[2,3,0,1] row_mask:0xf bank_mask:0xf bound_ctrl:1
	v_cndmask_b32_e64 v84, v84, v85, s[4:5]
	v_cmp_class_f32_e64 s[4:5], v71, v142
	v_add_f32_dpp v70, v70, v70 row_half_mirror row_mask:0xf bank_mask:0xf bound_ctrl:1
	v_fmac_f32_e32 v69, v21, v21
	v_cndmask_b32_e64 v84, v84, v71, s[4:5]
	v_div_fmas_f32 v71, v81, v86, v82
	v_add_f32_dpp v70, v70, v70 row_ror:8 row_mask:0xf bank_mask:0xf bound_ctrl:1
	v_div_scale_f32 v85, s[4:5], v84, v84, s87
	v_div_fixup_f32 v71, v71, v83, s87
	v_mov_b32_e32 v83, v70
	v_rcp_f32_e32 v87, v85
	s_nop 0
	v_permlane16_swap_b32_e32 v70, v83
	v_add_f32_e32 v70, v70, v83
	v_fmamk_f32 v70, v70, 0x3c000000, v141
	v_mul_f32_e32 v83, 0x4f800000, v70
	v_cmp_gt_f32_e64 s[4:5], s86, v70
	v_fma_f32 v81, -v85, v87, 1.0
	v_fmac_f32_e32 v87, v81, v87
	v_cndmask_b32_e64 v70, v70, v83, s[4:5]
	v_div_scale_f32 v81, vcc, s87, v84, s87
	v_sqrt_f32_e32 v83, v70
	v_mul_f32_e32 v82, v81, v87
	v_fma_f32 v86, -v85, v82, v81
	v_fmac_f32_e32 v82, v86, v87
	v_fma_f32 v81, -v85, v82, v81
	v_add_u32_e32 v85, -1, v83
	v_fma_f32 v86, -v85, v83, v70
	v_cmp_ge_f32_e64 s[6:7], 0, v86
	v_add_u32_e32 v86, 1, v83
	v_fmac_f32_e32 v69, v37, v37
	v_cndmask_b32_e64 v85, v83, v85, s[6:7]
	v_fma_f32 v83, -v86, v83, v70
	v_fmac_f32_e32 v69, v50, v50
	v_cmp_lt_f32_e64 s[6:7], 0, v83
	v_fma_f32 v68, v4, v4, 0
	v_add_f32_dpp v69, v69, v69 quad_perm:[1,0,3,2] row_mask:0xf bank_mask:0xf bound_ctrl:1
	v_cndmask_b32_e64 v83, v85, v86, s[6:7]
	v_mul_f32_e32 v85, 0x37800000, v83
	v_add_f32_dpp v69, v69, v69 quad_perm:[2,3,0,1] row_mask:0xf bank_mask:0xf bound_ctrl:1
	v_cndmask_b32_e64 v83, v83, v85, s[4:5]
	v_cmp_class_f32_e64 s[4:5], v70, v142
	v_add_f32_dpp v69, v69, v69 row_half_mirror row_mask:0xf bank_mask:0xf bound_ctrl:1
	v_fmac_f32_e32 v68, v20, v20
	v_cndmask_b32_e64 v83, v83, v70, s[4:5]
	v_div_fmas_f32 v70, v81, v87, v82
	v_add_f32_dpp v69, v69, v69 row_ror:8 row_mask:0xf bank_mask:0xf bound_ctrl:1
	v_div_scale_f32 v85, s[4:5], v83, v83, s87
	v_div_fixup_f32 v70, v70, v84, s87
	v_mov_b32_e32 v84, v69
	v_rcp_f32_e32 v86, v85
	s_nop 0
	v_permlane16_swap_b32_e32 v69, v84
	v_add_f32_e32 v69, v69, v84
	v_fmamk_f32 v69, v69, 0x3c000000, v141
	v_mul_f32_e32 v84, 0x4f800000, v69
	v_cmp_gt_f32_e64 s[4:5], s86, v69
	v_fma_f32 v81, -v85, v86, 1.0
	v_fmac_f32_e32 v86, v81, v86
	v_cndmask_b32_e64 v69, v69, v84, s[4:5]
	v_div_scale_f32 v81, vcc, s87, v83, s87
	v_sqrt_f32_e32 v84, v69
	v_mul_f32_e32 v82, v81, v86
	v_fma_f32 v87, -v85, v82, v81
	v_fmac_f32_e32 v82, v87, v86
	v_fma_f32 v81, -v85, v82, v81
	v_add_u32_e32 v85, -1, v84
	v_fma_f32 v87, -v85, v84, v69
	v_cmp_ge_f32_e64 s[6:7], 0, v87
	v_add_u32_e32 v87, 1, v84
	v_fmac_f32_e32 v68, v36, v36
	v_cndmask_b32_e64 v85, v84, v85, s[6:7]
	v_fma_f32 v84, -v87, v84, v69
	v_fmac_f32_e32 v68, v55, v55
	v_cmp_lt_f32_e64 s[6:7], 0, v84
	v_fma_f32 v1, v3, v3, 0
	v_add_f32_dpp v68, v68, v68 quad_perm:[1,0,3,2] row_mask:0xf bank_mask:0xf bound_ctrl:1
	v_cndmask_b32_e64 v84, v85, v87, s[6:7]
	v_mul_f32_e32 v85, 0x37800000, v84
	v_add_f32_dpp v68, v68, v68 quad_perm:[2,3,0,1] row_mask:0xf bank_mask:0xf bound_ctrl:1
	v_cndmask_b32_e64 v84, v84, v85, s[4:5]
	v_cmp_class_f32_e64 s[4:5], v69, v142
	v_add_f32_dpp v68, v68, v68 row_half_mirror row_mask:0xf bank_mask:0xf bound_ctrl:1
	v_fmac_f32_e32 v1, v19, v19
	v_cndmask_b32_e64 v84, v84, v69, s[4:5]
	v_div_fmas_f32 v69, v81, v86, v82
	v_add_f32_dpp v68, v68, v68 row_ror:8 row_mask:0xf bank_mask:0xf bound_ctrl:1
	v_div_scale_f32 v85, s[4:5], v84, v84, s87
	v_div_fixup_f32 v69, v69, v83, s87
	v_mov_b32_e32 v83, v68
	v_rcp_f32_e32 v87, v85
	s_nop 0
	v_permlane16_swap_b32_e32 v68, v83
	v_add_f32_e32 v68, v68, v83
	v_fmamk_f32 v68, v68, 0x3c000000, v141
	v_mul_f32_e32 v83, 0x4f800000, v68
	v_cmp_gt_f32_e64 s[4:5], s86, v68
	v_fma_f32 v81, -v85, v87, 1.0
	v_fmac_f32_e32 v87, v81, v87
	v_cndmask_b32_e64 v68, v68, v83, s[4:5]
	v_div_scale_f32 v81, vcc, s87, v84, s87
	v_sqrt_f32_e32 v83, v68
	v_mul_f32_e32 v82, v81, v87
	v_fma_f32 v86, -v85, v82, v81
	v_fmac_f32_e32 v82, v86, v87
	v_fma_f32 v81, -v85, v82, v81
	v_add_u32_e32 v85, -1, v83
	v_fma_f32 v86, -v85, v83, v68
	v_cmp_ge_f32_e64 s[6:7], 0, v86
	v_add_u32_e32 v86, 1, v83
	v_fmac_f32_e32 v1, v35, v35
	v_cndmask_b32_e64 v85, v83, v85, s[6:7]
	v_fma_f32 v83, -v86, v83, v68
	v_cmp_lt_f32_e64 s[6:7], 0, v83
	v_fmac_f32_e32 v1, v51, v51
	v_lshlrev_b32_e32 v89, 2, v64
	v_cndmask_b32_e64 v83, v85, v86, s[6:7]
	v_mul_f32_e32 v85, 0x37800000, v83
	v_add_f32_dpp v1, v1, v1 quad_perm:[1,0,3,2] row_mask:0xf bank_mask:0xf bound_ctrl:1
	v_cndmask_b32_e64 v83, v83, v85, s[4:5]
	v_cmp_class_f32_e64 s[4:5], v68, v142
	v_add_f32_dpp v1, v1, v1 quad_perm:[2,3,0,1] row_mask:0xf bank_mask:0xf bound_ctrl:1
	v_fma_f32 v0, v2, v2, 0
	v_cndmask_b32_e64 v85, v83, v68, s[4:5]
	v_add_f32_dpp v1, v1, v1 row_half_mirror row_mask:0xf bank_mask:0xf bound_ctrl:1
	v_div_scale_f32 v83, s[4:5], v85, v85, s87
	s_nop 0
	v_add_f32_dpp v1, v1, v1 row_ror:8 row_mask:0xf bank_mask:0xf bound_ctrl:1
	v_rcp_f32_e32 v86, v83
	v_div_fmas_f32 v68, v81, v87, v82
	v_mov_b32_e32 v82, v1
	s_nop 1
	v_permlane16_swap_b32_e32 v1, v82
	v_add_f32_e32 v1, v1, v82
	v_fmamk_f32 v1, v1, 0x3c000000, v141
	v_fma_f32 v81, -v83, v86, 1.0
	v_mul_f32_e32 v82, 0x4f800000, v1
	v_cmp_gt_f32_e64 s[4:5], s86, v1
	v_fmac_f32_e32 v86, v81, v86
	v_div_scale_f32 v81, vcc, s87, v85, s87
	v_cndmask_b32_e64 v1, v1, v82, s[4:5]
	v_mul_f32_e32 v87, v81, v86
	v_sqrt_f32_e32 v82, v1
	v_div_fixup_f32 v68, v68, v84, s87
	v_fma_f32 v84, -v83, v87, v81
	v_fmac_f32_e32 v87, v84, v86
	v_fma_f32 v88, -v83, v87, v81
	global_load_dword v81, v89, s[8:9]
	v_add_u32_e32 v83, -1, v82
	v_fma_f32 v84, -v83, v82, v1
	v_cmp_ge_f32_e64 s[6:7], 0, v84
	v_add_u32_e32 v84, 1, v82
	v_fma_f32 v90, -v84, v82, v1
	v_cndmask_b32_e64 v83, v82, v83, s[6:7]
	global_load_dword v82, v89, s[8:9] offset:128
	v_cmp_lt_f32_e64 s[6:7], 0, v90
	v_fmac_f32_e32 v0, v18, v18
	v_fmac_f32_e32 v0, v34, v34
	v_cndmask_b32_e64 v83, v83, v84, s[6:7]
	v_mul_f32_e32 v84, 0x37800000, v83
	v_cndmask_b32_e64 v84, v83, v84, s[4:5]
	global_load_dword v83, v89, s[8:9] offset:256
	v_cmp_class_f32_e64 s[4:5], v1, v142
	v_fma_f32 v52, -v140, v95, v52
	v_fmac_f32_e32 v0, v52, v52
	v_cndmask_b32_e64 v1, v84, v1, s[4:5]
	global_load_dword v84, v89, s[8:9] offset:384
	v_add_f32_dpp v0, v0, v0 quad_perm:[1,0,3,2] row_mask:0xf bank_mask:0xf bound_ctrl:1
	v_div_scale_f32 v90, s[4:5], v1, v1, s87
	s_nop 0
	v_add_f32_dpp v0, v0, v0 quad_perm:[2,3,0,1] row_mask:0xf bank_mask:0xf bound_ctrl:1
	v_div_fmas_f32 v86, v88, v86, v87
	v_rcp_f32_e32 v89, v90
	v_add_f32_dpp v0, v0, v0 row_half_mirror row_mask:0xf bank_mask:0xf bound_ctrl:1
	v_div_fixup_f32 v85, v86, v85, s87
	v_mov_b32_e32 v133, v128
	v_add_f32_dpp v0, v0, v0 row_ror:8 row_mask:0xf bank_mask:0xf bound_ctrl:1
	v_mov_b32_e32 v88, v0
	s_nop 1
	v_permlane16_swap_b32_e32 v0, v88
	v_add_f32_e32 v0, v0, v88
	v_fmamk_f32 v0, v0, 0x3c000000, v141
	v_mul_f32_e32 v88, 0x4f800000, v0
	v_cmp_gt_f32_e64 s[4:5], s86, v0
	v_fma_f32 v86, -v90, v89, 1.0
	v_fmac_f32_e32 v89, v86, v89
	v_cndmask_b32_e64 v0, v0, v88, s[4:5]
	v_div_scale_f32 v86, vcc, s87, v1, s87
	v_sqrt_f32_e32 v88, v0
	v_mul_f32_e32 v87, v86, v89
	v_fma_f32 v91, -v90, v87, v86
	v_fmac_f32_e32 v87, v91, v89
	v_fma_f32 v86, -v90, v87, v86
	v_add_u32_e32 v90, -1, v88
	v_fma_f32 v91, -v90, v88, v0
	v_cmp_ge_f32_e64 s[6:7], 0, v91
	v_add_u32_e32 v91, 1, v88
	v_div_fmas_f32 v86, v86, v89, v87
	v_cndmask_b32_e64 v90, v88, v90, s[6:7]
	v_fma_f32 v88, -v91, v88, v0
	v_cmp_lt_f32_e64 s[6:7], 0, v88
	v_div_fixup_f32 v87, v86, v1, s87
	v_mul_f32_e32 v17, v17, v72
	v_cndmask_b32_e64 v88, v90, v91, s[6:7]
	v_mul_f32_e32 v90, 0x37800000, v88
	v_cndmask_b32_e64 v88, v88, v90, s[4:5]
	v_cmp_class_f32_e64 s[4:5], v0, v142
	v_lshlrev_b32_e32 v64, 1, v64
	v_mul_f32_e32 v16, v16, v73
	v_cndmask_b32_e64 v0, v88, v0, s[4:5]
	v_div_scale_f32 v88, s[4:5], v0, v0, s87
	v_rcp_f32_e32 v90, v88
	v_mul_f32_e32 v15, v15, v75
	v_mul_f32_e32 v14, v14, v77
	v_mul_f32_e32 v12, v12, v79
	v_fma_f32 v1, -v88, v90, 1.0
	v_fmac_f32_e32 v90, v1, v90
	v_div_scale_f32 v1, vcc, s87, v0, s87
	v_mul_f32_e32 v86, v1, v90
	v_fma_f32 v89, -v88, v86, v1
	v_fmac_f32_e32 v86, v89, v90
	v_fma_f32 v1, -v88, v86, v1
	v_div_fmas_f32 v1, v1, v90, v86
	v_lshlrev_b32_e32 v88, 2, v65
	v_div_fixup_f32 v86, v1, v0, s87
	v_lshl_add_u64 v[0:1], s[66:67], 0, v[132:133]
	v_mov_b32_e32 v65, v128
	v_ashrrev_i32_e32 v89, 31, v88
	s_waitcnt vmcnt(3)
	v_mul_f32_e32 v17, v17, v81
	v_lshl_add_u64 v[64:65], v[0:1], 0, v[64:65]
	v_mbcnt_lo_u32_b32 v236, -1, 0
	v_mbcnt_hi_u32_b32 v236, -1, v236
	v_and_b32_e32 v237, 31, v236
	v_lshrrev_b32_e32 v238, 5, v236
	v_lshlrev_b32_e32 v239, 1, v237
	v_lshl_add_u32 v240, v238, 10, v239
	v_mov_b32_e32 v238, s93
	v_lshlrev_b32_e32 v238, 13, v238
	v_add_u32_e32 v238, 0x18000, v238
	v_add_u32_e32 v240, v240, v238
	v_lshl_add_u32 v241, v236, 4, v238
	v_lshrrev_b32_e32 v237, 4, v236
	v_and_b32_e32 v236, 15, v236
	v_lshlrev_b32_e32 v237, 11, v237
	v_lshl_add_u32 v237, v236, 4, v237
	v_sub_u32_e32 v236, v237, v239
	v_ashrrev_i32_e32 v237, 31, v236
	v_lshl_add_u64 v[242:243], v[64:65], 0, v[236:237]
	v_mov_b32_e32 v232, 0x2000
	v_mov_b32_e32 v233, 0
	v_lshlrev_b64 v[0:1], 11, v[88:89]
	v_bfe_u32 v89, v17, 16, 1
	v_lshl_add_u64 v[0:1], v[64:65], 0, v[0:1]
	v_add3_u32 v17, v17, v89, s88
	ds_write_b16_d16_hi v240, v17
	v_mul_f32_e32 v17, v33, v72
	s_waitcnt vmcnt(2)
	v_mul_f32_e32 v17, v17, v82
	v_bfe_u32 v33, v17, 16, 1
	v_add3_u32 v17, v17, v33, s88
	ds_write_b16_d16_hi v240, v17 offset:64
	v_mul_f32_e32 v17, v49, v72
	s_waitcnt vmcnt(1)
	v_mul_f32_e32 v17, v17, v83
	v_bfe_u32 v33, v17, 16, 1
	v_add3_u32 v17, v17, v33, s88
	ds_write_b16_d16_hi v240, v17 offset:128
	v_mul_f32_e32 v17, v67, v72
	s_waitcnt vmcnt(0)
	v_mul_f32_e32 v17, v17, v84
	v_bfe_u32 v33, v17, 16, 1
	v_or_b32_e32 v90, 1, v88
	v_add3_u32 v17, v17, v33, s88
	v_ashrrev_i32_e32 v91, 31, v90
	v_mul_f32_e32 v16, v16, v81
	ds_write_b16_d16_hi v240, v17 offset:192
	v_lshlrev_b64 v[90:91], 11, v[90:91]
	v_bfe_u32 v17, v16, 16, 1
	v_lshl_add_u64 v[90:91], v[64:65], 0, v[90:91]
	v_add3_u32 v16, v16, v17, s88
	ds_write_b16_d16_hi v240, v16 offset:256
	v_mul_f32_e32 v16, v32, v73
	v_mul_f32_e32 v16, v16, v82
	v_bfe_u32 v17, v16, 16, 1
	v_add3_u32 v16, v16, v17, s88
	ds_write_b16_d16_hi v240, v16 offset:320
	v_mul_f32_e32 v16, v48, v73
	v_mul_f32_e32 v16, v16, v83
	v_bfe_u32 v17, v16, 16, 1
	v_add3_u32 v16, v16, v17, s88
	ds_write_b16_d16_hi v240, v16 offset:384
	v_mul_f32_e32 v16, v66, v73
	v_mul_f32_e32 v16, v16, v84
	v_bfe_u32 v17, v16, 16, 1
	v_add3_u32 v16, v16, v17, s88
	ds_write_b16_d16_hi v240, v16 offset:448
	v_or_b32_e32 v16, 2, v88
	v_ashrrev_i32_e32 v17, 31, v16
	v_mul_f32_e32 v15, v15, v81
	v_lshlrev_b64 v[16:17], 11, v[16:17]
	v_bfe_u32 v32, v15, 16, 1
	v_lshl_add_u64 v[16:17], v[64:65], 0, v[16:17]
	v_add3_u32 v15, v15, v32, s88
	ds_write_b16_d16_hi v240, v15 offset:512
	v_mul_f32_e32 v15, v31, v75
	v_mul_f32_e32 v15, v15, v82
	v_bfe_u32 v31, v15, 16, 1
	v_add3_u32 v15, v15, v31, s88
	ds_write_b16_d16_hi v240, v15 offset:576
	v_mul_f32_e32 v15, v47, v75
	v_mul_f32_e32 v15, v15, v83
	v_bfe_u32 v31, v15, 16, 1
	v_add3_u32 v15, v15, v31, s88
	ds_write_b16_d16_hi v240, v15 offset:640
	v_mul_f32_e32 v15, v63, v75
	v_mul_f32_e32 v15, v15, v84
	v_bfe_u32 v31, v15, 16, 1
	v_add3_u32 v15, v15, v31, s88
	ds_write_b16_d16_hi v240, v15 offset:704
	v_or_b32_e32 v16, 3, v88
	v_ashrrev_i32_e32 v17, 31, v16
	v_mul_f32_e32 v14, v14, v81
	v_lshlrev_b64 v[16:17], 11, v[16:17]
	v_bfe_u32 v15, v14, 16, 1
	v_lshl_add_u64 v[16:17], v[64:65], 0, v[16:17]
	v_add3_u32 v14, v14, v15, s88
	ds_write_b16_d16_hi v240, v14 offset:768
	v_mul_f32_e32 v14, v30, v77
	v_mul_f32_e32 v14, v14, v82
	v_bfe_u32 v15, v14, 16, 1
	v_add3_u32 v14, v14, v15, s88
	ds_write_b16_d16_hi v240, v14 offset:832
	v_mul_f32_e32 v14, v46, v77
	v_mul_f32_e32 v14, v14, v83
	v_bfe_u32 v15, v14, 16, 1
	v_add3_u32 v14, v14, v15, s88
	ds_write_b16_d16_hi v240, v14 offset:896
	v_mul_f32_e32 v14, v62, v77
	v_mul_f32_e32 v14, v14, v84
	v_bfe_u32 v15, v14, 16, 1
	v_add3_u32 v14, v14, v15, s88
	s_mov_b64 s[4:5], 0x4000
	v_mul_f32_e32 v12, v12, v81
	ds_write_b16_d16_hi v240, v14 offset:960
	v_lshl_add_u64 v[14:15], v[0:1], 0, s[4:5]
	v_bfe_u32 v16, v12, 16, 1
	s_movk_i32 s4, 0x4000
	v_add3_u32 v12, v12, v16, s88
	v_add_co_u32_e32 v16, vcc, s4, v0
	s_movk_i32 s4, 0x5000
	s_nop 0
	v_addc_co_u32_e32 v17, vcc, 0, v1, vcc
	v_add_co_u32_e32 v30, vcc, s4, v0
	v_mul_f32_e32 v10, v10, v80
	s_nop 0
	v_addc_co_u32_e32 v31, vcc, 0, v1, vcc
	ds_write_b16_d16_hi v240, v12 offset:2048
	v_mul_f32_e32 v12, v28, v79
	v_mul_f32_e32 v12, v12, v82
	v_bfe_u32 v28, v12, 16, 1
	v_add3_u32 v12, v12, v28, s88
	ds_write_b16_d16_hi v240, v12 offset:2112
	v_mul_f32_e32 v12, v44, v79
	v_mul_f32_e32 v12, v12, v83
	v_bfe_u32 v28, v12, 16, 1
	v_add3_u32 v12, v12, v28, s88
	ds_write_b16_d16_hi v240, v12 offset:2176
	v_mul_f32_e32 v12, v60, v79
	v_mul_f32_e32 v12, v12, v84
	v_bfe_u32 v28, v12, 16, 1
	v_add3_u32 v12, v12, v28, s88
	v_mul_f32_e32 v10, v10, v81
	ds_write_b16_d16_hi v240, v12 offset:2240
	v_bfe_u32 v12, v10, 16, 1
	v_add3_u32 v10, v10, v12, s88
	ds_write_b16_d16_hi v240, v10 offset:2304
	v_mul_f32_e32 v10, v26, v80
	v_mul_f32_e32 v10, v10, v82
	s_mov_b64 s[4:5], 0x4800
	v_bfe_u32 v12, v10, 16, 1
	v_lshl_add_u64 v[14:15], v[0:1], 0, s[4:5]
	v_add3_u32 v10, v10, v12, s88
	ds_write_b16_d16_hi v240, v10 offset:2368
	v_mul_f32_e32 v10, v42, v80
	v_mul_f32_e32 v10, v10, v83
	v_bfe_u32 v12, v10, 16, 1
	v_add3_u32 v10, v10, v12, s88
	ds_write_b16_d16_hi v240, v10 offset:2432
	v_mul_f32_e32 v10, v58, v80
	v_mul_f32_e32 v10, v10, v84
	v_bfe_u32 v12, v10, 16, 1
	v_mul_f32_e32 v9, v9, v78
	v_add3_u32 v10, v10, v12, s88
	v_mul_f32_e32 v9, v9, v81
	ds_write_b16_d16_hi v240, v10 offset:2496
	v_bfe_u32 v10, v9, 16, 1
	v_add3_u32 v9, v9, v10, s88
	ds_write_b16_d16_hi v240, v9 offset:2560
	v_mul_f32_e32 v9, v24, v78
	v_mul_f32_e32 v9, v9, v82
	s_mov_b64 s[4:5], 0x5000
	v_bfe_u32 v10, v9, 16, 1
	v_lshl_add_u64 v[14:15], v[0:1], 0, s[4:5]
	v_add3_u32 v9, v9, v10, s88
	ds_write_b16_d16_hi v240, v9 offset:2624
	v_mul_f32_e32 v9, v40, v78
	v_mul_f32_e32 v9, v9, v83
	v_bfe_u32 v10, v9, 16, 1
	v_add3_u32 v9, v9, v10, s88
	ds_write_b16_d16_hi v240, v9 offset:2688
	v_mul_f32_e32 v9, v56, v78
	v_mul_f32_e32 v9, v9, v84
	v_bfe_u32 v10, v9, 16, 1
	v_mul_f32_e32 v7, v7, v76
	v_add3_u32 v9, v9, v10, s88
	v_mul_f32_e32 v7, v7, v81
	ds_write_b16_d16_hi v240, v9 offset:2752
	v_bfe_u32 v9, v7, 16, 1
	v_add3_u32 v7, v7, v9, s88
	ds_write_b16_d16_hi v240, v7 offset:2816
	v_mul_f32_e32 v7, v22, v76
	v_mul_f32_e32 v7, v7, v82
	s_mov_b64 s[4:5], 0x5800
	v_bfe_u32 v9, v7, 16, 1
	v_lshl_add_u64 v[14:15], v[0:1], 0, s[4:5]
	v_add3_u32 v7, v7, v9, s88
	ds_write_b16_d16_hi v240, v7 offset:2880
	v_mul_f32_e32 v7, v38, v76
	v_mul_f32_e32 v7, v7, v83
	v_bfe_u32 v9, v7, 16, 1
	v_add3_u32 v7, v7, v9, s88
	ds_write_b16_d16_hi v240, v7 offset:2944
	v_mul_f32_e32 v7, v53, v76
	v_mul_f32_e32 v7, v7, v84
	v_bfe_u32 v9, v7, 16, 1
	v_add3_u32 v7, v7, v9, s88
	s_mov_b64 s[4:5], 0x8000
	ds_write_b16_d16_hi v240, v7 offset:3008
	v_lshl_add_u64 v[14:15], v[0:1], 0, s[4:5]
	s_mov_b32 s4, 0x8000
	v_mul_f32_e32 v7, v13, v74
	v_add_co_u32_e32 v12, vcc, s4, v0
	v_mul_f32_e32 v7, v7, v81
	s_nop 0
	v_addc_co_u32_e32 v13, vcc, 0, v1, vcc
	s_mov_b32 s4, 0x9000
	v_bfe_u32 v9, v7, 16, 1
	v_add_co_u32_e32 v16, vcc, s4, v0
	v_add3_u32 v7, v7, v9, s88
	s_nop 0
	v_addc_co_u32_e32 v17, vcc, 0, v1, vcc
	ds_write_b16_d16_hi v240, v7 offset:4096
	v_mul_f32_e32 v7, v29, v74
	v_mul_f32_e32 v7, v7, v82
	v_bfe_u32 v9, v7, 16, 1
	v_add3_u32 v7, v7, v9, s88
	ds_write_b16_d16_hi v240, v7 offset:4160
	v_mul_f32_e32 v7, v45, v74
	v_mul_f32_e32 v7, v7, v83
	v_bfe_u32 v9, v7, 16, 1
	v_add3_u32 v7, v7, v9, s88
	ds_write_b16_d16_hi v240, v7 offset:4224
	v_mul_f32_e32 v7, v61, v74
	v_mul_f32_e32 v7, v7, v84
	v_bfe_u32 v9, v7, 16, 1
	v_add3_u32 v7, v7, v9, s88
	ds_write_b16_d16_hi v240, v7 offset:4288
	v_mul_f32_e32 v7, v11, v71
	v_mul_f32_e32 v7, v7, v81
	v_bfe_u32 v9, v7, 16, 1
	v_add3_u32 v7, v7, v9, s88
	ds_write_b16_d16_hi v240, v7 offset:4352
	v_mul_f32_e32 v7, v27, v71
	v_mul_f32_e32 v7, v7, v82
	s_mov_b64 s[4:5], 0x8800
	v_bfe_u32 v9, v7, 16, 1
	v_lshl_add_u64 v[14:15], v[0:1], 0, s[4:5]
	v_add3_u32 v7, v7, v9, s88
	ds_write_b16_d16_hi v240, v7 offset:4416
	v_mul_f32_e32 v7, v43, v71
	v_mul_f32_e32 v7, v7, v83
	v_bfe_u32 v9, v7, 16, 1
	v_add3_u32 v7, v7, v9, s88
	ds_write_b16_d16_hi v240, v7 offset:4480
	v_mul_f32_e32 v7, v59, v71
	v_mul_f32_e32 v7, v7, v84
	v_bfe_u32 v9, v7, 16, 1
	v_add3_u32 v7, v7, v9, s88
	ds_write_b16_d16_hi v240, v7 offset:4544
	v_mul_f32_e32 v7, v8, v70
	v_mul_f32_e32 v7, v7, v81
	v_bfe_u32 v8, v7, 16, 1
	v_add3_u32 v7, v7, v8, s88
	ds_write_b16_d16_hi v240, v7 offset:4608
	v_mul_f32_e32 v7, v25, v70
	v_mul_f32_e32 v7, v7, v82
	s_mov_b64 s[4:5], 0x9000
	v_bfe_u32 v8, v7, 16, 1
	v_lshl_add_u64 v[10:11], v[0:1], 0, s[4:5]
	v_add3_u32 v7, v7, v8, s88
	ds_write_b16_d16_hi v240, v7 offset:4672
	v_mul_f32_e32 v7, v41, v70
	v_mul_f32_e32 v7, v7, v83
	v_bfe_u32 v8, v7, 16, 1
	v_add3_u32 v7, v7, v8, s88
	ds_write_b16_d16_hi v240, v7 offset:4736
	v_mul_f32_e32 v7, v57, v70
	v_mul_f32_e32 v7, v7, v84
	v_bfe_u32 v8, v7, 16, 1
	v_mul_f32_e32 v6, v6, v69
	v_add3_u32 v7, v7, v8, s88
	v_mul_f32_e32 v6, v6, v81
	ds_write_b16_d16_hi v240, v7 offset:4800
	v_bfe_u32 v7, v6, 16, 1
	v_add3_u32 v6, v6, v7, s88
	ds_write_b16_d16_hi v240, v6 offset:4864
	v_mul_f32_e32 v6, v23, v69
	v_mul_f32_e32 v6, v6, v82
	s_mov_b64 s[4:5], 0x9800
	v_bfe_u32 v7, v6, 16, 1
	v_lshl_add_u64 v[8:9], v[0:1], 0, s[4:5]
	v_add3_u32 v6, v6, v7, s88
	ds_write_b16_d16_hi v240, v6 offset:4928
	v_mul_f32_e32 v6, v39, v69
	v_mul_f32_e32 v6, v6, v83
	v_bfe_u32 v7, v6, 16, 1
	v_add3_u32 v6, v6, v7, s88
	ds_write_b16_d16_hi v240, v6 offset:4992
	v_mul_f32_e32 v6, v54, v69
	v_mul_f32_e32 v6, v6, v84
	v_bfe_u32 v7, v6, 16, 1
	v_mul_f32_e32 v5, v5, v68
	v_add3_u32 v6, v6, v7, s88
	s_mov_b64 s[4:5], 0xc000
	v_mul_f32_e32 v5, v5, v81
	ds_write_b16_d16_hi v240, v6 offset:5056
	v_lshl_add_u64 v[6:7], v[0:1], 0, s[4:5]
	v_bfe_u32 v8, v5, 16, 1
	s_mov_b32 s4, 0xc000
	v_add3_u32 v5, v5, v8, s88
	v_add_co_u32_e32 v8, vcc, s4, v0
	v_mul_f32_e32 v4, v4, v85
	s_nop 0
	v_addc_co_u32_e32 v9, vcc, 0, v1, vcc
	v_add_co_u32_e32 v10, vcc, s89, v0
	v_mul_f32_e32 v4, v4, v81
	s_nop 0
	v_addc_co_u32_e32 v11, vcc, 0, v1, vcc
	ds_write_b16_d16_hi v240, v5 offset:6144
	v_mul_f32_e32 v5, v21, v68
	v_mul_f32_e32 v5, v5, v82
	v_bfe_u32 v12, v5, 16, 1
	v_add3_u32 v5, v5, v12, s88
	ds_write_b16_d16_hi v240, v5 offset:6208
	v_mul_f32_e32 v5, v37, v68
	v_mul_f32_e32 v5, v5, v83
	v_bfe_u32 v12, v5, 16, 1
	v_add3_u32 v5, v5, v12, s88
	ds_write_b16_d16_hi v240, v5 offset:6272
	v_mul_f32_e32 v5, v50, v68
	v_mul_f32_e32 v5, v5, v84
	v_bfe_u32 v12, v5, 16, 1
	v_add3_u32 v5, v5, v12, s88
	ds_write_b16_d16_hi v240, v5 offset:6336
	v_bfe_u32 v5, v4, 16, 1
	v_add3_u32 v4, v4, v5, s88
	ds_write_b16_d16_hi v240, v4 offset:6400
	v_mul_f32_e32 v4, v20, v85
	v_mul_f32_e32 v4, v4, v82
	s_mov_b64 s[4:5], 0xc800
	v_bfe_u32 v5, v4, 16, 1
	v_lshl_add_u64 v[6:7], v[0:1], 0, s[4:5]
	v_add3_u32 v4, v4, v5, s88
	ds_write_b16_d16_hi v240, v4 offset:6464
	v_mul_f32_e32 v4, v36, v85
	v_mul_f32_e32 v4, v4, v83
	v_bfe_u32 v5, v4, 16, 1
	v_add3_u32 v4, v4, v5, s88
	ds_write_b16_d16_hi v240, v4 offset:6528
	v_mul_f32_e32 v4, v55, v85
	v_mul_f32_e32 v4, v4, v84
	v_bfe_u32 v5, v4, 16, 1
	v_mul_f32_e32 v3, v3, v87
	v_add3_u32 v4, v4, v5, s88
	v_mul_f32_e32 v3, v81, v3
	ds_write_b16_d16_hi v240, v4 offset:6592
	v_bfe_u32 v6, v3, 16, 1
	v_add3_u32 v3, v3, v6, s88
	ds_write_b16_d16_hi v240, v3 offset:6656
	v_mul_f32_e32 v3, v19, v87
	v_mul_f32_e32 v3, v82, v3
	s_mov_b64 s[4:5], 0xd000
	v_bfe_u32 v6, v3, 16, 1
	v_lshl_add_u64 v[4:5], v[0:1], 0, s[4:5]
	v_add3_u32 v3, v3, v6, s88
	ds_write_b16_d16_hi v240, v3 offset:6720
	v_mul_f32_e32 v3, v35, v87
	v_mul_f32_e32 v3, v3, v83
	v_bfe_u32 v6, v3, 16, 1
	v_add3_u32 v3, v3, v6, s88
	ds_write_b16_d16_hi v240, v3 offset:6784
	v_mul_f32_e32 v3, v51, v87
	v_mul_f32_e32 v3, v3, v84
	v_bfe_u32 v6, v3, 16, 1
	v_mul_f32_e32 v2, v2, v86
	v_add3_u32 v3, v3, v6, s88
	v_mul_f32_e32 v2, v81, v2
	ds_write_b16_d16_hi v240, v3 offset:6848
	v_bfe_u32 v3, v2, 16, 1
	v_add3_u32 v2, v2, v3, s88
	ds_write_b16_d16_hi v240, v2 offset:6912
	v_mul_f32_e32 v2, v18, v86
	v_mul_f32_e32 v2, v82, v2
	v_bfe_u32 v3, v2, 16, 1
	v_lshl_add_u64 v[0:1], v[0:1], 0, s[62:63]
	v_add3_u32 v2, v2, v3, s88
	ds_write_b16_d16_hi v240, v2 offset:6976
	v_mul_f32_e32 v2, v34, v86
	v_mul_f32_e32 v2, v83, v2
	v_bfe_u32 v3, v2, 16, 1
	v_add3_u32 v2, v2, v3, s88
	ds_write_b16_d16_hi v240, v2 offset:7040
	v_mul_f32_e32 v2, v52, v86
	v_mul_f32_e32 v2, v84, v2
	v_bfe_u32 v3, v2, 16, 1
	v_add3_u32 v2, v2, v3, s88
	ds_write_b16_d16_hi v240, v2 offset:7104
	s_waitcnt lgkmcnt(0)
	ds_read_b128 v[228:231], v241
	s_waitcnt lgkmcnt(0)
	global_store_dwordx4 v[242:243], v[228:231], off sc1
	s_nop 1
	v_lshl_add_u64 v[242:243], v[242:243], 0, v[232:233]
	ds_read_b128 v[244:247], v241 offset:1024
	s_waitcnt lgkmcnt(0)
	global_store_dwordx4 v[242:243], v[244:247], off sc1
	s_nop 1
	v_lshl_add_u64 v[242:243], v[242:243], 0, v[232:233]
	ds_read_b128 v[228:231], v241 offset:2048
	s_waitcnt lgkmcnt(0)
	global_store_dwordx4 v[242:243], v[228:231], off sc1
	s_nop 1
	v_lshl_add_u64 v[242:243], v[242:243], 0, v[232:233]
	ds_read_b128 v[244:247], v241 offset:3072
	s_waitcnt lgkmcnt(0)
	global_store_dwordx4 v[242:243], v[244:247], off sc1
	s_nop 1
	v_lshl_add_u64 v[242:243], v[242:243], 0, v[232:233]
	ds_read_b128 v[228:231], v241 offset:4096
	s_waitcnt lgkmcnt(0)
	global_store_dwordx4 v[242:243], v[228:231], off sc1
	s_nop 1
	v_lshl_add_u64 v[242:243], v[242:243], 0, v[232:233]
	ds_read_b128 v[244:247], v241 offset:5120
	s_waitcnt lgkmcnt(0)
	global_store_dwordx4 v[242:243], v[244:247], off sc1
	s_nop 1
	v_lshl_add_u64 v[242:243], v[242:243], 0, v[232:233]
	ds_read_b128 v[228:231], v241 offset:6144
	s_waitcnt lgkmcnt(0)
	global_store_dwordx4 v[242:243], v[228:231], off sc1
	s_nop 1
	v_lshl_add_u64 v[242:243], v[242:243], 0, v[232:233]
	ds_read_b128 v[244:247], v241 offset:7168
	s_waitcnt lgkmcnt(0)
	global_store_dwordx4 v[242:243], v[244:247], off sc1
	s_nop 1
	s_branch .LBB0_459

.LBB0_511:
	s_add_i32 s5, s25, s4
	s_sub_i32 s48, s5, 24
	s_ashr_i32 s49, s48, 31
	s_add_u32 s48, s44, s48
	s_addc_u32 s49, s45, s49
	ds_read_b128 v[10:13], v187 offset:14336
	ds_read_b128 v[6:9], v187 offset:14352
	ds_read_b128 v[18:21], v187 offset:12288
	ds_read_b128 v[14:17], v187 offset:12304
	ds_read_b128 v[26:29], v187 offset:10240
	ds_read_b128 v[22:25], v187 offset:10256
	ds_read_b128 v[34:37], v187 offset:8192
	ds_read_b128 v[30:33], v187 offset:8208
	ds_read_b128 v[42:45], v187 offset:6144
	ds_read_b128 v[38:41], v187 offset:6160
	ds_read_b128 v[58:61], v187 offset:4096
	ds_read_b128 v[54:57], v187 offset:4112
	ds_read_b128 v[66:69], v187 offset:2048
	ds_read_b128 v[62:65], v187 offset:2064
	ds_read_b128 v[82:85], v187
	ds_read_b128 v[78:81], v187 offset:16
	ds_read_b128 v[50:53], v187 offset:16384
	ds_read_b128 v[46:49], v187 offset:16400
	ds_read_b128 v[74:77], v187 offset:18432
	ds_read_b128 v[70:73], v187 offset:18448
	ds_read_b128 v[90:93], v187 offset:20480
	ds_read_b128 v[86:89], v187 offset:20496
	ds_read_b128 v[98:101], v187 offset:22528
	ds_read_b128 v[94:97], v187 offset:22544
	ds_read_b128 v[106:109], v187 offset:24576
	ds_read_b128 v[102:105], v187 offset:24592
	s_lshl_b64 s[48:49], s[48:49], 10
	s_waitcnt lgkmcnt(11)
	v_mov_b32_e32 v218, v82
	v_mov_b32_e32 v219, v84
	v_mov_b32_e32 v84, v83
	s_waitcnt lgkmcnt(10)
	v_mov_b32_e32 v82, v78
	v_mov_b32_e32 v83, v80
	v_mov_b32_e32 v80, v79
	v_lshl_add_u64 v[78:79], v[118:119], 0, s[48:49]
	global_load_dwordx4 v[188:191], v[78:79], off
	s_sub_i32 s50, s5, 23
	s_ashr_i32 s51, s50, 31
	s_add_u32 s48, s44, s50
	s_addc_u32 s49, s45, s51
	s_sub_i32 s50, s5, 22
	s_lshl_b64 s[48:49], s[48:49], 10
	s_ashr_i32 s51, s50, 31
	v_lshl_add_u64 v[78:79], v[118:119], 0, s[48:49]
	s_add_u32 s48, s44, s50
	s_addc_u32 s49, s45, s51
	s_sub_i32 s50, s5, 21
	s_lshl_b64 s[48:49], s[48:49], 10
	s_ashr_i32 s51, s50, 31
	global_load_dwordx4 v[192:195], v[78:79], off
	v_lshl_add_u64 v[78:79], v[118:119], 0, s[48:49]
	s_add_u32 s48, s44, s50
	s_addc_u32 s49, s45, s51
	s_sub_i32 s50, s5, 20
	s_lshl_b64 s[48:49], s[48:49], 10
	s_ashr_i32 s51, s50, 31
	global_load_dwordx4 v[196:199], v[78:79], off
	v_lshl_add_u64 v[78:79], v[118:119], 0, s[48:49]
	s_add_u32 s48, s44, s50
	s_addc_u32 s49, s45, s51
	s_sub_i32 s5, s5, 19
	s_lshl_b64 s[48:49], s[48:49], 10
	s_ashr_i32 s50, s5, 31
	v_mov_b32_e32 v212, v58
	v_mov_b32_e32 v213, v60
	v_mov_b32_e32 v60, v59
	s_waitcnt lgkmcnt(3)
	v_mov_b32_e32 v58, v98
	v_mov_b32_e32 v59, v100
	v_mov_b32_e32 v100, v99
	v_lshl_add_u64 v[98:99], v[118:119], 0, s[48:49]
	s_add_u32 s48, s44, s5
	s_addc_u32 s49, s45, s50
	v_add_u32_e32 v184, 0x3000, v187
	global_load_dwordx4 v[200:203], v[78:79], off
	s_lshl_b64 s[48:49], s[48:49], 10
	v_mov_b32_e32 v187, v184
	v_mov_b32_e32 v184, v10
	v_mov_b32_e32 v185, v12
	v_mov_b32_e32 v12, v11
	v_mov_b32_e32 v10, v6
	v_mov_b32_e32 v11, v8
	v_mov_b32_e32 v8, v7
	v_mov_b32_e32 v6, v18
	v_mov_b32_e32 v7, v20
	v_mov_b32_e32 v20, v19
	v_mov_b32_e32 v18, v14
	v_mov_b32_e32 v19, v16
	v_mov_b32_e32 v16, v15
	v_mov_b32_e32 v14, v26
	v_mov_b32_e32 v15, v28
	v_mov_b32_e32 v28, v27
	v_mov_b32_e32 v26, v22
	v_mov_b32_e32 v27, v24
	v_mov_b32_e32 v24, v23
	v_mov_b32_e32 v22, v34
	v_mov_b32_e32 v23, v36
	v_mov_b32_e32 v36, v35
	v_mov_b32_e32 v34, v30
	v_mov_b32_e32 v35, v32
	v_mov_b32_e32 v32, v31
	v_mov_b32_e32 v214, v54
	v_mov_b32_e32 v215, v56
	v_mov_b32_e32 v56, v55
	v_mov_b32_e32 v216, v66
	v_mov_b32_e32 v217, v68
	v_mov_b32_e32 v68, v67
	v_mov_b32_e32 v66, v62
	v_mov_b32_e32 v67, v64
	v_mov_b32_e32 v64, v63
	v_mov_b32_e32 v30, v50
	v_mov_b32_e32 v31, v52
	v_mov_b32_e32 v52, v51
	v_mov_b32_e32 v50, v90
	v_mov_b32_e32 v51, v92
	v_mov_b32_e32 v92, v91
	v_mov_b32_e32 v54, v86
	v_mov_b32_e32 v55, v88
	v_mov_b32_e32 v88, v87
	s_waitcnt lgkmcnt(2)
	v_mov_b32_e32 v62, v94
	v_mov_b32_e32 v63, v96
	v_mov_b32_e32 v96, v95
	s_waitcnt vmcnt(3)
	v_lshlrev_b32_e32 v79, 16, v189
	v_lshlrev_b32_e32 v78, 16, v188
	v_and_b32_e32 v87, 0xffff0000, v189
	v_and_b32_e32 v86, 0xffff0000, v188
	v_lshlrev_b32_e32 v91, 16, v191
	v_lshlrev_b32_e32 v90, 16, v190
	v_and_b32_e32 v95, 0xffff0000, v191
	v_and_b32_e32 v94, 0xffff0000, v190
	global_load_dwordx4 v[188:191], v[98:99], off
	v_lshl_add_u64 v[98:99], v[118:119], 0, s[48:49]
	global_load_dwordx4 v[204:207], v[98:99], off
	v_mov_b32_e32 v208, v42
	v_mov_b32_e32 v209, v44
	v_mov_b32_e32 v44, v43
	v_mov_b32_e32 v210, v38
	v_mov_b32_e32 v211, v40
	v_mov_b32_e32 v40, v39
	v_mov_b32_e32 v38, v46
	v_mov_b32_e32 v39, v48
	v_mov_b32_e32 v48, v47
	v_mov_b32_e32 v42, v74
	v_mov_b32_e32 v43, v76
	v_mov_b32_e32 v76, v75
	v_mov_b32_e32 v46, v70
	v_mov_b32_e32 v47, v72
	v_mov_b32_e32 v72, v71
	s_waitcnt lgkmcnt(1)
	v_mov_b32_e32 v70, v106
	v_mov_b32_e32 v71, v108
	v_mov_b32_e32 v108, v107
	s_waitcnt lgkmcnt(0)
	v_mov_b32_e32 v74, v102
	v_mov_b32_e32 v75, v104
	v_mov_b32_e32 v104, v103
	v_pk_fma_f32 v[4:5], v[212:213], v[78:79], v[4:5]
	v_pk_fma_f32 v[0:1], v[214:215], v[90:91], v[0:1]
	v_pk_fma_f32 v[98:99], v[184:185], v[78:79], v[182:183]
	v_pk_fma_f32 v[102:103], v[12:13], v[86:87], v[180:181]
	v_pk_fma_f32 v[106:107], v[10:11], v[90:91], v[178:179]
	v_pk_fma_f32 v[176:177], v[8:9], v[94:95], v[176:177]
	v_pk_fma_f32 v[174:175], v[6:7], v[78:79], v[174:175]
	v_pk_fma_f32 v[172:173], v[20:21], v[86:87], v[172:173]
	v_pk_fma_f32 v[170:171], v[18:19], v[90:91], v[170:171]
	v_pk_fma_f32 v[168:169], v[16:17], v[94:95], v[168:169]
	v_pk_fma_f32 v[166:167], v[14:15], v[78:79], v[166:167]
	v_pk_fma_f32 v[164:165], v[28:29], v[86:87], v[164:165]
	v_pk_fma_f32 v[162:163], v[26:27], v[90:91], v[162:163]
	v_pk_fma_f32 v[160:161], v[24:25], v[94:95], v[160:161]
	v_pk_fma_f32 v[158:159], v[22:23], v[78:79], v[158:159]
	v_pk_fma_f32 v[156:157], v[36:37], v[86:87], v[156:157]
	v_pk_fma_f32 v[154:155], v[34:35], v[90:91], v[154:155]
	v_pk_fma_f32 v[152:153], v[32:33], v[94:95], v[152:153]
	v_pk_fma_f32 v[150:151], v[208:209], v[78:79], v[150:151]
	v_pk_fma_f32 v[148:149], v[44:45], v[86:87], v[148:149]
	v_pk_fma_f32 v[146:147], v[210:211], v[90:91], v[146:147]
	v_pk_fma_f32 v[144:145], v[40:41], v[94:95], v[144:145]
	v_pk_fma_f32 v[142:143], v[60:61], v[86:87], v[142:143]
	v_pk_fma_f32 v[140:141], v[56:57], v[94:95], v[140:141]
	v_pk_fma_f32 v[138:139], v[216:217], v[78:79], v[138:139]
	v_pk_fma_f32 v[136:137], v[68:69], v[86:87], v[136:137]
	v_pk_fma_f32 v[134:135], v[66:67], v[90:91], v[134:135]
	v_pk_fma_f32 v[132:133], v[64:65], v[94:95], v[132:133]
	v_pk_fma_f32 v[78:79], v[218:219], v[78:79], v[130:131]
	v_pk_fma_f32 v[84:85], v[84:85], v[86:87], v[128:129]
	v_pk_fma_f32 v[82:83], v[82:83], v[90:91], v[126:127]
	v_pk_fma_f32 v[2:3], v[80:81], v[94:95], v[2:3]
	s_waitcnt vmcnt(4)
	v_lshlrev_b32_e32 v81, 16, v193
	v_lshlrev_b32_e32 v80, 16, v192
	v_and_b32_e32 v87, 0xffff0000, v193
	v_and_b32_e32 v86, 0xffff0000, v192
	v_lshlrev_b32_e32 v91, 16, v195
	v_lshlrev_b32_e32 v90, 16, v194
	v_and_b32_e32 v95, 0xffff0000, v195
	v_and_b32_e32 v94, 0xffff0000, v194
	v_pk_fma_f32 v[98:99], v[30:31], v[80:81], v[98:99]
	v_pk_fma_f32 v[102:103], v[52:53], v[86:87], v[102:103]
	v_pk_fma_f32 v[106:107], v[38:39], v[90:91], v[106:107]
	v_pk_fma_f32 v[126:127], v[48:49], v[94:95], v[176:177]
	v_pk_fma_f32 v[128:129], v[184:185], v[80:81], v[174:175]
	v_pk_fma_f32 v[130:131], v[12:13], v[86:87], v[172:173]
	v_pk_fma_f32 v[170:171], v[10:11], v[90:91], v[170:171]
	v_pk_fma_f32 v[168:169], v[8:9], v[94:95], v[168:169]
	v_pk_fma_f32 v[166:167], v[6:7], v[80:81], v[166:167]
	v_pk_fma_f32 v[164:165], v[20:21], v[86:87], v[164:165]
	v_pk_fma_f32 v[162:163], v[18:19], v[90:91], v[162:163]
	v_pk_fma_f32 v[160:161], v[16:17], v[94:95], v[160:161]
	v_pk_fma_f32 v[158:159], v[14:15], v[80:81], v[158:159]
	v_pk_fma_f32 v[156:157], v[28:29], v[86:87], v[156:157]
	v_pk_fma_f32 v[154:155], v[26:27], v[90:91], v[154:155]
	v_pk_fma_f32 v[152:153], v[24:25], v[94:95], v[152:153]
	v_pk_fma_f32 v[150:151], v[22:23], v[80:81], v[150:151]
	v_pk_fma_f32 v[148:149], v[36:37], v[86:87], v[148:149]
	v_pk_fma_f32 v[146:147], v[34:35], v[90:91], v[146:147]
	v_pk_fma_f32 v[144:145], v[32:33], v[94:95], v[144:145]
	v_pk_fma_f32 v[4:5], v[208:209], v[80:81], v[4:5]
	v_pk_fma_f32 v[142:143], v[44:45], v[86:87], v[142:143]
	v_pk_fma_f32 v[0:1], v[210:211], v[90:91], v[0:1]
	v_pk_fma_f32 v[140:141], v[40:41], v[94:95], v[140:141]
	v_pk_fma_f32 v[138:139], v[212:213], v[80:81], v[138:139]
	v_pk_fma_f32 v[136:137], v[60:61], v[86:87], v[136:137]
	v_pk_fma_f32 v[134:135], v[214:215], v[90:91], v[134:135]
	v_pk_fma_f32 v[132:133], v[56:57], v[94:95], v[132:133]
	v_pk_fma_f32 v[78:79], v[216:217], v[80:81], v[78:79]
	v_pk_fma_f32 v[68:69], v[68:69], v[86:87], v[84:85]
	v_pk_fma_f32 v[66:67], v[66:67], v[90:91], v[82:83]
	v_pk_fma_f32 v[2:3], v[64:65], v[94:95], v[2:3]
	s_waitcnt vmcnt(3)
	v_lshlrev_b32_e32 v65, 16, v197
	v_lshlrev_b32_e32 v64, 16, v196
	v_and_b32_e32 v81, 0xffff0000, v197
	v_and_b32_e32 v80, 0xffff0000, v196
	v_lshlrev_b32_e32 v83, 16, v199
	v_lshlrev_b32_e32 v82, 16, v198
	v_and_b32_e32 v85, 0xffff0000, v199
	v_and_b32_e32 v84, 0xffff0000, v198
	v_pk_fma_f32 v[86:87], v[42:43], v[64:65], v[98:99]
	v_pk_fma_f32 v[90:91], v[76:77], v[80:81], v[102:103]
	v_pk_fma_f32 v[94:95], v[46:47], v[82:83], v[106:107]
	v_pk_fma_f32 v[98:99], v[72:73], v[84:85], v[126:127]
	v_pk_fma_f32 v[102:103], v[30:31], v[64:65], v[128:129]
	v_pk_fma_f32 v[106:107], v[52:53], v[80:81], v[130:131]
	v_pk_fma_f32 v[126:127], v[38:39], v[82:83], v[170:171]
	v_pk_fma_f32 v[128:129], v[48:49], v[84:85], v[168:169]
	v_pk_fma_f32 v[130:131], v[184:185], v[64:65], v[166:167]
	v_pk_fma_f32 v[164:165], v[12:13], v[80:81], v[164:165]
	v_pk_fma_f32 v[162:163], v[10:11], v[82:83], v[162:163]
	v_pk_fma_f32 v[160:161], v[8:9], v[84:85], v[160:161]
	v_pk_fma_f32 v[158:159], v[6:7], v[64:65], v[158:159]
	v_pk_fma_f32 v[156:157], v[20:21], v[80:81], v[156:157]
	v_pk_fma_f32 v[154:155], v[18:19], v[82:83], v[154:155]
	v_pk_fma_f32 v[152:153], v[16:17], v[84:85], v[152:153]
	v_pk_fma_f32 v[150:151], v[14:15], v[64:65], v[150:151]
	v_pk_fma_f32 v[148:149], v[28:29], v[80:81], v[148:149]
	v_pk_fma_f32 v[146:147], v[26:27], v[82:83], v[146:147]
	v_pk_fma_f32 v[144:145], v[24:25], v[84:85], v[144:145]
	v_pk_fma_f32 v[4:5], v[22:23], v[64:65], v[4:5]
	v_pk_fma_f32 v[142:143], v[36:37], v[80:81], v[142:143]
	v_pk_fma_f32 v[0:1], v[34:35], v[82:83], v[0:1]
	v_pk_fma_f32 v[140:141], v[32:33], v[84:85], v[140:141]
	v_pk_fma_f32 v[138:139], v[208:209], v[64:65], v[138:139]
	v_pk_fma_f32 v[136:137], v[44:45], v[80:81], v[136:137]
	v_pk_fma_f32 v[134:135], v[210:211], v[82:83], v[134:135]
	v_pk_fma_f32 v[132:133], v[40:41], v[84:85], v[132:133]
	v_pk_fma_f32 v[64:65], v[212:213], v[64:65], v[78:79]
	v_pk_fma_f32 v[60:61], v[60:61], v[80:81], v[68:69]
	v_pk_fma_f32 v[66:67], v[214:215], v[82:83], v[66:67]
	v_pk_fma_f32 v[2:3], v[56:57], v[84:85], v[2:3]
	s_waitcnt vmcnt(2)
	v_lshlrev_b32_e32 v57, 16, v201
	v_lshlrev_b32_e32 v56, 16, v200
	v_and_b32_e32 v69, 0xffff0000, v201
	v_and_b32_e32 v68, 0xffff0000, v200
	v_lshlrev_b32_e32 v79, 16, v203
	v_lshlrev_b32_e32 v78, 16, v202
	v_and_b32_e32 v81, 0xffff0000, v203
	v_and_b32_e32 v80, 0xffff0000, v202
	v_pk_fma_f32 v[82:83], v[50:51], v[56:57], v[86:87]
	v_pk_fma_f32 v[84:85], v[92:93], v[68:69], v[90:91]
	v_pk_fma_f32 v[86:87], v[54:55], v[78:79], v[94:95]
	v_pk_fma_f32 v[90:91], v[88:89], v[80:81], v[98:99]
	v_pk_fma_f32 v[94:95], v[42:43], v[56:57], v[102:103]
	v_pk_fma_f32 v[98:99], v[76:77], v[68:69], v[106:107]
	v_pk_fma_f32 v[102:103], v[46:47], v[78:79], v[126:127]
	v_pk_fma_f32 v[106:107], v[72:73], v[80:81], v[128:129]
	v_pk_fma_f32 v[126:127], v[30:31], v[56:57], v[130:131]
	v_pk_fma_f32 v[128:129], v[52:53], v[68:69], v[164:165]
	v_pk_fma_f32 v[130:131], v[38:39], v[78:79], v[162:163]
	v_pk_fma_f32 v[160:161], v[48:49], v[80:81], v[160:161]
	v_pk_fma_f32 v[158:159], v[184:185], v[56:57], v[158:159]
	v_pk_fma_f32 v[156:157], v[12:13], v[68:69], v[156:157]
	v_pk_fma_f32 v[154:155], v[10:11], v[78:79], v[154:155]
	v_pk_fma_f32 v[152:153], v[8:9], v[80:81], v[152:153]
	v_pk_fma_f32 v[150:151], v[6:7], v[56:57], v[150:151]
	v_pk_fma_f32 v[148:149], v[20:21], v[68:69], v[148:149]
	v_pk_fma_f32 v[146:147], v[18:19], v[78:79], v[146:147]
	v_pk_fma_f32 v[144:145], v[16:17], v[80:81], v[144:145]
	v_pk_fma_f32 v[4:5], v[14:15], v[56:57], v[4:5]
	v_pk_fma_f32 v[142:143], v[28:29], v[68:69], v[142:143]
	v_pk_fma_f32 v[0:1], v[26:27], v[78:79], v[0:1]
	v_pk_fma_f32 v[140:141], v[24:25], v[80:81], v[140:141]
	v_pk_fma_f32 v[138:139], v[22:23], v[56:57], v[138:139]
	v_pk_fma_f32 v[136:137], v[36:37], v[68:69], v[136:137]
	v_pk_fma_f32 v[134:135], v[34:35], v[78:79], v[134:135]
	v_pk_fma_f32 v[132:133], v[32:33], v[80:81], v[132:133]
	v_pk_fma_f32 v[56:57], v[208:209], v[56:57], v[64:65]
	v_pk_fma_f32 v[44:45], v[44:45], v[68:69], v[60:61]
	v_pk_fma_f32 v[60:61], v[210:211], v[78:79], v[66:67]
	v_pk_fma_f32 v[2:3], v[40:41], v[80:81], v[2:3]
	s_waitcnt vmcnt(1)
	v_lshlrev_b32_e32 v41, 16, v189
	v_lshlrev_b32_e32 v40, 16, v188
	v_and_b32_e32 v65, 0xffff0000, v189
	v_and_b32_e32 v64, 0xffff0000, v188
	v_lshlrev_b32_e32 v67, 16, v191
	v_lshlrev_b32_e32 v66, 16, v190
	v_and_b32_e32 v69, 0xffff0000, v191
	v_and_b32_e32 v68, 0xffff0000, v190
	s_add_i32 s4, s4, 6
	v_pk_fma_f32 v[78:79], v[58:59], v[40:41], v[82:83]
	v_pk_fma_f32 v[80:81], v[100:101], v[64:65], v[84:85]
	v_pk_fma_f32 v[82:83], v[62:63], v[66:67], v[86:87]
	v_pk_fma_f32 v[84:85], v[96:97], v[68:69], v[90:91]
	v_pk_fma_f32 v[86:87], v[50:51], v[40:41], v[94:95]
	v_pk_fma_f32 v[90:91], v[92:93], v[64:65], v[98:99]
	v_pk_fma_f32 v[94:95], v[54:55], v[66:67], v[102:103]
	v_pk_fma_f32 v[98:99], v[88:89], v[68:69], v[106:107]
	v_pk_fma_f32 v[102:103], v[42:43], v[40:41], v[126:127]
	v_pk_fma_f32 v[106:107], v[76:77], v[64:65], v[128:129]
	v_pk_fma_f32 v[126:127], v[46:47], v[66:67], v[130:131]
	v_pk_fma_f32 v[128:129], v[72:73], v[68:69], v[160:161]
	v_pk_fma_f32 v[130:131], v[30:31], v[40:41], v[158:159]
	v_pk_fma_f32 v[156:157], v[52:53], v[64:65], v[156:157]
	v_pk_fma_f32 v[154:155], v[38:39], v[66:67], v[154:155]
	v_pk_fma_f32 v[152:153], v[48:49], v[68:69], v[152:153]
	v_pk_fma_f32 v[150:151], v[184:185], v[40:41], v[150:151]
	v_pk_fma_f32 v[148:149], v[12:13], v[64:65], v[148:149]
	v_pk_fma_f32 v[146:147], v[10:11], v[66:67], v[146:147]
	v_pk_fma_f32 v[144:145], v[8:9], v[68:69], v[144:145]
	v_pk_fma_f32 v[4:5], v[6:7], v[40:41], v[4:5]
	v_pk_fma_f32 v[142:143], v[20:21], v[64:65], v[142:143]
	v_pk_fma_f32 v[0:1], v[18:19], v[66:67], v[0:1]
	v_pk_fma_f32 v[140:141], v[16:17], v[68:69], v[140:141]
	v_pk_fma_f32 v[138:139], v[14:15], v[40:41], v[138:139]
	v_pk_fma_f32 v[136:137], v[28:29], v[64:65], v[136:137]
	v_pk_fma_f32 v[134:135], v[26:27], v[66:67], v[134:135]
	v_pk_fma_f32 v[132:133], v[24:25], v[68:69], v[132:133]
	v_pk_fma_f32 v[22:23], v[22:23], v[40:41], v[56:57]
	v_pk_fma_f32 v[36:37], v[36:37], v[64:65], v[44:45]
	v_pk_fma_f32 v[34:35], v[34:35], v[66:67], v[60:61]
	v_pk_fma_f32 v[2:3], v[32:33], v[68:69], v[2:3]
	s_waitcnt vmcnt(0)
	v_lshlrev_b32_e32 v33, 16, v205
	v_lshlrev_b32_e32 v32, 16, v204
	v_and_b32_e32 v41, 0xffff0000, v205
	v_and_b32_e32 v40, 0xffff0000, v204
	v_lshlrev_b32_e32 v45, 16, v207
	v_lshlrev_b32_e32 v44, 16, v206
	v_and_b32_e32 v57, 0xffff0000, v207
	v_and_b32_e32 v56, 0xffff0000, v206
	s_cmp_lt_u32 s4, 32
	v_pk_fma_f32 v[182:183], v[70:71], v[32:33], v[78:79]
	v_pk_fma_f32 v[180:181], v[108:109], v[40:41], v[80:81]
	v_pk_fma_f32 v[178:179], v[74:75], v[44:45], v[82:83]
	v_pk_fma_f32 v[176:177], v[104:105], v[56:57], v[84:85]
	v_pk_fma_f32 v[174:175], v[58:59], v[32:33], v[86:87]
	v_pk_fma_f32 v[172:173], v[100:101], v[40:41], v[90:91]
	v_pk_fma_f32 v[170:171], v[62:63], v[44:45], v[94:95]
	v_pk_fma_f32 v[168:169], v[96:97], v[56:57], v[98:99]
	v_pk_fma_f32 v[166:167], v[50:51], v[32:33], v[102:103]
	v_pk_fma_f32 v[164:165], v[92:93], v[40:41], v[106:107]
	v_pk_fma_f32 v[162:163], v[54:55], v[44:45], v[126:127]
	v_pk_fma_f32 v[160:161], v[88:89], v[56:57], v[128:129]
	v_pk_fma_f32 v[158:159], v[42:43], v[32:33], v[130:131]
	v_pk_fma_f32 v[156:157], v[76:77], v[40:41], v[156:157]
	v_pk_fma_f32 v[154:155], v[46:47], v[44:45], v[154:155]
	v_pk_fma_f32 v[152:153], v[72:73], v[56:57], v[152:153]
	v_pk_fma_f32 v[150:151], v[30:31], v[32:33], v[150:151]
	v_pk_fma_f32 v[148:149], v[52:53], v[40:41], v[148:149]
	v_pk_fma_f32 v[146:147], v[38:39], v[44:45], v[146:147]
	v_pk_fma_f32 v[144:145], v[48:49], v[56:57], v[144:145]
	v_pk_fma_f32 v[4:5], v[184:185], v[32:33], v[4:5]
	v_pk_fma_f32 v[142:143], v[12:13], v[40:41], v[142:143]
	v_pk_fma_f32 v[0:1], v[10:11], v[44:45], v[0:1]
	v_pk_fma_f32 v[140:141], v[8:9], v[56:57], v[140:141]
	v_pk_fma_f32 v[138:139], v[6:7], v[32:33], v[138:139]
	v_pk_fma_f32 v[136:137], v[20:21], v[40:41], v[136:137]
	v_pk_fma_f32 v[134:135], v[18:19], v[44:45], v[134:135]
	v_pk_fma_f32 v[132:133], v[16:17], v[56:57], v[132:133]
	v_pk_fma_f32 v[130:131], v[14:15], v[32:33], v[22:23]
	v_pk_fma_f32 v[128:129], v[28:29], v[40:41], v[36:37]
	v_pk_fma_f32 v[126:127], v[26:27], v[44:45], v[34:35]
	v_pk_fma_f32 v[2:3], v[24:25], v[56:57], v[2:3]
	s_cbranch_scc1 .LBB0_511
	v_add_f32_e32 v6, 0, v182
	v_add_f32_e32 v6, v180, v6
	v_add_f32_e32 v6, v183, v6
	v_add_f32_e32 v6, v181, v6
	v_add_f32_e32 v6, v178, v6
	v_add_f32_e32 v6, v176, v6
	v_add_f32_e32 v6, v179, v6
	v_add_f32_e32 v22, v177, v6
	v_add_f32_e32 v6, 0, v174
	v_add_f32_e32 v6, v172, v6
	v_add_f32_e32 v6, v175, v6
	v_add_f32_e32 v6, v173, v6
	v_add_f32_e32 v6, v170, v6
	v_add_f32_e32 v6, v168, v6
	v_add_f32_e32 v6, v171, v6
	v_add_f32_e32 v31, v169, v6
	v_add_f32_e32 v6, 0, v166
	v_add_f32_e32 v6, v164, v6
	v_add_f32_e32 v6, v167, v6
	v_add_f32_e32 v6, v165, v6
	v_add_f32_e32 v6, v162, v6
	v_add_f32_e32 v6, v160, v6
	v_add_f32_e32 v6, v163, v6
	v_add_f32_e32 v46, v161, v6
	v_add_f32_e32 v6, 0, v158
	v_add_f32_e32 v6, v156, v6
	v_add_f32_e32 v6, v159, v6
	v_add_f32_e32 v6, v157, v6
	v_add_f32_e32 v6, v154, v6
	v_add_f32_e32 v23, v152, v6
	global_load_dwordx4 v[6:9], v[122:123], off offset:16
	global_load_dwordx4 v[14:17], v[122:123], off
	global_load_dwordx4 v[10:13], v[124:125], off offset:16
	global_load_dwordx4 v[18:21], v[124:125], off
	v_add_f32_e32 v23, v155, v23
	v_add_f32_e32 v30, v153, v23
	v_add_f32_e32 v23, 0, v150
	v_add_f32_e32 v23, v148, v23
	v_add_f32_e32 v23, v151, v23
	v_add_f32_e32 v23, v149, v23
	v_add_f32_e32 v23, v146, v23
	v_add_f32_e32 v23, v144, v23
	v_add_f32_e32 v23, v147, v23
	v_add_f32_e32 v29, v145, v23
	v_add_f32_e32 v23, 0, v4
	v_add_f32_e32 v23, v142, v23
	v_add_f32_e32 v23, v5, v23
	v_add_f32_e32 v23, v143, v23
	v_add_f32_e32 v23, v0, v23
	v_add_f32_e32 v23, v140, v23
	v_add_f32_e32 v23, v1, v23
	v_add_f32_e32 v28, v141, v23
	v_add_f32_e32 v23, 0, v138
	v_add_f32_e32 v23, v136, v23
	v_add_f32_e32 v23, v139, v23
	v_add_f32_e32 v23, v137, v23
	v_add_f32_e32 v23, v134, v23
	v_add_f32_e32 v23, v132, v23
	v_add_f32_e32 v23, v135, v23
	v_add_f32_e32 v27, v133, v23
	v_add_f32_e32 v23, 0, v130
	v_add_f32_e32 v23, v128, v23
	v_add_f32_e32 v23, v131, v23
	v_add_f32_e32 v23, v129, v23
	v_add_f32_dpp v22, v22, v22 quad_perm:[1,0,3,2] row_mask:0xf bank_mask:0xf bound_ctrl:1
	v_add_f32_e32 v23, v126, v23
	v_add_f32_e32 v23, v2, v23
	v_add_f32_dpp v22, v22, v22 quad_perm:[2,3,0,1] row_mask:0xf bank_mask:0xf bound_ctrl:1
	v_add_f32_e32 v23, v127, v23
	v_add_f32_e32 v26, v3, v23
	v_add_f32_dpp v22, v22, v22 row_half_mirror row_mask:0xf bank_mask:0xf bound_ctrl:1
	s_add_u32 s44, s44, s24
	s_addc_u32 s45, s45, 0
	v_add_f32_dpp v22, v22, v22 row_ror:8 row_mask:0xf bank_mask:0xf bound_ctrl:1
	v_mov_b32_e32 v23, v22
	s_nop 1
	v_permlane16_swap_b32_e32 v22, v23
	v_add_f32_e32 v22, v22, v23
	v_mov_b32_e32 v23, v22
	s_nop 1
	v_permlane32_swap_b32_e32 v22, v23
	v_add_f32_e32 v22, v22, v23
	v_mul_f32_e32 v22, 0x3b000000, v22
	v_pk_add_f32 v[32:33], v[182:183], v[22:23] op_sel_hi:[1,0] neg_lo:[0,1] neg_hi:[0,1]
	s_lshl_b64 s[24:25], s[44:45], 11
	v_fma_f32 v23, v32, v32, 0
	v_pk_add_f32 v[34:35], v[180:181], v[22:23] op_sel_hi:[1,0] neg_lo:[0,1] neg_hi:[0,1]
	s_add_u32 s44, s18, s24
	v_fmac_f32_e32 v23, v34, v34
	v_fmac_f32_e32 v23, v33, v33
	v_fmac_f32_e32 v23, v35, v35
	v_pk_add_f32 v[36:37], v[178:179], v[22:23] op_sel_hi:[1,0] neg_lo:[0,1] neg_hi:[0,1]
	v_pk_add_f32 v[38:39], v[176:177], v[22:23] op_sel_hi:[1,0] neg_lo:[0,1] neg_hi:[0,1]
	v_fmac_f32_e32 v23, v36, v36
	v_fmac_f32_e32 v23, v38, v38
	v_fmac_f32_e32 v23, v37, v37
	v_fmac_f32_e32 v23, v39, v39
	s_addc_u32 s45, s19, s25
	s_add_i32 s47, s47, s33
	v_add_f32_dpp v22, v23, v23 quad_perm:[1,0,3,2] row_mask:0xf bank_mask:0xf bound_ctrl:1
	s_add_i32 s26, s26, 1
	s_add_i32 s46, s46, s14
	v_add_f32_dpp v22, v22, v22 quad_perm:[2,3,0,1] row_mask:0xf bank_mask:0xf bound_ctrl:1
	s_cmpk_gt_i32 s47, 0xff
	s_waitcnt vmcnt(0)
	v_mov_b32_e32 v24, v18
	v_add_f32_dpp v22, v22, v22 row_half_mirror row_mask:0xf bank_mask:0xf bound_ctrl:1
	s_nop 1
	v_add_f32_dpp v22, v22, v22 row_ror:8 row_mask:0xf bank_mask:0xf bound_ctrl:1
	v_mov_b32_e32 v23, v22
	s_nop 1
	v_permlane16_swap_b32_e32 v22, v23
	v_add_f32_e32 v22, v22, v23
	v_mov_b32_e32 v23, v22
	s_nop 1
	v_permlane32_swap_b32_e32 v22, v23
	v_add_f32_e32 v22, v22, v23
	v_fmamk_f32 v22, v22, 0x3b000000, v115
	v_mul_f32_e32 v23, 0x4f800000, v22
	v_cmp_gt_f32_e32 vcc, s29, v22
	s_nop 1
	v_cndmask_b32_e32 v25, v22, v23, vcc
	v_sqrt_f32_e32 v40, v25
	v_mov_b32_e32 v22, v14
	v_mov_b32_e32 v23, v16
	v_add_u32_e32 v14, -1, v40
	v_fma_f32 v16, -v14, v40, v25
	v_cmp_ge_f32_e64 s[4:5], 0, v16
	v_add_u32_e32 v16, 1, v40
	v_fma_f32 v18, -v16, v40, v25
	v_cndmask_b32_e64 v14, v40, v14, s[4:5]
	v_cmp_lt_f32_e64 s[4:5], 0, v18
	s_nop 1
	v_cndmask_b32_e64 v14, v14, v16, s[4:5]
	v_mul_f32_e32 v16, 0x37800000, v14
	v_cndmask_b32_e32 v14, v14, v16, vcc
	v_cmp_class_f32_e32 vcc, v25, v186
	v_mov_b32_e32 v16, v15
	s_nop 0
	v_cndmask_b32_e32 v14, v14, v25, vcc
	v_div_scale_f32 v18, s[4:5], v14, v14, 1.0
	v_rcp_f32_e32 v40, v18
	v_mov_b32_e32 v25, v20
	v_mov_b32_e32 v20, v19
	v_fma_f32 v15, -v18, v40, 1.0
	v_fmac_f32_e32 v40, v15, v40
	v_div_scale_f32 v15, vcc, 1.0, v14, 1.0
	v_mul_f32_e32 v19, v15, v40
	v_fma_f32 v41, -v18, v19, v15
	v_fmac_f32_e32 v19, v41, v40
	v_fma_f32 v15, -v18, v19, v15
	v_div_fmas_f32 v15, v15, v40, v19
	v_div_fixup_f32 v40, v15, v14, 1.0
	v_pk_mul_f32 v[14:15], v[32:33], v[40:41] op_sel_hi:[1,0]
	v_mov_b32_e32 v19, v12
	v_pk_fma_f32 v[32:33], v[22:23], v[14:15], v[24:25]
	v_mov_b32_e32 v12, v11
	v_mul_f32_e32 v14, 0xbfb8aa3b, v32
	v_exp_f32_e32 v18, v14
	v_pk_mul_f32 v[14:15], v[34:35], v[40:41] op_sel_hi:[1,0]
	s_nop 0
	v_pk_fma_f32 v[34:35], v[16:17], v[14:15], v[20:21]
	v_add_f32_e32 v15, 1.0, v18
	v_mul_f32_e32 v14, 0xbfb8aa3b, v34
	v_exp_f32_e32 v14, v14
	v_rcp_f32_e32 v42, v15
	v_mul_f32_e32 v15, 0xbfb8aa3b, v33
	v_mul_f32_e32 v18, 0xbfb8aa3b, v35
	v_exp_f32_e32 v15, v15
	v_exp_f32_e32 v18, v18
	v_add_f32_e32 v14, 1.0, v14
	v_rcp_f32_e32 v44, v14
	v_add_f32_e32 v14, 1.0, v15
	v_add_f32_e32 v41, 1.0, v18
	v_rcp_f32_e32 v43, v14
	v_pk_mul_f32 v[36:37], v[36:37], v[40:41] op_sel_hi:[1,0]
	v_mov_b32_e32 v14, v6
	v_mov_b32_e32 v15, v8
	v_mov_b32_e32 v18, v10
	v_pk_fma_f32 v[36:37], v[14:15], v[36:37], v[18:19]
	v_pk_mul_f32 v[38:39], v[38:39], v[40:41] op_sel_hi:[1,0]
	v_mul_f32_e32 v6, 0xbfb8aa3b, v36
	v_mov_b32_e32 v8, v7
	v_exp_f32_e32 v10, v6
	v_pk_fma_f32 v[6:7], v[8:9], v[38:39], v[12:13]
	v_mul_f32_e32 v38, 0xbfb8aa3b, v37
	v_mul_f32_e32 v11, 0xbfb8aa3b, v6
	v_exp_f32_e32 v11, v11
	v_exp_f32_e32 v39, v38
	v_mul_f32_e32 v38, 0xbfb8aa3b, v7
	v_exp_f32_e32 v40, v38
	v_add_f32_e32 v11, 1.0, v11
	v_rcp_f32_e32 v38, v11
	v_add_f32_e32 v11, 1.0, v39
	v_add_f32_e32 v39, 1.0, v40
	v_add_f32_e32 v10, 1.0, v10
	v_rcp_f32_e32 v39, v39
	v_rcp_f32_e32 v10, v10
	v_rcp_f32_e32 v11, v11
	v_rcp_f32_e32 v45, v41
	v_pk_mul_f32 v[6:7], v[6:7], v[38:39]
	v_pk_mul_f32 v[32:33], v[32:33], v[42:43]
	v_pk_mul_f32 v[10:11], v[36:37], v[10:11]
	v_bfe_u32 v36, v7, 16, 1
	v_pk_mul_f32 v[34:35], v[34:35], v[44:45]
	v_add3_u32 v7, v7, v36, s30
	v_bfe_u32 v36, v10, 16, 1
	v_bfe_u32 v37, v6, 16, 1
	v_bfe_u32 v39, v34, 16, 1
	v_add3_u32 v10, v10, v36, s30
	v_add3_u32 v42, v34, v39, s30
	v_add3_u32 v6, v6, v37, s30
	v_bfe_u32 v34, v32, 16, 1
	v_lshrrev_b32_e32 v10, 16, v10
	v_add3_u32 v32, v32, v34, s30
	v_and_or_b32 v34, v6, s27, v10
	v_add_f32_dpp v6, v31, v31 quad_perm:[1,0,3,2] row_mask:0xf bank_mask:0xf bound_ctrl:1
	v_bfe_u32 v37, v11, 16, 1
	v_bfe_u32 v38, v35, 16, 1
	v_add_f32_dpp v6, v6, v6 quad_perm:[2,3,0,1] row_mask:0xf bank_mask:0xf bound_ctrl:1
	v_add3_u32 v11, v11, v37, s30
	v_add3_u32 v43, v35, v38, s30
	v_add_f32_dpp v6, v6, v6 row_half_mirror row_mask:0xf bank_mask:0xf bound_ctrl:1
	v_bfe_u32 v35, v33, 16, 1
	v_lshrrev_b32_e32 v11, 16, v11
	v_add_f32_dpp v6, v6, v6 row_ror:8 row_mask:0xf bank_mask:0xf bound_ctrl:1
	v_add3_u32 v33, v33, v35, s30
	v_and_or_b32 v35, v7, s27, v11
	v_mov_b32_e32 v7, v6
	s_nop 1
	v_permlane16_swap_b32_e32 v6, v7
	v_add_f32_e32 v6, v6, v7
	v_mov_b32_e32 v7, v6
	s_nop 1
	v_permlane32_swap_b32_e32 v6, v7
	v_add_f32_e32 v6, v6, v7
	v_mul_f32_e32 v6, 0x3b000000, v6
	v_pk_add_f32 v[10:11], v[174:175], v[6:7] op_sel_hi:[1,0] neg_lo:[0,1] neg_hi:[0,1]
	v_lshrrev_b32_e32 v32, 16, v32
	v_fma_f32 v7, v10, v10, 0
	v_pk_add_f32 v[36:37], v[172:173], v[6:7] op_sel_hi:[1,0] neg_lo:[0,1] neg_hi:[0,1]
	v_and_or_b32 v32, v42, s27, v32
	v_fmac_f32_e32 v7, v36, v36
	v_fmac_f32_e32 v7, v11, v11
	v_fmac_f32_e32 v7, v37, v37
	v_pk_add_f32 v[38:39], v[170:171], v[6:7] op_sel_hi:[1,0] neg_lo:[0,1] neg_hi:[0,1]
	v_pk_add_f32 v[40:41], v[168:169], v[6:7] op_sel_hi:[1,0] neg_lo:[0,1] neg_hi:[0,1]
	v_fmac_f32_e32 v7, v38, v38
	v_fmac_f32_e32 v7, v40, v40
	v_fmac_f32_e32 v7, v39, v39
	v_fmac_f32_e32 v7, v41, v41
	v_lshrrev_b32_e32 v33, 16, v33
	v_and_or_b32 v33, v43, s27, v33
	v_add_f32_dpp v6, v7, v7 quad_perm:[1,0,3,2] row_mask:0xf bank_mask:0xf bound_ctrl:1
	global_store_dwordx4 v116, v[32:35], s[44:45] offset:1024 sc1
	s_nop 0
	v_add_f32_dpp v6, v6, v6 quad_perm:[2,3,0,1] row_mask:0xf bank_mask:0xf bound_ctrl:1
	s_nop 1
	v_add_f32_dpp v6, v6, v6 row_half_mirror row_mask:0xf bank_mask:0xf bound_ctrl:1
	s_nop 1
	v_add_f32_dpp v6, v6, v6 row_ror:8 row_mask:0xf bank_mask:0xf bound_ctrl:1
	v_mov_b32_e32 v7, v6
	s_nop 1
	v_permlane16_swap_b32_e32 v6, v7
	v_add_f32_e32 v6, v6, v7
	v_mov_b32_e32 v7, v6
	s_nop 1
	v_permlane32_swap_b32_e32 v6, v7
	v_add_f32_e32 v6, v6, v7
	v_fmamk_f32 v6, v6, 0x3b000000, v115
	v_mul_f32_e32 v7, 0x4f800000, v6
	v_cmp_gt_f32_e32 vcc, s29, v6
	s_nop 1
	v_cndmask_b32_e32 v6, v6, v7, vcc
	v_sqrt_f32_e32 v7, v6
	s_nop 0
	v_add_u32_e32 v31, -1, v7
	v_fma_f32 v42, -v31, v7, v6
	v_cmp_ge_f32_e64 s[4:5], 0, v42
	v_add_u32_e32 v42, 1, v7
	s_nop 0
	v_cndmask_b32_e64 v31, v7, v31, s[4:5]
	v_fma_f32 v7, -v42, v7, v6
	v_cmp_lt_f32_e64 s[4:5], 0, v7
	s_nop 1
	v_cndmask_b32_e64 v7, v31, v42, s[4:5]
	v_mul_f32_e32 v31, 0x37800000, v7
	v_cndmask_b32_e32 v7, v7, v31, vcc
	v_cmp_class_f32_e32 vcc, v6, v186
	s_nop 1
	v_cndmask_b32_e32 v31, v7, v6, vcc
	v_div_scale_f32 v42, s[4:5], v31, v31, 1.0
	v_rcp_f32_e32 v43, v42
	v_lshl_add_u64 v[6:7], s[44:45], 0, v[116:117]
	v_fma_f32 v44, -v42, v43, 1.0
	v_fmac_f32_e32 v43, v44, v43
	v_div_scale_f32 v44, vcc, 1.0, v31, 1.0
	v_mul_f32_e32 v45, v44, v43
	v_fma_f32 v47, -v42, v45, v44
	v_fmac_f32_e32 v45, v47, v43
	v_fma_f32 v42, -v42, v45, v44
	v_div_fmas_f32 v42, v42, v43, v45
	v_div_fixup_f32 v42, v42, v31, 1.0
	v_pk_mul_f32 v[10:11], v[10:11], v[42:43] op_sel_hi:[1,0]
	v_pk_mul_f32 v[36:37], v[36:37], v[42:43] op_sel_hi:[1,0]
	v_pk_fma_f32 v[10:11], v[22:23], v[10:11], v[24:25]
	v_pk_fma_f32 v[36:37], v[16:17], v[36:37], v[20:21]
	v_mul_f32_e32 v31, 0xbfb8aa3b, v10
	v_exp_f32_e32 v31, v31
	v_mul_f32_e32 v43, 0xbfb8aa3b, v36
	v_exp_f32_e32 v43, v43
	v_mul_f32_e32 v33, 0xbfb8aa3b, v11
	v_exp_f32_e32 v33, v33
	v_mul_f32_e32 v34, 0xbfb8aa3b, v37
	v_exp_f32_e32 v35, v34
	v_add_f32_e32 v31, 1.0, v31
	v_rcp_f32_e32 v32, v31
	v_add_f32_e32 v31, 1.0, v43
	v_pk_mul_f32 v[38:39], v[38:39], v[42:43] op_sel_hi:[1,0]
	v_rcp_f32_e32 v34, v31
	v_add_f32_e32 v31, 1.0, v33
	v_pk_fma_f32 v[38:39], v[14:15], v[38:39], v[18:19]
	v_rcp_f32_e32 v33, v31
	v_add_f32_e32 v31, 1.0, v35
	v_mul_f32_e32 v35, 0xbfb8aa3b, v38
	v_exp_f32_e32 v43, v35
	v_pk_mul_f32 v[10:11], v[10:11], v[32:33]
	v_pk_mul_f32 v[40:41], v[40:41], v[42:43] op_sel_hi:[1,0]
	s_nop 0
	v_pk_fma_f32 v[40:41], v[8:9], v[40:41], v[12:13]
	s_nop 0
	v_mul_f32_e32 v35, 0xbfb8aa3b, v40
	v_exp_f32_e32 v44, v35
	v_rcp_f32_e32 v35, v31
	v_add_f32_e32 v31, 1.0, v43
	v_mul_f32_e32 v43, 0xbfb8aa3b, v39
	v_rcp_f32_e32 v42, v31
	v_add_f32_e32 v31, 1.0, v44
	v_exp_f32_e32 v43, v43
	v_mul_f32_e32 v44, 0xbfb8aa3b, v41
	v_exp_f32_e32 v45, v44
	v_rcp_f32_e32 v44, v31
	v_add_f32_e32 v31, 1.0, v43
	v_rcp_f32_e32 v43, v31
	v_add_f32_e32 v31, 1.0, v45
	v_rcp_f32_e32 v45, v31
	v_pk_mul_f32 v[32:33], v[36:37], v[34:35]
	v_pk_mul_f32 v[34:35], v[38:39], v[42:43]
	v_bfe_u32 v39, v33, 16, 1
	v_pk_mul_f32 v[36:37], v[40:41], v[44:45]
	v_add3_u32 v33, v33, v39, s30
	v_bfe_u32 v38, v36, 16, 1
	v_add3_u32 v42, v36, v38, s30
	v_bfe_u32 v36, v10, 16, 1
	v_add3_u32 v10, v10, v36, s30
	v_lshrrev_b32_e32 v43, 16, v10
	v_bfe_u32 v31, v37, 16, 1
	v_add_f32_dpp v10, v46, v46 quad_perm:[1,0,3,2] row_mask:0xf bank_mask:0xf bound_ctrl:1
	v_add3_u32 v31, v37, v31, s30
	v_bfe_u32 v37, v11, 16, 1
	v_add_f32_dpp v10, v10, v10 quad_perm:[2,3,0,1] row_mask:0xf bank_mask:0xf bound_ctrl:1
	v_add3_u32 v11, v11, v37, s30
	v_lshrrev_b32_e32 v44, 16, v11
	v_add_f32_dpp v10, v10, v10 row_half_mirror row_mask:0xf bank_mask:0xf bound_ctrl:1
	v_bfe_u32 v38, v34, 16, 1
	v_bfe_u32 v39, v35, 16, 1
	v_add_f32_dpp v10, v10, v10 row_ror:8 row_mask:0xf bank_mask:0xf bound_ctrl:1
	v_mov_b32_e32 v11, v10
	s_nop 1
	v_permlane16_swap_b32_e32 v10, v11
	v_add_f32_e32 v10, v10, v11
	v_mov_b32_e32 v11, v10
	s_nop 1
	v_permlane32_swap_b32_e32 v10, v11
	v_add_f32_e32 v10, v10, v11
	v_mul_f32_e32 v10, 0x3b000000, v10
	v_pk_add_f32 v[36:37], v[166:167], v[10:11] op_sel_hi:[1,0] neg_lo:[0,1] neg_hi:[0,1]
	v_add3_u32 v35, v35, v39, s30
	v_add3_u32 v34, v34, v38, s30
	v_fma_f32 v45, v36, v36, 0
	v_pk_add_f32 v[38:39], v[164:165], v[10:11] op_sel_hi:[1,0] neg_lo:[0,1] neg_hi:[0,1]
	v_bfe_u32 v40, v32, 16, 1
	v_fmac_f32_e32 v45, v38, v38
	v_fmac_f32_e32 v45, v37, v37
	v_add3_u32 v32, v32, v40, s30
	v_fmac_f32_e32 v45, v39, v39
	v_pk_add_f32 v[40:41], v[162:163], v[10:11] op_sel_hi:[1,0] neg_lo:[0,1] neg_hi:[0,1]
	v_pk_add_f32 v[10:11], v[160:161], v[10:11] op_sel_hi:[1,0] neg_lo:[0,1] neg_hi:[0,1]
	v_fmac_f32_e32 v45, v40, v40
	v_fmac_f32_e32 v45, v10, v10
	v_fmac_f32_e32 v45, v41, v41
	v_fmac_f32_e32 v45, v11, v11
	v_lshrrev_b32_e32 v35, 16, v35
	v_and_or_b32 v35, v31, s27, v35
	v_add_f32_dpp v45, v45, v45 quad_perm:[1,0,3,2] row_mask:0xf bank_mask:0xf bound_ctrl:1
	v_lshrrev_b32_e32 v34, 16, v34
	v_and_or_b32 v34, v42, s27, v34
	v_add_f32_dpp v45, v45, v45 quad_perm:[2,3,0,1] row_mask:0xf bank_mask:0xf bound_ctrl:1
	v_and_or_b32 v32, v32, s27, v43
	v_and_or_b32 v33, v33, s27, v44
	v_add_f32_dpp v45, v45, v45 row_half_mirror row_mask:0xf bank_mask:0xf bound_ctrl:1
	global_store_dwordx4 v116, v[32:35], s[44:45] offset:3072 sc1
	s_nop 0
	v_add_f32_dpp v45, v45, v45 row_ror:8 row_mask:0xf bank_mask:0xf bound_ctrl:1
	v_mov_b32_e32 v46, v45
	s_nop 1
	v_permlane16_swap_b32_e32 v45, v46
	v_add_f32_e32 v45, v45, v46
	v_mov_b32_e32 v46, v45
	s_nop 1
	v_permlane32_swap_b32_e32 v45, v46
	v_add_f32_e32 v45, v45, v46
	v_fmamk_f32 v45, v45, 0x3b000000, v115
	v_mul_f32_e32 v46, 0x4f800000, v45
	v_cmp_gt_f32_e32 vcc, s29, v45
	s_nop 1
	v_cndmask_b32_e32 v45, v45, v46, vcc
	v_sqrt_f32_e32 v46, v45
	s_nop 0
	v_add_u32_e32 v31, -1, v46
	v_fma_f32 v47, -v31, v46, v45
	v_cmp_ge_f32_e64 s[4:5], 0, v47
	v_add_u32_e32 v47, 1, v46
	s_nop 0
	v_cndmask_b32_e64 v31, v46, v31, s[4:5]
	v_fma_f32 v46, -v47, v46, v45
	v_cmp_lt_f32_e64 s[4:5], 0, v46
	s_nop 1
	v_cndmask_b32_e64 v31, v31, v47, s[4:5]
	v_mul_f32_e32 v46, 0x37800000, v31
	v_cndmask_b32_e32 v31, v31, v46, vcc
	v_cmp_class_f32_e32 vcc, v45, v186
	s_nop 1
	v_cndmask_b32_e32 v31, v31, v45, vcc
	v_div_scale_f32 v45, s[4:5], v31, v31, 1.0
	v_rcp_f32_e32 v46, v45
	s_nop 0
	v_fma_f32 v42, -v45, v46, 1.0
	v_fmac_f32_e32 v46, v42, v46
	v_div_scale_f32 v42, vcc, 1.0, v31, 1.0
	v_mul_f32_e32 v43, v42, v46
	v_fma_f32 v44, -v45, v43, v42
	v_fmac_f32_e32 v43, v44, v46
	v_fma_f32 v42, -v45, v43, v42
	v_div_fmas_f32 v42, v42, v46, v43
	v_div_fixup_f32 v42, v42, v31, 1.0
	v_pk_mul_f32 v[36:37], v[36:37], v[42:43] op_sel_hi:[1,0]
	v_pk_mul_f32 v[38:39], v[38:39], v[42:43] op_sel_hi:[1,0]
	v_pk_fma_f32 v[36:37], v[22:23], v[36:37], v[24:25]
	v_pk_fma_f32 v[38:39], v[16:17], v[38:39], v[20:21]
	v_mul_f32_e32 v31, 0xbfb8aa3b, v36
	v_exp_f32_e32 v31, v31
	v_mul_f32_e32 v43, 0xbfb8aa3b, v38
	v_exp_f32_e32 v43, v43
	v_mul_f32_e32 v33, 0xbfb8aa3b, v37
	v_exp_f32_e32 v33, v33
	v_mul_f32_e32 v34, 0xbfb8aa3b, v39
	v_exp_f32_e32 v35, v34
	v_add_f32_e32 v31, 1.0, v31
	v_rcp_f32_e32 v32, v31
	v_add_f32_e32 v31, 1.0, v43
	v_pk_mul_f32 v[40:41], v[40:41], v[42:43] op_sel_hi:[1,0]
	v_rcp_f32_e32 v34, v31
	v_add_f32_e32 v31, 1.0, v33
	v_pk_fma_f32 v[40:41], v[14:15], v[40:41], v[18:19]
	v_rcp_f32_e32 v33, v31
	v_add_f32_e32 v31, 1.0, v35
	v_mul_f32_e32 v35, 0xbfb8aa3b, v40
	v_exp_f32_e32 v43, v35
	v_pk_mul_f32 v[32:33], v[36:37], v[32:33]
	v_pk_mul_f32 v[10:11], v[10:11], v[42:43] op_sel_hi:[1,0]
	s_nop 0
	v_pk_fma_f32 v[10:11], v[8:9], v[10:11], v[12:13]
	s_nop 0
	v_mul_f32_e32 v35, 0xbfb8aa3b, v10
	v_exp_f32_e32 v44, v35
	v_rcp_f32_e32 v35, v31
	v_add_f32_e32 v31, 1.0, v43
	v_mul_f32_e32 v43, 0xbfb8aa3b, v41
	v_rcp_f32_e32 v42, v31
	v_add_f32_e32 v31, 1.0, v44
	v_exp_f32_e32 v43, v43
	v_mul_f32_e32 v44, 0xbfb8aa3b, v11
	v_exp_f32_e32 v45, v44
	v_rcp_f32_e32 v44, v31
	v_add_f32_e32 v31, 1.0, v43
	v_rcp_f32_e32 v43, v31
	v_add_f32_e32 v31, 1.0, v45
	v_rcp_f32_e32 v45, v31
	v_pk_mul_f32 v[34:35], v[38:39], v[34:35]
	v_pk_mul_f32 v[36:37], v[40:41], v[42:43]
	v_bfe_u32 v39, v35, 16, 1
	v_pk_mul_f32 v[10:11], v[10:11], v[44:45]
	v_add3_u32 v41, v35, v39, s30
	v_bfe_u32 v31, v11, 16, 1
	v_bfe_u32 v38, v10, 16, 1
	v_add3_u32 v42, v10, v38, s30
	v_add3_u32 v10, v11, v31, s30
	v_bfe_u32 v11, v32, 16, 1
	v_bfe_u32 v35, v37, 16, 1
	v_add3_u32 v35, v37, v35, s30
	v_add3_u32 v11, v32, v11, s30
	v_bfe_u32 v31, v33, 16, 1
	v_lshrrev_b32_e32 v43, 16, v11
	v_lshrrev_b32_e32 v11, 16, v35
	v_add3_u32 v31, v33, v31, s30
	v_and_or_b32 v33, v10, s27, v11
	v_add_f32_dpp v10, v30, v30 quad_perm:[1,0,3,2] row_mask:0xf bank_mask:0xf bound_ctrl:1
	v_bfe_u32 v40, v34, 16, 1
	v_add3_u32 v40, v34, v40, s30
	v_add_f32_dpp v10, v10, v10 quad_perm:[2,3,0,1] row_mask:0xf bank_mask:0xf bound_ctrl:1
	v_bfe_u32 v34, v36, 16, 1
	v_add3_u32 v34, v36, v34, s30
	v_add_f32_dpp v10, v10, v10 row_half_mirror row_mask:0xf bank_mask:0xf bound_ctrl:1
	v_lshrrev_b32_e32 v32, 16, v34
	v_lshrrev_b32_e32 v31, 16, v31
	v_add_f32_dpp v10, v10, v10 row_ror:8 row_mask:0xf bank_mask:0xf bound_ctrl:1
	v_mov_b32_e32 v11, v10
	s_nop 1
	v_permlane16_swap_b32_e32 v10, v11
	v_add_f32_e32 v10, v10, v11
	v_mov_b32_e32 v11, v10
	s_nop 1
	v_permlane32_swap_b32_e32 v10, v11
	v_add_f32_e32 v10, v10, v11
	v_mul_f32_e32 v10, 0x3b000000, v10
	v_pk_add_f32 v[34:35], v[158:159], v[10:11] op_sel_hi:[1,0] neg_lo:[0,1] neg_hi:[0,1]
	v_pk_add_f32 v[36:37], v[156:157], v[10:11] op_sel_hi:[1,0] neg_lo:[0,1] neg_hi:[0,1]
	v_fma_f32 v30, v34, v34, 0
	v_fmac_f32_e32 v30, v36, v36
	v_fmac_f32_e32 v30, v35, v35
	v_fmac_f32_e32 v30, v37, v37
	v_pk_add_f32 v[38:39], v[154:155], v[10:11] op_sel_hi:[1,0] neg_lo:[0,1] neg_hi:[0,1]
	v_pk_add_f32 v[10:11], v[152:153], v[10:11] op_sel_hi:[1,0] neg_lo:[0,1] neg_hi:[0,1]
	v_fmac_f32_e32 v30, v38, v38
	v_fmac_f32_e32 v30, v10, v10
	v_fmac_f32_e32 v30, v39, v39
	v_fmac_f32_e32 v30, v11, v11
	v_and_or_b32 v31, v41, s27, v31
	v_and_or_b32 v32, v42, s27, v32
	v_add_f32_dpp v30, v30, v30 quad_perm:[1,0,3,2] row_mask:0xf bank_mask:0xf bound_ctrl:1
	s_nop 1
	v_add_f32_dpp v30, v30, v30 quad_perm:[2,3,0,1] row_mask:0xf bank_mask:0xf bound_ctrl:1
	s_nop 1
	v_add_f32_dpp v30, v30, v30 row_half_mirror row_mask:0xf bank_mask:0xf bound_ctrl:1
	s_nop 1
	v_add_f32_dpp v30, v30, v30 row_ror:8 row_mask:0xf bank_mask:0xf bound_ctrl:1
	v_mov_b32_e32 v44, v30
	s_nop 1
	v_permlane16_swap_b32_e32 v30, v44
	v_add_f32_e32 v30, v30, v44
	v_mov_b32_e32 v44, v30
	s_nop 1
	v_permlane32_swap_b32_e32 v30, v44
	v_add_f32_e32 v30, v30, v44
	v_fmamk_f32 v30, v30, 0x3b000000, v115
	v_mul_f32_e32 v44, 0x4f800000, v30
	v_cmp_gt_f32_e32 vcc, s29, v30
	s_nop 1
	v_cndmask_b32_e32 v44, v30, v44, vcc
	v_sqrt_f32_e32 v45, v44
	v_and_or_b32 v30, v40, s27, v43
	v_add_u32_e32 v40, -1, v45
	v_fma_f32 v41, -v40, v45, v44
	v_cmp_ge_f32_e64 s[4:5], 0, v41
	v_add_u32_e32 v41, 1, v45
	v_fma_f32 v42, -v41, v45, v44
	v_cndmask_b32_e64 v40, v45, v40, s[4:5]
	v_cmp_lt_f32_e64 s[4:5], 0, v42
	s_nop 1
	v_cndmask_b32_e64 v40, v40, v41, s[4:5]
	v_mul_f32_e32 v41, 0x37800000, v40
	v_cndmask_b32_e32 v40, v40, v41, vcc
	v_cmp_class_f32_e32 vcc, v44, v186
	s_nop 1
	v_cndmask_b32_e32 v42, v40, v44, vcc
	v_div_scale_f32 v43, s[4:5], v42, v42, 1.0
	v_rcp_f32_e32 v44, v43
	v_add_co_u32_e32 v40, vcc, s31, v6
	v_fma_f32 v45, -v43, v44, 1.0
	s_nop 0
	v_addc_co_u32_e32 v41, vcc, 0, v7, vcc
	v_fmac_f32_e32 v44, v45, v44
	v_div_scale_f32 v45, vcc, 1.0, v42, 1.0
	v_mul_f32_e32 v46, v45, v44
	v_fma_f32 v47, -v43, v46, v45
	v_fmac_f32_e32 v46, v47, v44
	v_fma_f32 v43, -v43, v46, v45
	v_div_fmas_f32 v43, v43, v44, v46
	v_div_fixup_f32 v42, v43, v42, 1.0
	v_pk_mul_f32 v[34:35], v[34:35], v[42:43] op_sel_hi:[1,0]
	global_store_dwordx4 v[40:41], v[30:33], off offset:1024 sc1
	v_pk_fma_f32 v[34:35], v[22:23], v[34:35], v[24:25]
	s_nop 0
	v_mul_f32_e32 v43, 0xbfb8aa3b, v34
	v_exp_f32_e32 v43, v43
	v_mul_f32_e32 v32, 0xbfb8aa3b, v35
	v_exp_f32_e32 v33, v32
	v_pk_mul_f32 v[36:37], v[36:37], v[42:43] op_sel_hi:[1,0]
	s_nop 0
	v_pk_fma_f32 v[36:37], v[16:17], v[36:37], v[20:21]
	v_add_f32_e32 v30, 1.0, v43
	v_mul_f32_e32 v32, 0xbfb8aa3b, v37
	v_mul_f32_e32 v44, 0xbfb8aa3b, v36
	v_exp_f32_e32 v43, v32
	v_exp_f32_e32 v44, v44
	v_rcp_f32_e32 v30, v30
	v_pk_mul_f32 v[38:39], v[38:39], v[42:43] op_sel_hi:[1,0]
	v_add_f32_e32 v31, 1.0, v44
	v_pk_fma_f32 v[38:39], v[14:15], v[38:39], v[18:19]
	v_rcp_f32_e32 v32, v31
	v_add_f32_e32 v31, 1.0, v33
	v_add_f32_e32 v33, 1.0, v43
	v_mul_f32_e32 v43, 0xbfb8aa3b, v38
	v_exp_f32_e32 v43, v43
	v_rcp_f32_e32 v33, v33
	v_rcp_f32_e32 v31, v31
	v_pk_mul_f32 v[10:11], v[10:11], v[42:43] op_sel_hi:[1,0]
	s_nop 0
	v_pk_fma_f32 v[10:11], v[8:9], v[10:11], v[12:13]
	v_pk_mul_f32 v[32:33], v[36:37], v[32:33]
	v_mul_f32_e32 v42, 0xbfb8aa3b, v10
	v_exp_f32_e32 v44, v42
	v_add_f32_e32 v42, 1.0, v43
	v_rcp_f32_e32 v42, v42
	v_pk_mul_f32 v[30:31], v[34:35], v[30:31]
	v_add_f32_e32 v43, 1.0, v44
	v_mul_f32_e32 v44, 0xbfb8aa3b, v39
	v_exp_f32_e32 v45, v44
	v_mul_f32_e32 v44, 0xbfb8aa3b, v11
	v_exp_f32_e32 v46, v44
	v_rcp_f32_e32 v44, v43
	v_add_f32_e32 v43, 1.0, v45
	v_rcp_f32_e32 v43, v43
	v_add_f32_e32 v45, 1.0, v46
	v_rcp_f32_e32 v45, v45
	v_pk_mul_f32 v[34:35], v[38:39], v[42:43]
	v_bfe_u32 v39, v32, 16, 1
	v_pk_mul_f32 v[10:11], v[10:11], v[44:45]
	v_add3_u32 v42, v32, v39, s30
	v_bfe_u32 v37, v10, 16, 1
	v_add3_u32 v32, v10, v37, s30
	v_bfe_u32 v10, v30, 16, 1
	v_add3_u32 v10, v30, v10, s30
	v_lshrrev_b32_e32 v30, 16, v10
	v_bfe_u32 v36, v11, 16, 1
	v_add_f32_dpp v10, v29, v29 quad_perm:[1,0,3,2] row_mask:0xf bank_mask:0xf bound_ctrl:1
	v_bfe_u32 v38, v33, 16, 1
	v_add3_u32 v43, v33, v38, s30
	v_add_f32_dpp v10, v10, v10 quad_perm:[2,3,0,1] row_mask:0xf bank_mask:0xf bound_ctrl:1
	v_add3_u32 v33, v11, v36, s30
	v_bfe_u32 v11, v31, 16, 1
	v_add_f32_dpp v10, v10, v10 row_half_mirror row_mask:0xf bank_mask:0xf bound_ctrl:1
	v_add3_u32 v11, v31, v11, s30
	v_lshrrev_b32_e32 v31, 16, v11
	v_add_f32_dpp v10, v10, v10 row_ror:8 row_mask:0xf bank_mask:0xf bound_ctrl:1
	v_mov_b32_e32 v11, v10
	s_nop 1
	v_permlane16_swap_b32_e32 v10, v11
	v_add_f32_e32 v10, v10, v11
	v_mov_b32_e32 v11, v10
	s_nop 1
	v_permlane32_swap_b32_e32 v10, v11
	v_add_f32_e32 v10, v10, v11
	v_bfe_u32 v36, v34, 16, 1
	v_bfe_u32 v37, v35, 16, 1
	v_mul_f32_e32 v10, 0x3b000000, v10
	v_add3_u32 v44, v35, v37, s30
	v_add3_u32 v45, v34, v36, s30
	v_pk_add_f32 v[34:35], v[150:151], v[10:11] op_sel_hi:[1,0] neg_lo:[0,1] neg_hi:[0,1]
	v_pk_add_f32 v[36:37], v[148:149], v[10:11] op_sel_hi:[1,0] neg_lo:[0,1] neg_hi:[0,1]
	v_fma_f32 v29, v34, v34, 0
	v_fmac_f32_e32 v29, v36, v36
	v_fmac_f32_e32 v29, v35, v35
	v_fmac_f32_e32 v29, v37, v37
	v_pk_add_f32 v[38:39], v[146:147], v[10:11] op_sel_hi:[1,0] neg_lo:[0,1] neg_hi:[0,1]
	v_pk_add_f32 v[10:11], v[144:145], v[10:11] op_sel_hi:[1,0] neg_lo:[0,1] neg_hi:[0,1]
	v_fmac_f32_e32 v29, v38, v38
	v_fmac_f32_e32 v29, v10, v10
	v_fmac_f32_e32 v29, v39, v39
	v_fmac_f32_e32 v29, v11, v11
	v_lshrrev_b32_e32 v44, 16, v44
	v_and_or_b32 v33, v33, s27, v44
	v_add_f32_dpp v29, v29, v29 quad_perm:[1,0,3,2] row_mask:0xf bank_mask:0xf bound_ctrl:1
	v_and_or_b32 v30, v42, s27, v30
	v_lshrrev_b32_e32 v45, 16, v45
	v_add_f32_dpp v29, v29, v29 quad_perm:[2,3,0,1] row_mask:0xf bank_mask:0xf bound_ctrl:1
	v_and_or_b32 v31, v43, s27, v31
	v_and_or_b32 v32, v32, s27, v45
	v_add_f32_dpp v29, v29, v29 row_half_mirror row_mask:0xf bank_mask:0xf bound_ctrl:1
	global_store_dwordx4 v[40:41], v[30:33], off offset:3072 sc1
	s_nop 0
	v_add_f32_dpp v29, v29, v29 row_ror:8 row_mask:0xf bank_mask:0xf bound_ctrl:1
	v_mov_b32_e32 v46, v29
	s_nop 1
	v_permlane16_swap_b32_e32 v29, v46
	v_add_f32_e32 v29, v29, v46
	v_mov_b32_e32 v46, v29
	s_nop 1
	v_permlane32_swap_b32_e32 v29, v46
	v_add_f32_e32 v29, v29, v46
	v_fmamk_f32 v29, v29, 0x3b000000, v115
	v_mul_f32_e32 v46, 0x4f800000, v29
	v_cmp_gt_f32_e32 vcc, s29, v29
	s_nop 1
	v_cndmask_b32_e32 v29, v29, v46, vcc
	v_sqrt_f32_e32 v46, v29
	s_nop 0
	v_add_u32_e32 v44, -1, v46
	v_fma_f32 v47, -v44, v46, v29
	v_cmp_ge_f32_e64 s[4:5], 0, v47
	v_add_u32_e32 v47, 1, v46
	s_nop 0
	v_cndmask_b32_e64 v44, v46, v44, s[4:5]
	v_fma_f32 v46, -v47, v46, v29
	v_cmp_lt_f32_e64 s[4:5], 0, v46
	s_nop 1
	v_cndmask_b32_e64 v44, v44, v47, s[4:5]
	v_mul_f32_e32 v46, 0x37800000, v44
	v_cndmask_b32_e32 v44, v44, v46, vcc
	v_cmp_class_f32_e32 vcc, v29, v186
	s_nop 1
	v_cndmask_b32_e32 v29, v44, v29, vcc
	v_div_scale_f32 v44, s[4:5], v29, v29, 1.0
	v_rcp_f32_e32 v46, v44
	s_nop 0
	v_fma_f32 v42, -v44, v46, 1.0
	v_fmac_f32_e32 v46, v42, v46
	v_div_scale_f32 v42, vcc, 1.0, v29, 1.0
	v_mul_f32_e32 v43, v42, v46
	v_fma_f32 v45, -v44, v43, v42
	v_fmac_f32_e32 v43, v45, v46
	v_fma_f32 v42, -v44, v43, v42
	v_div_fmas_f32 v42, v42, v46, v43
	v_div_fixup_f32 v42, v42, v29, 1.0
	v_pk_mul_f32 v[34:35], v[34:35], v[42:43] op_sel_hi:[1,0]
	v_pk_mul_f32 v[36:37], v[36:37], v[42:43] op_sel_hi:[1,0]
	v_pk_fma_f32 v[34:35], v[22:23], v[34:35], v[24:25]
	v_pk_fma_f32 v[36:37], v[16:17], v[36:37], v[20:21]
	v_mul_f32_e32 v29, 0xbfb8aa3b, v34
	v_exp_f32_e32 v29, v29
	v_mul_f32_e32 v43, 0xbfb8aa3b, v36
	v_exp_f32_e32 v43, v43
	v_mul_f32_e32 v31, 0xbfb8aa3b, v35
	v_exp_f32_e32 v31, v31
	v_mul_f32_e32 v32, 0xbfb8aa3b, v37
	v_exp_f32_e32 v33, v32
	v_add_f32_e32 v29, 1.0, v29
	v_rcp_f32_e32 v30, v29
	v_add_f32_e32 v29, 1.0, v43
	v_pk_mul_f32 v[38:39], v[38:39], v[42:43] op_sel_hi:[1,0]
	v_rcp_f32_e32 v32, v29
	v_add_f32_e32 v29, 1.0, v31
	v_pk_fma_f32 v[38:39], v[14:15], v[38:39], v[18:19]
	v_pk_mul_f32 v[10:11], v[10:11], v[42:43] op_sel_hi:[1,0]
	v_rcp_f32_e32 v31, v29
	v_add_f32_e32 v29, 1.0, v33
	v_mul_f32_e32 v33, 0xbfb8aa3b, v38
	v_pk_fma_f32 v[10:11], v[8:9], v[10:11], v[12:13]
	v_exp_f32_e32 v40, v33
	v_mul_f32_e32 v33, 0xbfb8aa3b, v10
	v_exp_f32_e32 v41, v33
	v_rcp_f32_e32 v33, v29
	v_add_f32_e32 v29, 1.0, v40
	v_rcp_f32_e32 v40, v29
	v_add_f32_e32 v29, 1.0, v41
	v_mul_f32_e32 v41, 0xbfb8aa3b, v39
	v_exp_f32_e32 v41, v41
	v_mul_f32_e32 v42, 0xbfb8aa3b, v11
	v_exp_f32_e32 v43, v42
	v_rcp_f32_e32 v42, v29
	v_add_f32_e32 v29, 1.0, v41
	v_rcp_f32_e32 v41, v29
	v_add_f32_e32 v29, 1.0, v43
	v_rcp_f32_e32 v43, v29
	v_pk_mul_f32 v[32:33], v[36:37], v[32:33]
	v_pk_mul_f32 v[30:31], v[34:35], v[30:31]
	v_pk_mul_f32 v[34:35], v[38:39], v[40:41]
	v_pk_mul_f32 v[10:11], v[10:11], v[42:43]
	v_bfe_u32 v37, v33, 16, 1
	v_bfe_u32 v29, v11, 16, 1
	v_bfe_u32 v36, v10, 16, 1
	v_bfe_u32 v38, v32, 16, 1
	v_add3_u32 v37, v33, v37, s30
	v_add3_u32 v36, v10, v36, s30
	v_add3_u32 v10, v11, v29, s30
	v_bfe_u32 v11, v30, 16, 1
	v_bfe_u32 v33, v35, 16, 1
	v_add3_u32 v38, v32, v38, s30
	v_bfe_u32 v32, v34, 16, 1
	v_add3_u32 v33, v35, v33, s30
	v_add3_u32 v11, v30, v11, s30
	v_bfe_u32 v29, v31, 16, 1
	v_add3_u32 v32, v34, v32, s30
	v_lshrrev_b32_e32 v34, 16, v11
	v_lshrrev_b32_e32 v11, 16, v33
	v_add3_u32 v29, v31, v29, s30
	v_and_or_b32 v31, v10, s27, v11
	v_add_f32_dpp v10, v28, v28 quad_perm:[1,0,3,2] row_mask:0xf bank_mask:0xf bound_ctrl:1
	v_lshrrev_b32_e32 v30, 16, v32
	v_and_or_b32 v30, v36, s27, v30
	v_add_f32_dpp v10, v10, v10 quad_perm:[2,3,0,1] row_mask:0xf bank_mask:0xf bound_ctrl:1
	v_lshrrev_b32_e32 v29, 16, v29
	v_and_or_b32 v29, v37, s27, v29
	v_add_f32_dpp v10, v10, v10 row_half_mirror row_mask:0xf bank_mask:0xf bound_ctrl:1
	s_nop 1
	v_add_f32_dpp v10, v10, v10 row_ror:8 row_mask:0xf bank_mask:0xf bound_ctrl:1
	v_mov_b32_e32 v11, v10
	s_nop 1
	v_permlane16_swap_b32_e32 v10, v11
	v_add_f32_e32 v10, v10, v11
	v_mov_b32_e32 v11, v10
	s_nop 1
	v_permlane32_swap_b32_e32 v10, v11
	v_add_f32_e32 v10, v10, v11
	v_mul_f32_e32 v10, 0x3b000000, v10
	v_pk_add_f32 v[4:5], v[4:5], v[10:11] op_sel_hi:[1,0] neg_lo:[0,1] neg_hi:[0,1]
	v_pk_add_f32 v[32:33], v[142:143], v[10:11] op_sel_hi:[1,0] neg_lo:[0,1] neg_hi:[0,1]
	v_fma_f32 v28, v4, v4, 0
	v_fmac_f32_e32 v28, v32, v32
	v_fmac_f32_e32 v28, v5, v5
	v_fmac_f32_e32 v28, v33, v33
	v_pk_add_f32 v[0:1], v[0:1], v[10:11] op_sel_hi:[1,0] neg_lo:[0,1] neg_hi:[0,1]
	v_pk_add_f32 v[10:11], v[140:141], v[10:11] op_sel_hi:[1,0] neg_lo:[0,1] neg_hi:[0,1]
	v_fmac_f32_e32 v28, v0, v0
	v_fmac_f32_e32 v28, v10, v10
	v_fmac_f32_e32 v28, v1, v1
	v_fmac_f32_e32 v28, v11, v11
	s_nop 1
	v_add_f32_dpp v28, v28, v28 quad_perm:[1,0,3,2] row_mask:0xf bank_mask:0xf bound_ctrl:1
	s_nop 1
	v_add_f32_dpp v28, v28, v28 quad_perm:[2,3,0,1] row_mask:0xf bank_mask:0xf bound_ctrl:1
	s_nop 1
	v_add_f32_dpp v28, v28, v28 row_half_mirror row_mask:0xf bank_mask:0xf bound_ctrl:1
	s_nop 1
	v_add_f32_dpp v28, v28, v28 row_ror:8 row_mask:0xf bank_mask:0xf bound_ctrl:1
	v_mov_b32_e32 v35, v28
	s_nop 1
	v_permlane16_swap_b32_e32 v28, v35
	v_add_f32_e32 v28, v28, v35
	v_mov_b32_e32 v35, v28
	s_nop 1
	v_permlane32_swap_b32_e32 v28, v35
	v_add_f32_e32 v28, v28, v35
	v_fmamk_f32 v28, v28, 0x3b000000, v115
	v_mul_f32_e32 v35, 0x4f800000, v28
	v_cmp_gt_f32_e32 vcc, s29, v28
	s_nop 1
	v_cndmask_b32_e32 v35, v28, v35, vcc
	v_sqrt_f32_e32 v39, v35
	v_and_or_b32 v28, v38, s27, v34
	v_add_u32_e32 v34, -1, v39
	v_fma_f32 v36, -v34, v39, v35
	v_cmp_ge_f32_e64 s[4:5], 0, v36
	v_add_u32_e32 v36, 1, v39
	v_fma_f32 v37, -v36, v39, v35
	v_cndmask_b32_e64 v34, v39, v34, s[4:5]
	v_cmp_lt_f32_e64 s[4:5], 0, v37
	s_nop 1
	v_cndmask_b32_e64 v34, v34, v36, s[4:5]
	v_mul_f32_e32 v36, 0x37800000, v34
	v_cndmask_b32_e32 v34, v34, v36, vcc
	v_cmp_class_f32_e32 vcc, v35, v186
	s_nop 1
	v_cndmask_b32_e32 v36, v34, v35, vcc
	v_div_scale_f32 v37, s[4:5], v36, v36, 1.0
	v_rcp_f32_e32 v38, v37
	v_add_co_u32_e32 v34, vcc, s35, v6
	v_fma_f32 v39, -v37, v38, 1.0
	s_nop 0
	v_addc_co_u32_e32 v35, vcc, 0, v7, vcc
	v_fmac_f32_e32 v38, v39, v38
	v_div_scale_f32 v39, vcc, 1.0, v36, 1.0
	v_mul_f32_e32 v40, v39, v38
	v_fma_f32 v41, -v37, v40, v39
	v_fmac_f32_e32 v40, v41, v38
	v_fma_f32 v37, -v37, v40, v39
	v_div_fmas_f32 v37, v37, v38, v40
	v_div_fixup_f32 v36, v37, v36, 1.0
	v_pk_mul_f32 v[4:5], v[4:5], v[36:37] op_sel_hi:[1,0]
	global_store_dwordx4 v[34:35], v[28:31], off offset:1024 sc1
	v_pk_fma_f32 v[4:5], v[22:23], v[4:5], v[24:25]
	s_nop 0
	v_mul_f32_e32 v37, 0xbfb8aa3b, v4
	v_exp_f32_e32 v37, v37
	v_mul_f32_e32 v30, 0xbfb8aa3b, v5
	v_exp_f32_e32 v31, v30
	v_pk_mul_f32 v[32:33], v[32:33], v[36:37] op_sel_hi:[1,0]
	s_nop 0
	v_pk_fma_f32 v[32:33], v[16:17], v[32:33], v[20:21]
	v_add_f32_e32 v28, 1.0, v37
	v_mul_f32_e32 v30, 0xbfb8aa3b, v33
	v_mul_f32_e32 v38, 0xbfb8aa3b, v32
	v_exp_f32_e32 v37, v30
	v_exp_f32_e32 v38, v38
	v_rcp_f32_e32 v28, v28
	v_pk_mul_f32 v[0:1], v[0:1], v[36:37] op_sel_hi:[1,0]
	v_add_f32_e32 v29, 1.0, v38
	v_pk_fma_f32 v[0:1], v[14:15], v[0:1], v[18:19]
	v_rcp_f32_e32 v30, v29
	v_add_f32_e32 v29, 1.0, v31
	v_add_f32_e32 v31, 1.0, v37
	v_mul_f32_e32 v37, 0xbfb8aa3b, v0
	v_exp_f32_e32 v37, v37
	v_rcp_f32_e32 v29, v29
	v_rcp_f32_e32 v31, v31
	v_pk_mul_f32 v[10:11], v[10:11], v[36:37] op_sel_hi:[1,0]
	s_nop 0
	v_pk_fma_f32 v[10:11], v[8:9], v[10:11], v[12:13]
	v_pk_mul_f32 v[4:5], v[4:5], v[28:29]
	v_mul_f32_e32 v36, 0xbfb8aa3b, v10
	v_exp_f32_e32 v38, v36
	v_add_f32_e32 v36, 1.0, v37
	v_rcp_f32_e32 v36, v36
	v_pk_mul_f32 v[28:29], v[32:33], v[30:31]
	v_add_f32_e32 v37, 1.0, v38
	v_mul_f32_e32 v38, 0xbfb8aa3b, v1
	v_exp_f32_e32 v39, v38
	v_mul_f32_e32 v38, 0xbfb8aa3b, v11
	v_exp_f32_e32 v40, v38
	v_rcp_f32_e32 v38, v37
	v_add_f32_e32 v37, 1.0, v39
	v_rcp_f32_e32 v37, v37
	v_add_f32_e32 v39, 1.0, v40
	v_rcp_f32_e32 v39, v39
	v_bfe_u32 v32, v29, 16, 1
	v_pk_mul_f32 v[0:1], v[0:1], v[36:37]
	v_add3_u32 v29, v29, v32, s30
	v_pk_mul_f32 v[10:11], v[10:11], v[38:39]
	v_bfe_u32 v32, v1, 16, 1
	v_bfe_u32 v30, v11, 16, 1
	v_bfe_u32 v31, v10, 16, 1
	v_add3_u32 v36, v10, v31, s30
	v_add3_u32 v30, v11, v30, s30
	v_bfe_u32 v11, v5, 16, 1
	v_bfe_u32 v31, v0, 16, 1
	v_add3_u32 v31, v0, v31, s30
	v_add3_u32 v0, v5, v11, s30
	v_lshrrev_b32_e32 v39, 16, v0
	v_bfe_u32 v10, v4, 16, 1
	v_add_f32_dpp v0, v27, v27 quad_perm:[1,0,3,2] row_mask:0xf bank_mask:0xf bound_ctrl:1
	v_add3_u32 v37, v1, v32, s30
	v_add3_u32 v1, v4, v10, s30
	v_add_f32_dpp v0, v0, v0 quad_perm:[2,3,0,1] row_mask:0xf bank_mask:0xf bound_ctrl:1
	v_lshrrev_b32_e32 v38, 16, v1
	v_bfe_u32 v33, v28, 16, 1
	v_add_f32_dpp v0, v0, v0 row_half_mirror row_mask:0xf bank_mask:0xf bound_ctrl:1
	v_add3_u32 v28, v28, v33, s30
	v_lshrrev_b32_e32 v41, 16, v31
	v_add_f32_dpp v0, v0, v0 row_ror:8 row_mask:0xf bank_mask:0xf bound_ctrl:1
	v_mov_b32_e32 v1, v0
	s_nop 1
	v_permlane16_swap_b32_e32 v0, v1
	v_add_f32_e32 v0, v0, v1
	v_mov_b32_e32 v1, v0
	s_nop 1
	v_permlane32_swap_b32_e32 v0, v1
	v_add_f32_e32 v0, v0, v1
	v_mul_f32_e32 v0, 0x3b000000, v0
	v_pk_add_f32 v[4:5], v[138:139], v[0:1] op_sel_hi:[1,0] neg_lo:[0,1] neg_hi:[0,1]
	v_pk_add_f32 v[10:11], v[136:137], v[0:1] op_sel_hi:[1,0] neg_lo:[0,1] neg_hi:[0,1]
	v_fma_f32 v27, v4, v4, 0
	v_fmac_f32_e32 v27, v10, v10
	v_fmac_f32_e32 v27, v5, v5
	v_fmac_f32_e32 v27, v11, v11
	v_pk_add_f32 v[32:33], v[134:135], v[0:1] op_sel_hi:[1,0] neg_lo:[0,1] neg_hi:[0,1]
	v_pk_add_f32 v[0:1], v[132:133], v[0:1] op_sel_hi:[1,0] neg_lo:[0,1] neg_hi:[0,1]
	v_fmac_f32_e32 v27, v32, v32
	v_fmac_f32_e32 v27, v0, v0
	v_fmac_f32_e32 v27, v33, v33
	v_fmac_f32_e32 v27, v1, v1
	v_lshrrev_b32_e32 v31, 16, v37
	v_and_or_b32 v31, v30, s27, v31
	v_add_f32_dpp v27, v27, v27 quad_perm:[1,0,3,2] row_mask:0xf bank_mask:0xf bound_ctrl:1
	v_and_or_b32 v28, v28, s27, v38
	v_and_or_b32 v29, v29, s27, v39
	v_add_f32_dpp v27, v27, v27 quad_perm:[2,3,0,1] row_mask:0xf bank_mask:0xf bound_ctrl:1
	s_nop 1
	v_add_f32_dpp v27, v27, v27 row_half_mirror row_mask:0xf bank_mask:0xf bound_ctrl:1
	s_nop 1
	v_add_f32_dpp v27, v27, v27 row_ror:8 row_mask:0xf bank_mask:0xf bound_ctrl:1
	v_mov_b32_e32 v40, v27
	s_nop 1
	v_permlane16_swap_b32_e32 v27, v40
	v_add_f32_e32 v27, v27, v40
	v_mov_b32_e32 v40, v27
	s_nop 1
	v_permlane32_swap_b32_e32 v27, v40
	v_add_f32_e32 v27, v27, v40
	v_fmamk_f32 v27, v27, 0x3b000000, v115
	v_mul_f32_e32 v40, 0x4f800000, v27
	v_cmp_gt_f32_e32 vcc, s29, v27
	s_nop 1
	v_cndmask_b32_e32 v27, v27, v40, vcc
	v_sqrt_f32_e32 v40, v27
	s_nop 0
	v_add_u32_e32 v30, -1, v40
	v_fma_f32 v37, -v30, v40, v27
	v_cmp_ge_f32_e64 s[4:5], 0, v37
	v_add_u32_e32 v37, 1, v40
	s_nop 0
	v_cndmask_b32_e64 v30, v40, v30, s[4:5]
	v_fma_f32 v40, -v37, v40, v27
	v_cmp_lt_f32_e64 s[4:5], 0, v40
	s_nop 1
	v_cndmask_b32_e64 v30, v30, v37, s[4:5]
	v_mul_f32_e32 v37, 0x37800000, v30
	v_cndmask_b32_e32 v30, v30, v37, vcc
	v_cmp_class_f32_e32 vcc, v27, v186
	s_nop 1
	v_cndmask_b32_e32 v27, v30, v27, vcc
	v_div_scale_f32 v37, s[4:5], v27, v27, 1.0
	v_rcp_f32_e32 v40, v37
	v_and_or_b32 v30, v36, s27, v41
	global_store_dwordx4 v[34:35], v[28:31], off offset:3072 sc1
	v_fma_f32 v36, -v37, v40, 1.0
	v_fmac_f32_e32 v40, v36, v40
	v_div_scale_f32 v36, vcc, 1.0, v27, 1.0
	v_mul_f32_e32 v38, v36, v40
	v_fma_f32 v39, -v37, v38, v36
	v_fmac_f32_e32 v38, v39, v40
	v_fma_f32 v36, -v37, v38, v36
	v_div_fmas_f32 v36, v36, v40, v38
	v_div_fixup_f32 v36, v36, v27, 1.0
	v_pk_mul_f32 v[4:5], v[4:5], v[36:37] op_sel_hi:[1,0]
	v_pk_mul_f32 v[10:11], v[10:11], v[36:37] op_sel_hi:[1,0]
	v_pk_fma_f32 v[4:5], v[22:23], v[4:5], v[24:25]
	v_pk_fma_f32 v[10:11], v[16:17], v[10:11], v[20:21]
	v_mul_f32_e32 v27, 0xbfb8aa3b, v4
	v_exp_f32_e32 v27, v27
	v_mul_f32_e32 v37, 0xbfb8aa3b, v10
	v_exp_f32_e32 v37, v37
	v_mul_f32_e32 v29, 0xbfb8aa3b, v5
	v_exp_f32_e32 v29, v29
	v_mul_f32_e32 v30, 0xbfb8aa3b, v11
	v_exp_f32_e32 v31, v30
	v_add_f32_e32 v27, 1.0, v27
	v_rcp_f32_e32 v28, v27
	v_add_f32_e32 v27, 1.0, v37
	v_pk_mul_f32 v[32:33], v[32:33], v[36:37] op_sel_hi:[1,0]
	v_rcp_f32_e32 v30, v27
	v_add_f32_e32 v27, 1.0, v29
	v_pk_fma_f32 v[32:33], v[14:15], v[32:33], v[18:19]
	v_pk_mul_f32 v[0:1], v[0:1], v[36:37] op_sel_hi:[1,0]
	v_rcp_f32_e32 v29, v27
	v_add_f32_e32 v27, 1.0, v31
	v_mul_f32_e32 v31, 0xbfb8aa3b, v32
	v_pk_fma_f32 v[0:1], v[8:9], v[0:1], v[12:13]
	v_exp_f32_e32 v34, v31
	v_mul_f32_e32 v31, 0xbfb8aa3b, v0
	v_exp_f32_e32 v35, v31
	v_rcp_f32_e32 v31, v27
	v_add_f32_e32 v27, 1.0, v34
	v_rcp_f32_e32 v34, v27
	v_add_f32_e32 v27, 1.0, v35
	v_mul_f32_e32 v35, 0xbfb8aa3b, v33
	v_exp_f32_e32 v35, v35
	v_mul_f32_e32 v36, 0xbfb8aa3b, v1
	v_exp_f32_e32 v37, v36
	v_rcp_f32_e32 v36, v27
	v_add_f32_e32 v27, 1.0, v35
	v_rcp_f32_e32 v35, v27
	v_add_f32_e32 v27, 1.0, v37
	v_rcp_f32_e32 v37, v27
	v_pk_mul_f32 v[4:5], v[4:5], v[28:29]
	v_pk_mul_f32 v[10:11], v[10:11], v[30:31]
	v_pk_mul_f32 v[28:29], v[32:33], v[34:35]
	v_pk_mul_f32 v[0:1], v[0:1], v[36:37]
	v_bfe_u32 v32, v10, 16, 1
	v_bfe_u32 v27, v1, 16, 1
	v_bfe_u32 v30, v0, 16, 1
	v_add3_u32 v30, v0, v30, s30
	v_add3_u32 v0, v1, v27, s30
	v_bfe_u32 v1, v4, 16, 1
	v_bfe_u32 v27, v29, 16, 1
	v_add3_u32 v32, v10, v32, s30
	v_bfe_u32 v10, v5, 16, 1
	v_add3_u32 v27, v29, v27, s30
	v_add3_u32 v1, v4, v1, s30
	v_add3_u32 v5, v5, v10, s30
	v_lshrrev_b32_e32 v33, 16, v1
	v_lshrrev_b32_e32 v1, 16, v27
	v_lshrrev_b32_e32 v34, 16, v5
	v_and_or_b32 v5, v0, s27, v1
	v_add_f32_dpp v0, v26, v26 quad_perm:[1,0,3,2] row_mask:0xf bank_mask:0xf bound_ctrl:1
	v_bfe_u32 v31, v11, 16, 1
	v_add3_u32 v31, v11, v31, s30
	v_add_f32_dpp v0, v0, v0 quad_perm:[2,3,0,1] row_mask:0xf bank_mask:0xf bound_ctrl:1
	v_bfe_u32 v11, v28, 16, 1
	v_add3_u32 v11, v28, v11, s30
	v_add_f32_dpp v0, v0, v0 row_half_mirror row_mask:0xf bank_mask:0xf bound_ctrl:1
	v_lshrrev_b32_e32 v4, 16, v11
	v_and_or_b32 v4, v30, s27, v4
	v_add_f32_dpp v0, v0, v0 row_ror:8 row_mask:0xf bank_mask:0xf bound_ctrl:1
	v_mov_b32_e32 v1, v0
	s_nop 1
	v_permlane16_swap_b32_e32 v0, v1
	v_add_f32_e32 v0, v0, v1
	v_mov_b32_e32 v1, v0
	s_nop 1
	v_permlane32_swap_b32_e32 v0, v1
	v_add_f32_e32 v0, v0, v1
	v_mul_f32_e32 v0, 0x3b000000, v0
	v_pk_add_f32 v[10:11], v[130:131], v[0:1] op_sel_hi:[1,0] neg_lo:[0,1] neg_hi:[0,1]
	v_pk_add_f32 v[26:27], v[128:129], v[0:1] op_sel_hi:[1,0] neg_lo:[0,1] neg_hi:[0,1]
	v_fma_f32 v35, v10, v10, 0
	v_fmac_f32_e32 v35, v26, v26
	v_fmac_f32_e32 v35, v11, v11
	v_fmac_f32_e32 v35, v27, v27
	v_pk_add_f32 v[28:29], v[126:127], v[0:1] op_sel_hi:[1,0] neg_lo:[0,1] neg_hi:[0,1]
	v_pk_add_f32 v[0:1], v[2:3], v[0:1] op_sel_hi:[1,0] neg_lo:[0,1] neg_hi:[0,1]
	v_fmac_f32_e32 v35, v28, v28
	v_fmac_f32_e32 v35, v0, v0
	v_fmac_f32_e32 v35, v29, v29
	v_fmac_f32_e32 v35, v1, v1
	s_nop 1
	v_add_f32_dpp v2, v35, v35 quad_perm:[1,0,3,2] row_mask:0xf bank_mask:0xf bound_ctrl:1
	s_nop 1
	v_add_f32_dpp v2, v2, v2 quad_perm:[2,3,0,1] row_mask:0xf bank_mask:0xf bound_ctrl:1
	s_nop 1
	v_add_f32_dpp v2, v2, v2 row_half_mirror row_mask:0xf bank_mask:0xf bound_ctrl:1
	s_nop 1
	v_add_f32_dpp v2, v2, v2 row_ror:8 row_mask:0xf bank_mask:0xf bound_ctrl:1
	v_mov_b32_e32 v3, v2
	s_nop 1
	v_permlane16_swap_b32_e32 v2, v3
	v_add_f32_e32 v2, v2, v3
	v_mov_b32_e32 v3, v2
	s_nop 1
	v_permlane32_swap_b32_e32 v2, v3
	v_add_f32_e32 v2, v2, v3
	v_fmamk_f32 v2, v2, 0x3b000000, v115
	v_mul_f32_e32 v3, 0x4f800000, v2
	v_cmp_gt_f32_e32 vcc, s29, v2
	s_nop 1
	v_cndmask_b32_e32 v35, v2, v3, vcc
	v_sqrt_f32_e32 v36, v35
	v_and_or_b32 v3, v31, s27, v34
	v_and_or_b32 v2, v32, s27, v33
	v_add_u32_e32 v30, -1, v36
	v_fma_f32 v31, -v30, v36, v35
	v_cmp_ge_f32_e64 s[4:5], 0, v31
	v_add_u32_e32 v31, 1, v36
	v_fma_f32 v32, -v31, v36, v35
	v_cndmask_b32_e64 v30, v36, v30, s[4:5]
	v_cmp_lt_f32_e64 s[4:5], 0, v32
	s_nop 1
	v_cndmask_b32_e64 v30, v30, v31, s[4:5]
	v_mul_f32_e32 v31, 0x37800000, v30
	v_cndmask_b32_e32 v30, v30, v31, vcc
	v_cmp_class_f32_e32 vcc, v35, v186
	s_nop 1
	v_cndmask_b32_e32 v30, v30, v35, vcc
	v_div_scale_f32 v31, s[4:5], v30, v30, 1.0
	v_rcp_f32_e32 v32, v31
	v_add_co_u32_e32 v6, vcc, s28, v6
	v_fma_f32 v33, -v31, v32, 1.0
	s_nop 0
	v_addc_co_u32_e32 v7, vcc, 0, v7, vcc
	v_fmac_f32_e32 v32, v33, v32
	v_div_scale_f32 v33, vcc, 1.0, v30, 1.0
	v_mul_f32_e32 v34, v33, v32
	v_fma_f32 v35, -v31, v34, v33
	v_fmac_f32_e32 v34, v35, v32
	v_fma_f32 v31, -v31, v34, v33
	v_div_fmas_f32 v31, v31, v32, v34
	v_div_fixup_f32 v30, v31, v30, 1.0
	v_pk_mul_f32 v[10:11], v[10:11], v[30:31] op_sel_hi:[1,0]
	global_store_dwordx4 v[6:7], v[2:5], off offset:1024 sc1
	v_pk_fma_f32 v[10:11], v[22:23], v[10:11], v[24:25]
	v_pk_mul_f32 v[0:1], v[0:1], v[30:31] op_sel_hi:[1,0]
	v_mul_f32_e32 v22, 0xbfb8aa3b, v10
	v_exp_f32_e32 v24, v22
	v_pk_mul_f32 v[22:23], v[26:27], v[30:31] op_sel_hi:[1,0]
	v_mul_f32_e32 v4, 0xbfb8aa3b, v11
	v_pk_fma_f32 v[16:17], v[16:17], v[22:23], v[20:21]
	v_exp_f32_e32 v5, v4
	v_mul_f32_e32 v20, 0xbfb8aa3b, v16
	v_exp_f32_e32 v20, v20
	v_mul_f32_e32 v4, 0xbfb8aa3b, v17
	v_pk_fma_f32 v[0:1], v[8:9], v[0:1], v[12:13]
	v_add_f32_e32 v2, 1.0, v24
	v_add_f32_e32 v3, 1.0, v20
	v_exp_f32_e32 v20, v4
	v_rcp_f32_e32 v4, v3
	v_add_f32_e32 v3, 1.0, v5
	v_mul_f32_e32 v8, 0xbfb8aa3b, v0
	v_add_f32_e32 v5, 1.0, v20
	v_pk_mul_f32 v[20:21], v[28:29], v[30:31] op_sel_hi:[1,0]
	v_exp_f32_e32 v9, v8
	v_pk_fma_f32 v[14:15], v[14:15], v[20:21], v[18:19]
	v_rcp_f32_e32 v5, v5
	v_mul_f32_e32 v18, 0xbfb8aa3b, v14
	v_exp_f32_e32 v18, v18
	v_mul_f32_e32 v12, 0xbfb8aa3b, v15
	v_exp_f32_e32 v13, v12
	v_mul_f32_e32 v12, 0xbfb8aa3b, v1
	v_add_f32_e32 v8, 1.0, v18
	v_exp_f32_e32 v18, v12
	v_add_f32_e32 v9, 1.0, v9
	v_rcp_f32_e32 v12, v9
	v_add_f32_e32 v9, 1.0, v13
	v_add_f32_e32 v13, 1.0, v18
	v_rcp_f32_e32 v13, v13
	v_rcp_f32_e32 v2, v2
	v_rcp_f32_e32 v3, v3
	v_rcp_f32_e32 v8, v8
	v_rcp_f32_e32 v9, v9
	v_pk_mul_f32 v[4:5], v[16:17], v[4:5]
	v_pk_mul_f32 v[0:1], v[0:1], v[12:13]
	v_pk_mul_f32 v[2:3], v[10:11], v[2:3]
	v_pk_mul_f32 v[8:9], v[14:15], v[8:9]
	v_bfe_u32 v10, v1, 16, 1
	v_bfe_u32 v11, v0, 16, 1
	v_bfe_u32 v12, v5, 16, 1
	v_bfe_u32 v13, v4, 16, 1
	v_add3_u32 v4, v4, v13, s30
	v_add3_u32 v5, v5, v12, s30
	v_add3_u32 v0, v0, v11, s30
	v_add3_u32 v1, v1, v10, s30
	v_bfe_u32 v10, v2, 16, 1
	v_bfe_u32 v11, v3, 16, 1
	v_bfe_u32 v12, v8, 16, 1
	v_bfe_u32 v13, v9, 16, 1
	v_add3_u32 v9, v9, v13, s30
	v_add3_u32 v8, v8, v12, s30
	v_add3_u32 v3, v3, v11, s30
	v_add3_u32 v2, v2, v10, s30
	v_lshrrev_b32_e32 v10, 16, v2
	v_lshrrev_b32_e32 v11, 16, v3
	v_lshrrev_b32_e32 v2, 16, v8
	v_lshrrev_b32_e32 v3, 16, v9
	v_and_or_b32 v3, v1, s27, v3
	v_and_or_b32 v2, v0, s27, v2
	v_and_or_b32 v1, v5, s27, v11
	v_and_or_b32 v0, v4, s27, v10
	global_store_dwordx4 v[6:7], v[0:3], off offset:3072 sc1
	s_cbranch_scc0 .LBB0_505

.LBB0_515:
	global_load_dwordx4 v[8:11], v[94:95], off
	global_load_dwordx4 v[12:15], v[96:97], off
	global_load_dwordx4 v[0:3], v[94:95], off offset:16
	global_load_dwordx4 v[4:7], v[96:97], off offset:16
	v_add_f32_e32 v18, 0, v66
	v_add_f32_e32 v18, v68, v18
	v_add_f32_e32 v18, v67, v18
	v_add_f32_e32 v18, v69, v18
	v_add_f32_e32 v18, v62, v18
	v_add_f32_e32 v18, v64, v18
	v_add_f32_e32 v18, v63, v18
	v_add_f32_e32 v18, v65, v18
	s_nop 1
	v_add_f32_dpp v18, v18, v18 quad_perm:[1,0,3,2] row_mask:0xf bank_mask:0xf bound_ctrl:1
	s_nop 1
	v_add_f32_dpp v18, v18, v18 quad_perm:[2,3,0,1] row_mask:0xf bank_mask:0xf bound_ctrl:1
	s_nop 1
	v_add_f32_dpp v18, v18, v18 row_half_mirror row_mask:0xf bank_mask:0xf bound_ctrl:1
	s_nop 1
	v_add_f32_dpp v18, v18, v18 row_ror:8 row_mask:0xf bank_mask:0xf bound_ctrl:1
	v_mov_b32_e32 v19, v18
	s_nop 1
	v_permlane16_swap_b32_e32 v18, v19
	v_add_f32_e32 v18, v18, v19
	v_mov_b32_e32 v19, v18
	s_nop 1
	v_permlane32_swap_b32_e32 v18, v19
	v_add_f32_e32 v18, v18, v19
	v_mul_f32_e32 v18, 0x3b000000, v18
	v_pk_add_f32 v[24:25], v[66:67], v[18:19] op_sel_hi:[1,0] neg_lo:[0,1] neg_hi:[0,1]
	v_pk_add_f32 v[26:27], v[68:69], v[18:19] op_sel_hi:[1,0] neg_lo:[0,1] neg_hi:[0,1]
	v_pk_add_f32 v[28:29], v[62:63], v[18:19] op_sel_hi:[1,0] neg_lo:[0,1] neg_hi:[0,1]
	v_pk_add_f32 v[30:31], v[64:65], v[18:19] op_sel_hi:[1,0] neg_lo:[0,1] neg_hi:[0,1]
	v_fma_f32 v18, v24, v24, 0
	v_fmac_f32_e32 v18, v26, v26
	v_fmac_f32_e32 v18, v25, v25
	v_fmac_f32_e32 v18, v27, v27
	v_fmac_f32_e32 v18, v28, v28
	v_fmac_f32_e32 v18, v30, v30
	v_fmac_f32_e32 v18, v29, v29
	v_fmac_f32_e32 v18, v31, v31
	s_nop 1
	v_add_f32_dpp v18, v18, v18 quad_perm:[1,0,3,2] row_mask:0xf bank_mask:0xf bound_ctrl:1
	s_nop 1
	v_add_f32_dpp v18, v18, v18 quad_perm:[2,3,0,1] row_mask:0xf bank_mask:0xf bound_ctrl:1
	s_nop 1
	v_add_f32_dpp v18, v18, v18 row_half_mirror row_mask:0xf bank_mask:0xf bound_ctrl:1
	s_nop 1
	v_add_f32_dpp v18, v18, v18 row_ror:8 row_mask:0xf bank_mask:0xf bound_ctrl:1
	v_mov_b32_e32 v19, v18
	s_nop 1
	v_permlane16_swap_b32_e32 v18, v19
	v_add_f32_e32 v18, v18, v19
	v_mov_b32_e32 v19, v18
	s_nop 1
	v_permlane32_swap_b32_e32 v18, v19
	v_add_f32_e32 v18, v18, v19
	v_fmamk_f32 v18, v18, 0x3b000000, v135
	v_mul_f32_e32 v19, 0x4f800000, v18
	v_cmp_gt_f32_e32 vcc, s26, v18
	s_nop 1
	v_cndmask_b32_e32 v18, v18, v19, vcc
	v_sqrt_f32_e32 v19, v18
	s_nop 0
	v_add_u32_e32 v22, -1, v19
	v_add_u32_e32 v23, 1, v19
	v_fma_f32 v32, -v22, v19, v18
	v_fma_f32 v33, -v23, v19, v18
	v_cmp_ge_f32_e64 s[4:5], 0, v32
	s_nop 1
	v_cndmask_b32_e64 v19, v19, v22, s[4:5]
	v_cmp_lt_f32_e64 s[4:5], 0, v33
	s_nop 1
	v_cndmask_b32_e64 v19, v19, v23, s[4:5]
	v_mul_f32_e32 v22, 0x37800000, v19
	v_cndmask_b32_e32 v19, v19, v22, vcc
	v_cmp_class_f32_e32 vcc, v18, v136
	s_waitcnt vmcnt(2)
	v_mov_b32_e32 v22, v12
	v_mov_b32_e32 v23, v14
	v_cndmask_b32_e32 v32, v19, v18, vcc
	v_div_scale_f32 v33, s[4:5], v32, v32, 1.0
	v_rcp_f32_e32 v34, v33
	v_div_scale_f32 v35, vcc, 1.0, v32, 1.0
	v_mov_b32_e32 v19, v10
	v_fma_f32 v18, -v33, v34, 1.0
	v_fmac_f32_e32 v34, v18, v34
	v_mul_f32_e32 v36, v35, v34
	v_fma_f32 v37, -v33, v36, v35
	v_fmac_f32_e32 v36, v37, v34
	v_mov_b32_e32 v18, v8
	v_fma_f32 v8, -v33, v36, v35
	v_div_fmas_f32 v8, v8, v34, v36
	v_div_fixup_f32 v32, v8, v32, 1.0
	v_mov_b32_e32 v10, v9
	v_pk_mul_f32 v[8:9], v[24:25], v[32:33] op_sel_hi:[1,0]
	v_mov_b32_e32 v14, v13
	v_pk_fma_f32 v[24:25], v[18:19], v[8:9], v[22:23]
	s_waitcnt vmcnt(0)
	v_mov_b32_e32 v13, v6
	v_mul_f32_e32 v8, 0xbfb8aa3b, v24
	v_exp_f32_e32 v12, v8
	v_pk_mul_f32 v[8:9], v[26:27], v[32:33] op_sel_hi:[1,0]
	v_mov_b32_e32 v6, v5
	v_pk_fma_f32 v[26:27], v[10:11], v[8:9], v[14:15]
	v_add_f32_e32 v9, 1.0, v12
	v_mul_f32_e32 v8, 0xbfb8aa3b, v26
	v_exp_f32_e32 v8, v8
	v_rcp_f32_e32 v34, v9
	v_mul_f32_e32 v9, 0xbfb8aa3b, v25
	v_mul_f32_e32 v12, 0xbfb8aa3b, v27
	v_exp_f32_e32 v9, v9
	v_exp_f32_e32 v12, v12
	v_add_f32_e32 v8, 1.0, v8
	v_rcp_f32_e32 v36, v8
	v_add_f32_e32 v8, 1.0, v9
	v_add_f32_e32 v33, 1.0, v12
	v_rcp_f32_e32 v35, v8
	v_pk_mul_f32 v[28:29], v[28:29], v[32:33] op_sel_hi:[1,0]
	v_mov_b32_e32 v8, v0
	v_mov_b32_e32 v9, v2
	v_mov_b32_e32 v12, v4
	v_pk_fma_f32 v[28:29], v[8:9], v[28:29], v[12:13]
	v_pk_mul_f32 v[30:31], v[30:31], v[32:33] op_sel_hi:[1,0]
	v_mul_f32_e32 v0, 0xbfb8aa3b, v28
	v_mov_b32_e32 v2, v1
	v_exp_f32_e32 v4, v0
	v_pk_fma_f32 v[0:1], v[2:3], v[30:31], v[6:7]
	v_mul_f32_e32 v30, 0xbfb8aa3b, v29
	v_mul_f32_e32 v5, 0xbfb8aa3b, v0
	v_exp_f32_e32 v5, v5
	v_exp_f32_e32 v31, v30
	v_mul_f32_e32 v30, 0xbfb8aa3b, v1
	v_exp_f32_e32 v32, v30
	v_add_f32_e32 v5, 1.0, v5
	v_rcp_f32_e32 v30, v5
	v_add_f32_e32 v5, 1.0, v31
	v_add_f32_e32 v31, 1.0, v32
	v_rcp_f32_e32 v37, v33
	v_add_f32_e32 v4, 1.0, v4
	v_rcp_f32_e32 v31, v31
	v_rcp_f32_e32 v4, v4
	v_rcp_f32_e32 v5, v5
	v_pk_mul_f32 v[26:27], v[26:27], v[36:37]
	v_pk_mul_f32 v[0:1], v[0:1], v[30:31]
	v_pk_mul_f32 v[24:25], v[24:25], v[34:35]
	v_pk_mul_f32 v[4:5], v[28:29], v[4:5]
	v_bfe_u32 v29, v0, 16, 1
	v_bfe_u32 v31, v26, 16, 1
	v_add3_u32 v32, v26, v31, s27
	v_add3_u32 v26, v0, v29, s27
	v_bfe_u32 v0, v24, 16, 1
	v_add3_u32 v0, v24, v0, s27
	v_lshrrev_b32_e32 v24, 16, v0
	v_add_f32_e32 v0, 0, v60
	v_add_f32_e32 v0, v58, v0
	v_add_f32_e32 v0, v61, v0
	v_add_f32_e32 v0, v59, v0
	v_add_f32_e32 v0, v54, v0
	v_add_f32_e32 v0, v56, v0
	v_add_f32_e32 v0, v55, v0
	v_add_f32_e32 v0, v57, v0
	v_bfe_u32 v28, v1, 16, 1
	v_bfe_u32 v30, v27, 16, 1
	v_add_f32_dpp v0, v0, v0 quad_perm:[1,0,3,2] row_mask:0xf bank_mask:0xf bound_ctrl:1
	v_add3_u32 v33, v27, v30, s27
	v_add3_u32 v27, v1, v28, s27
	v_add_f32_dpp v0, v0, v0 quad_perm:[2,3,0,1] row_mask:0xf bank_mask:0xf bound_ctrl:1
	v_bfe_u32 v1, v25, 16, 1
	v_add3_u32 v1, v25, v1, s27
	v_add_f32_dpp v0, v0, v0 row_half_mirror row_mask:0xf bank_mask:0xf bound_ctrl:1
	v_lshrrev_b32_e32 v25, 16, v1
	v_bfe_u32 v28, v4, 16, 1
	v_add_f32_dpp v0, v0, v0 row_ror:8 row_mask:0xf bank_mask:0xf bound_ctrl:1
	v_mov_b32_e32 v1, v0
	s_nop 1
	v_permlane16_swap_b32_e32 v0, v1
	v_add_f32_e32 v0, v0, v1
	v_mov_b32_e32 v1, v0
	s_nop 1
	v_permlane32_swap_b32_e32 v0, v1
	v_bfe_u32 v29, v5, 16, 1
	v_add_f32_e32 v0, v0, v1
	v_add3_u32 v5, v5, v29, s27
	v_add3_u32 v4, v4, v28, s27
	v_mul_f32_e32 v0, 0x3b000000, v0
	v_lshrrev_b32_e32 v34, 16, v4
	v_lshrrev_b32_e32 v35, 16, v5
	v_pk_add_f32 v[4:5], v[60:61], v[0:1] op_sel_hi:[1,0] neg_lo:[0,1] neg_hi:[0,1]
	v_pk_add_f32 v[28:29], v[58:59], v[0:1] op_sel_hi:[1,0] neg_lo:[0,1] neg_hi:[0,1]
	v_fma_f32 v36, v4, v4, 0
	v_fmac_f32_e32 v36, v28, v28
	v_fmac_f32_e32 v36, v5, v5
	v_fmac_f32_e32 v36, v29, v29
	v_pk_add_f32 v[30:31], v[54:55], v[0:1] op_sel_hi:[1,0] neg_lo:[0,1] neg_hi:[0,1]
	v_pk_add_f32 v[0:1], v[56:57], v[0:1] op_sel_hi:[1,0] neg_lo:[0,1] neg_hi:[0,1]
	v_fmac_f32_e32 v36, v30, v30
	v_fmac_f32_e32 v36, v0, v0
	v_fmac_f32_e32 v36, v31, v31
	v_fmac_f32_e32 v36, v1, v1
	v_and_or_b32 v25, v33, s25, v25
	v_and_or_b32 v26, v26, s25, v34
	v_add_f32_dpp v36, v36, v36 quad_perm:[1,0,3,2] row_mask:0xf bank_mask:0xf bound_ctrl:1
	v_and_or_b32 v27, v27, s25, v35
	v_and_or_b32 v24, v32, s25, v24
	v_add_f32_dpp v36, v36, v36 quad_perm:[2,3,0,1] row_mask:0xf bank_mask:0xf bound_ctrl:1
	s_nop 1
	v_add_f32_dpp v36, v36, v36 row_half_mirror row_mask:0xf bank_mask:0xf bound_ctrl:1
	s_nop 1
	v_add_f32_dpp v36, v36, v36 row_ror:8 row_mask:0xf bank_mask:0xf bound_ctrl:1
	v_mov_b32_e32 v37, v36
	s_nop 1
	v_permlane16_swap_b32_e32 v36, v37
	v_add_f32_e32 v36, v36, v37
	v_mov_b32_e32 v37, v36
	s_nop 1
	v_permlane32_swap_b32_e32 v36, v37
	v_add_f32_e32 v36, v36, v37
	v_fmamk_f32 v36, v36, 0x3b000000, v135
	v_mul_f32_e32 v37, 0x4f800000, v36
	v_cmp_gt_f32_e32 vcc, s26, v36
	s_nop 1
	v_cndmask_b32_e32 v36, v36, v37, vcc
	v_sqrt_f32_e32 v37, v36
	s_nop 0
	v_add_u32_e32 v33, -1, v37
	v_fma_f32 v34, -v33, v37, v36
	v_cmp_ge_f32_e64 s[4:5], 0, v34
	v_add_u32_e32 v34, 1, v37
	v_fma_f32 v35, -v34, v37, v36
	v_cndmask_b32_e64 v33, v37, v33, s[4:5]
	v_cmp_lt_f32_e64 s[4:5], 0, v35
	s_nop 1
	v_cndmask_b32_e64 v33, v33, v34, s[4:5]
	v_mul_f32_e32 v34, 0x37800000, v33
	v_cndmask_b32_e32 v33, v33, v34, vcc
	v_cmp_class_f32_e32 vcc, v36, v136
	s_nop 1
	v_cndmask_b32_e32 v34, v33, v36, vcc
	v_div_scale_f32 v35, s[4:5], v34, v34, 1.0
	v_rcp_f32_e32 v36, v35
	s_lshl_b64 s[4:5], s[44:45], 11
	v_lshl_add_u64 v[32:33], v[98:99], 0, s[4:5]
	global_store_dwordx4 v[32:33], v[24:27], off offset:1024 sc1
	v_fma_f32 v37, -v35, v36, 1.0
	v_fmac_f32_e32 v36, v37, v36
	v_div_scale_f32 v37, vcc, 1.0, v34, 1.0
	v_mul_f32_e32 v38, v37, v36
	v_fma_f32 v39, -v35, v38, v37
	v_fmac_f32_e32 v38, v39, v36
	v_fma_f32 v35, -v35, v38, v37
	v_div_fmas_f32 v35, v35, v36, v38
	v_div_fixup_f32 v34, v35, v34, 1.0
	v_pk_mul_f32 v[4:5], v[4:5], v[34:35] op_sel_hi:[1,0]
	s_lshl_b64 s[4:5], s[12:13], 13
	v_pk_fma_f32 v[4:5], v[18:19], v[4:5], v[22:23]
	s_add_u32 s4, s18, s4
	v_mul_f32_e32 v35, 0xbfb8aa3b, v4
	v_exp_f32_e32 v35, v35
	v_mul_f32_e32 v26, 0xbfb8aa3b, v5
	v_exp_f32_e32 v27, v26
	s_addc_u32 s5, s19, s5
	v_pk_mul_f32 v[28:29], v[28:29], v[34:35] op_sel_hi:[1,0]
	v_pk_mul_f32 v[0:1], v[0:1], v[34:35] op_sel_hi:[1,0]
	v_pk_fma_f32 v[28:29], v[10:11], v[28:29], v[14:15]
	v_pk_mul_f32 v[30:31], v[30:31], v[34:35] op_sel_hi:[1,0]
	v_mul_f32_e32 v36, 0xbfb8aa3b, v28
	v_exp_f32_e32 v36, v36
	v_mul_f32_e32 v26, 0xbfb8aa3b, v29
	v_exp_f32_e32 v32, v26
	v_pk_fma_f32 v[0:1], v[2:3], v[0:1], v[6:7]
	v_add_f32_e32 v25, 1.0, v36
	v_pk_fma_f32 v[30:31], v[8:9], v[30:31], v[12:13]
	v_mul_f32_e32 v33, 0xbfb8aa3b, v0
	v_rcp_f32_e32 v26, v25
	v_add_f32_e32 v25, 1.0, v27
	v_add_f32_e32 v27, 1.0, v32
	v_mul_f32_e32 v32, 0xbfb8aa3b, v30
	v_exp_f32_e32 v33, v33
	v_mul_f32_e32 v34, 0xbfb8aa3b, v31
	v_add_f32_e32 v24, 1.0, v35
	v_exp_f32_e32 v32, v32
	v_exp_f32_e32 v35, v34
	v_mul_f32_e32 v34, 0xbfb8aa3b, v1
	v_exp_f32_e32 v36, v34
	v_add_f32_e32 v33, 1.0, v33
	v_rcp_f32_e32 v24, v24
	v_rcp_f32_e32 v25, v25
	v_rcp_f32_e32 v27, v27
	v_add_f32_e32 v32, 1.0, v32
	v_rcp_f32_e32 v34, v33
	v_add_f32_e32 v33, 1.0, v35
	v_rcp_f32_e32 v32, v32
	v_rcp_f32_e32 v33, v33
	v_add_f32_e32 v35, 1.0, v36
	v_rcp_f32_e32 v35, v35
	v_pk_mul_f32 v[4:5], v[4:5], v[24:25]
	v_pk_mul_f32 v[24:25], v[28:29], v[26:27]
	v_pk_mul_f32 v[26:27], v[30:31], v[32:33]
	v_bfe_u32 v30, v25, 16, 1
	v_pk_mul_f32 v[0:1], v[0:1], v[34:35]
	v_add3_u32 v25, v25, v30, s27
	v_bfe_u32 v30, v26, 16, 1
	v_bfe_u32 v29, v0, 16, 1
	v_add3_u32 v26, v26, v30, s27
	v_add3_u32 v0, v0, v29, s27
	v_lshrrev_b32_e32 v26, 16, v26
	v_and_or_b32 v26, v0, s25, v26
	v_add_f32_e32 v0, 0, v52
	v_add_f32_e32 v0, v50, v0
	v_add_f32_e32 v0, v53, v0
	v_add_f32_e32 v0, v51, v0
	v_add_f32_e32 v0, v46, v0
	v_add_f32_e32 v0, v48, v0
	v_add_f32_e32 v0, v47, v0
	v_add_f32_e32 v0, v49, v0
	v_bfe_u32 v31, v24, 16, 1
	v_add3_u32 v24, v24, v31, s27
	v_add_f32_dpp v0, v0, v0 quad_perm:[1,0,3,2] row_mask:0xf bank_mask:0xf bound_ctrl:1
	v_bfe_u32 v31, v27, 16, 1
	v_bfe_u32 v28, v1, 16, 1
	v_add_f32_dpp v0, v0, v0 quad_perm:[2,3,0,1] row_mask:0xf bank_mask:0xf bound_ctrl:1
	v_add3_u32 v27, v27, v31, s27
	v_add3_u32 v1, v1, v28, s27
	v_add_f32_dpp v0, v0, v0 row_half_mirror row_mask:0xf bank_mask:0xf bound_ctrl:1
	v_lshrrev_b32_e32 v27, 16, v27
	v_and_or_b32 v27, v1, s25, v27
	v_add_f32_dpp v0, v0, v0 row_ror:8 row_mask:0xf bank_mask:0xf bound_ctrl:1
	v_mov_b32_e32 v1, v0
	s_nop 1
	v_permlane16_swap_b32_e32 v0, v1
	v_add_f32_e32 v0, v0, v1
	v_mov_b32_e32 v1, v0
	v_bfe_u32 v28, v4, 16, 1
	v_bfe_u32 v29, v5, 16, 1
	v_permlane32_swap_b32_e32 v0, v1
	v_add3_u32 v5, v5, v29, s27
	v_add3_u32 v4, v4, v28, s27
	v_add_f32_e32 v0, v0, v1
	v_lshrrev_b32_e32 v4, 16, v4
	v_lshrrev_b32_e32 v5, 16, v5
	v_mul_f32_e32 v0, 0x3b000000, v0
	v_and_or_b32 v25, v25, s25, v5
	v_and_or_b32 v24, v24, s25, v4
	v_pk_add_f32 v[4:5], v[52:53], v[0:1] op_sel_hi:[1,0] neg_lo:[0,1] neg_hi:[0,1]
	v_pk_add_f32 v[28:29], v[50:51], v[0:1] op_sel_hi:[1,0] neg_lo:[0,1] neg_hi:[0,1]
	v_fma_f32 v32, v4, v4, 0
	v_fmac_f32_e32 v32, v28, v28
	v_fmac_f32_e32 v32, v5, v5
	v_fmac_f32_e32 v32, v29, v29
	v_pk_add_f32 v[30:31], v[46:47], v[0:1] op_sel_hi:[1,0] neg_lo:[0,1] neg_hi:[0,1]
	v_pk_add_f32 v[0:1], v[48:49], v[0:1] op_sel_hi:[1,0] neg_lo:[0,1] neg_hi:[0,1]
	v_fmac_f32_e32 v32, v30, v30
	v_fmac_f32_e32 v32, v0, v0
	v_fmac_f32_e32 v32, v31, v31
	v_fmac_f32_e32 v32, v1, v1
	s_add_i32 s12, s12, s14
	s_add_u32 s6, s6, s24
	v_add_f32_dpp v32, v32, v32 quad_perm:[1,0,3,2] row_mask:0xf bank_mask:0xf bound_ctrl:1
	s_addc_u32 s7, s7, s15
	s_add_u32 s8, s8, s24
	v_add_f32_dpp v32, v32, v32 quad_perm:[2,3,0,1] row_mask:0xf bank_mask:0xf bound_ctrl:1
	s_addc_u32 s9, s9, s15
	s_cmp_lt_i32 s12, 32
	v_add_f32_dpp v32, v32, v32 row_half_mirror row_mask:0xf bank_mask:0xf bound_ctrl:1
	s_nop 1
	v_add_f32_dpp v32, v32, v32 row_ror:8 row_mask:0xf bank_mask:0xf bound_ctrl:1
	v_mov_b32_e32 v33, v32
	s_nop 1
	v_permlane16_swap_b32_e32 v32, v33
	v_add_f32_e32 v32, v32, v33
	v_mov_b32_e32 v33, v32
	s_nop 1
	v_permlane32_swap_b32_e32 v32, v33
	v_add_f32_e32 v32, v32, v33
	v_fmamk_f32 v32, v32, 0x3b000000, v135
	v_mul_f32_e32 v33, 0x4f800000, v32
	v_cmp_gt_f32_e32 vcc, s26, v32
	s_nop 1
	v_cndmask_b32_e32 v34, v32, v33, vcc
	v_sqrt_f32_e32 v35, v34
	v_lshl_add_u64 v[32:33], s[4:5], 0, v[110:111]
	v_add_u32_e32 v36, -1, v35
	v_fma_f32 v37, -v36, v35, v34
	v_cmp_ge_f32_e64 s[4:5], 0, v37
	v_add_u32_e32 v37, 1, v35
	s_nop 0
	v_cndmask_b32_e64 v36, v35, v36, s[4:5]
	v_fma_f32 v35, -v37, v35, v34
	v_cmp_lt_f32_e64 s[4:5], 0, v35
	s_nop 1
	v_cndmask_b32_e64 v35, v36, v37, s[4:5]
	v_mul_f32_e32 v36, 0x37800000, v35
	v_cndmask_b32_e32 v35, v35, v36, vcc
	v_cmp_class_f32_e32 vcc, v34, v136
	s_nop 1
	v_cndmask_b32_e32 v36, v35, v34, vcc
	v_div_scale_f32 v37, s[4:5], v36, v36, 1.0
	v_rcp_f32_e32 v38, v37
	v_add_co_u32_e32 v34, vcc, s28, v32
	v_fma_f32 v39, -v37, v38, 1.0
	s_nop 0
	v_addc_co_u32_e32 v35, vcc, 0, v33, vcc
	v_fmac_f32_e32 v38, v39, v38
	v_div_scale_f32 v39, vcc, 1.0, v36, 1.0
	v_mul_f32_e32 v40, v39, v38
	v_fma_f32 v41, -v37, v40, v39
	v_fmac_f32_e32 v40, v41, v38
	v_fma_f32 v37, -v37, v40, v39
	v_div_fmas_f32 v37, v37, v38, v40
	v_div_fixup_f32 v36, v37, v36, 1.0
	v_pk_mul_f32 v[4:5], v[4:5], v[36:37] op_sel_hi:[1,0]
	global_store_dwordx4 v[34:35], v[24:27], off offset:3072 sc1
	v_pk_fma_f32 v[4:5], v[18:19], v[4:5], v[22:23]
	s_nop 0
	v_mul_f32_e32 v37, 0xbfb8aa3b, v4
	v_exp_f32_e32 v37, v37
	v_mul_f32_e32 v26, 0xbfb8aa3b, v5
	v_exp_f32_e32 v27, v26
	v_pk_mul_f32 v[28:29], v[28:29], v[36:37] op_sel_hi:[1,0]
	s_nop 0
	v_pk_fma_f32 v[28:29], v[10:11], v[28:29], v[14:15]
	v_pk_mul_f32 v[30:31], v[30:31], v[36:37] op_sel_hi:[1,0]
	v_mul_f32_e32 v38, 0xbfb8aa3b, v28
	v_exp_f32_e32 v38, v38
	v_mul_f32_e32 v26, 0xbfb8aa3b, v29
	v_exp_f32_e32 v34, v26
	v_pk_mul_f32 v[0:1], v[0:1], v[36:37] op_sel_hi:[1,0]
	v_pk_fma_f32 v[30:31], v[8:9], v[30:31], v[12:13]
	v_pk_fma_f32 v[0:1], v[2:3], v[0:1], v[6:7]
	v_mul_f32_e32 v36, 0xbfb8aa3b, v31
	v_mul_f32_e32 v35, 0xbfb8aa3b, v0
	v_add_f32_e32 v24, 1.0, v37
	v_add_f32_e32 v25, 1.0, v38
	v_exp_f32_e32 v35, v35
	v_exp_f32_e32 v37, v36
	v_mul_f32_e32 v36, 0xbfb8aa3b, v1
	v_rcp_f32_e32 v26, v25
	v_add_f32_e32 v25, 1.0, v27
	v_add_f32_e32 v27, 1.0, v34
	v_mul_f32_e32 v34, 0xbfb8aa3b, v30
	v_exp_f32_e32 v38, v36
	v_exp_f32_e32 v34, v34
	v_add_f32_e32 v35, 1.0, v35
	v_rcp_f32_e32 v36, v35
	v_add_f32_e32 v35, 1.0, v37
	v_add_f32_e32 v37, 1.0, v38
	v_rcp_f32_e32 v24, v24
	v_rcp_f32_e32 v25, v25
	v_rcp_f32_e32 v27, v27
	v_add_f32_e32 v34, 1.0, v34
	v_rcp_f32_e32 v37, v37
	v_rcp_f32_e32 v34, v34
	v_rcp_f32_e32 v35, v35
	v_pk_mul_f32 v[4:5], v[4:5], v[24:25]
	v_pk_mul_f32 v[24:25], v[28:29], v[26:27]
	v_pk_mul_f32 v[0:1], v[0:1], v[36:37]
	v_pk_mul_f32 v[26:27], v[30:31], v[34:35]
	v_bfe_u32 v28, v1, 16, 1
	v_bfe_u32 v29, v0, 16, 1
	v_bfe_u32 v30, v25, 16, 1
	v_bfe_u32 v31, v24, 16, 1
	v_add3_u32 v24, v24, v31, s27
	v_add3_u32 v25, v25, v30, s27
	v_add3_u32 v30, v0, v29, s27
	v_add3_u32 v0, v1, v28, s27
	v_bfe_u32 v1, v4, 16, 1
	v_bfe_u32 v31, v27, 16, 1
	v_add3_u32 v27, v27, v31, s27
	v_add3_u32 v1, v4, v1, s27
	v_lshrrev_b32_e32 v31, 16, v1
	v_lshrrev_b32_e32 v1, 16, v27
	v_and_or_b32 v27, v0, s25, v1
	v_add_f32_e32 v0, 0, v44
	v_add_f32_e32 v0, v42, v0
	v_add_f32_e32 v0, v45, v0
	v_add_f32_e32 v0, v43, v0
	v_add_f32_e32 v0, v16, v0
	v_add_f32_e32 v0, v20, v0
	v_add_f32_e32 v0, v17, v0
	v_add_f32_e32 v0, v21, v0
	v_bfe_u32 v28, v5, 16, 1
	v_add3_u32 v5, v5, v28, s27
	v_add_f32_dpp v0, v0, v0 quad_perm:[1,0,3,2] row_mask:0xf bank_mask:0xf bound_ctrl:1
	v_bfe_u32 v29, v26, 16, 1
	v_lshrrev_b32_e32 v34, 16, v5
	v_add_f32_dpp v0, v0, v0 quad_perm:[2,3,0,1] row_mask:0xf bank_mask:0xf bound_ctrl:1
	v_add3_u32 v26, v26, v29, s27
	v_lshrrev_b32_e32 v26, 16, v26
	v_add_f32_dpp v0, v0, v0 row_half_mirror row_mask:0xf bank_mask:0xf bound_ctrl:1
	v_and_or_b32 v26, v30, s25, v26
	v_and_or_b32 v24, v24, s25, v31
	v_add_f32_dpp v0, v0, v0 row_ror:8 row_mask:0xf bank_mask:0xf bound_ctrl:1
	v_mov_b32_e32 v1, v0
	s_nop 1
	v_permlane16_swap_b32_e32 v0, v1
	v_add_f32_e32 v0, v0, v1
	v_mov_b32_e32 v1, v0
	s_nop 1
	v_permlane32_swap_b32_e32 v0, v1
	v_add_f32_e32 v0, v0, v1
	v_mul_f32_e32 v0, 0x3b000000, v0
	v_pk_add_f32 v[4:5], v[44:45], v[0:1] op_sel_hi:[1,0] neg_lo:[0,1] neg_hi:[0,1]
	v_pk_add_f32 v[28:29], v[42:43], v[0:1] op_sel_hi:[1,0] neg_lo:[0,1] neg_hi:[0,1]
	v_fma_f32 v35, v4, v4, 0
	v_fmac_f32_e32 v35, v28, v28
	v_fmac_f32_e32 v35, v5, v5
	v_fmac_f32_e32 v35, v29, v29
	v_pk_add_f32 v[16:17], v[16:17], v[0:1] op_sel_hi:[1,0] neg_lo:[0,1] neg_hi:[0,1]
	v_pk_add_f32 v[0:1], v[20:21], v[0:1] op_sel_hi:[1,0] neg_lo:[0,1] neg_hi:[0,1]
	v_fmac_f32_e32 v35, v16, v16
	v_fmac_f32_e32 v35, v0, v0
	v_fmac_f32_e32 v35, v17, v17
	v_fmac_f32_e32 v35, v1, v1
	v_and_or_b32 v25, v25, s25, v34
	s_nop 0
	v_add_f32_dpp v20, v35, v35 quad_perm:[1,0,3,2] row_mask:0xf bank_mask:0xf bound_ctrl:1
	s_nop 1
	v_add_f32_dpp v20, v20, v20 quad_perm:[2,3,0,1] row_mask:0xf bank_mask:0xf bound_ctrl:1
	s_nop 1
	v_add_f32_dpp v20, v20, v20 row_half_mirror row_mask:0xf bank_mask:0xf bound_ctrl:1
	s_nop 1
	v_add_f32_dpp v20, v20, v20 row_ror:8 row_mask:0xf bank_mask:0xf bound_ctrl:1
	v_mov_b32_e32 v21, v20
	s_nop 1
	v_permlane16_swap_b32_e32 v20, v21
	v_add_f32_e32 v20, v20, v21
	v_mov_b32_e32 v21, v20
	s_nop 1
	v_permlane32_swap_b32_e32 v20, v21
	v_add_f32_e32 v20, v20, v21
	v_fmamk_f32 v20, v20, 0x3b000000, v135
	v_mul_f32_e32 v21, 0x4f800000, v20
	v_cmp_gt_f32_e32 vcc, s26, v20
	s_nop 1
	v_cndmask_b32_e32 v20, v20, v21, vcc
	v_sqrt_f32_e32 v21, v20
	s_nop 0
	v_add_u32_e32 v30, -1, v21
	v_fma_f32 v31, -v30, v21, v20
	v_cmp_ge_f32_e64 s[4:5], 0, v31
	v_add_u32_e32 v31, 1, v21
	s_nop 0
	v_cndmask_b32_e64 v30, v21, v30, s[4:5]
	v_fma_f32 v21, -v31, v21, v20
	v_cmp_lt_f32_e64 s[4:5], 0, v21
	s_nop 1
	v_cndmask_b32_e64 v21, v30, v31, s[4:5]
	v_mul_f32_e32 v30, 0x37800000, v21
	v_cndmask_b32_e32 v21, v21, v30, vcc
	v_cmp_class_f32_e32 vcc, v20, v136
	s_nop 1
	v_cndmask_b32_e32 v30, v21, v20, vcc
	v_div_scale_f32 v31, s[4:5], v30, v30, 1.0
	v_rcp_f32_e32 v34, v31
	v_add_co_u32_e32 v20, vcc, s29, v32
	v_fma_f32 v32, -v31, v34, 1.0
	s_nop 0
	v_addc_co_u32_e32 v21, vcc, 0, v33, vcc
	v_fmac_f32_e32 v34, v32, v34
	v_div_scale_f32 v32, vcc, 1.0, v30, 1.0
	v_mul_f32_e32 v33, v32, v34
	v_fma_f32 v35, -v31, v33, v32
	v_fmac_f32_e32 v33, v35, v34
	v_fma_f32 v31, -v31, v33, v32
	v_div_fmas_f32 v31, v31, v34, v33
	v_div_fixup_f32 v30, v31, v30, 1.0
	v_pk_mul_f32 v[4:5], v[4:5], v[30:31] op_sel_hi:[1,0]
	v_pk_mul_f32 v[16:17], v[16:17], v[30:31] op_sel_hi:[1,0]
	v_pk_fma_f32 v[4:5], v[18:19], v[4:5], v[22:23]
	v_pk_fma_f32 v[8:9], v[8:9], v[16:17], v[12:13]
	v_mul_f32_e32 v18, 0xbfb8aa3b, v4
	v_mul_f32_e32 v12, 0xbfb8aa3b, v8
	v_exp_f32_e32 v22, v18
	v_pk_mul_f32 v[18:19], v[28:29], v[30:31] op_sel_hi:[1,0]
	v_exp_f32_e32 v12, v12
	v_pk_mul_f32 v[0:1], v[0:1], v[30:31] op_sel_hi:[1,0]
	v_pk_fma_f32 v[10:11], v[10:11], v[18:19], v[14:15]
	v_pk_fma_f32 v[0:1], v[2:3], v[0:1], v[6:7]
	v_mul_f32_e32 v14, 0xbfb8aa3b, v10
	v_mul_f32_e32 v18, 0xbfb8aa3b, v5
	v_mul_f32_e32 v2, 0xbfb8aa3b, v0
	v_mul_f32_e32 v6, 0xbfb8aa3b, v9
	v_exp_f32_e32 v15, v14
	v_exp_f32_e32 v19, v18
	v_mul_f32_e32 v18, 0xbfb8aa3b, v11
	v_exp_f32_e32 v3, v2
	v_exp_f32_e32 v7, v6
	v_mul_f32_e32 v6, 0xbfb8aa3b, v1
	v_add_f32_e32 v14, 1.0, v22
	v_exp_f32_e32 v22, v18
	v_add_f32_e32 v2, 1.0, v12
	v_exp_f32_e32 v12, v6
	v_add_f32_e32 v15, 1.0, v15
	v_add_f32_e32 v3, 1.0, v3
	v_rcp_f32_e32 v18, v15
	v_add_f32_e32 v15, 1.0, v19
	v_add_f32_e32 v19, 1.0, v22
	v_rcp_f32_e32 v6, v3
	v_add_f32_e32 v3, 1.0, v7
	v_add_f32_e32 v7, 1.0, v12
	v_rcp_f32_e32 v19, v19
	v_rcp_f32_e32 v7, v7
	v_rcp_f32_e32 v14, v14
	v_rcp_f32_e32 v15, v15
	v_rcp_f32_e32 v2, v2
	v_rcp_f32_e32 v3, v3
	v_pk_mul_f32 v[10:11], v[10:11], v[18:19]
	v_pk_mul_f32 v[0:1], v[0:1], v[6:7]
	v_pk_mul_f32 v[4:5], v[4:5], v[14:15]
	v_pk_mul_f32 v[2:3], v[8:9], v[2:3]
	v_bfe_u32 v6, v1, 16, 1
	v_bfe_u32 v7, v0, 16, 1
	v_bfe_u32 v8, v11, 16, 1
	v_bfe_u32 v9, v10, 16, 1
	v_add3_u32 v9, v10, v9, s27
	v_add3_u32 v8, v11, v8, s27
	v_add3_u32 v0, v0, v7, s27
	v_add3_u32 v1, v1, v6, s27
	v_bfe_u32 v6, v4, 16, 1
	v_bfe_u32 v7, v5, 16, 1
	v_bfe_u32 v10, v2, 16, 1
	v_bfe_u32 v11, v3, 16, 1
	v_add3_u32 v3, v3, v11, s27
	v_add3_u32 v2, v2, v10, s27
	v_add3_u32 v5, v5, v7, s27
	v_add3_u32 v4, v4, v6, s27
	v_lshrrev_b32_e32 v4, 16, v4
	v_lshrrev_b32_e32 v5, 16, v5
	v_lshrrev_b32_e32 v2, 16, v2
	v_lshrrev_b32_e32 v3, 16, v3
	v_and_or_b32 v3, v1, s25, v3
	v_and_or_b32 v2, v0, s25, v2
	v_and_or_b32 v1, v8, s25, v5
	v_and_or_b32 v0, v9, s25, v4
	global_store_dwordx4 v[20:21], v[24:27], off offset:1024 sc1
	global_store_dwordx4 v[20:21], v[0:3], off offset:3072 sc1
	s_cbranch_scc0 .LBB0_548
